# v19 MFMA order plus mid-burst s_setprio 0/1 flip moved from after 16 MFMAs to after 12 MFMAs (size-preserving reorder)
# baseline (speedup 1.0000x reference)
; #define PG8_STAGE(bufoff, gbase, voff) do { _Pragma("unroll") for (int _i = 0; _i < 2; ++_i) \
;         __builtin_amdgcn_global_load_lds((const unsigned*)((const char*)(gbase) + (voff)[_i]), (PG8_LAS unsigned*)(lds + (bufoff) + ldsw + _i * 8192), 16, 0, 0); } while (0)
; #define PG8_LDA(dst, b, h) do { _Pragma("unroll") for (int m = 0; m < 4; ++m) _Pragma("unroll") for (int k = 0; k < 2; ++k) dst[m][k] = *(const PG8_LAS bf16x8*)(lds + PG8_SA(b, h) + aoff + m * 2048 + k * 1024); } while (0)
; #define PG8_LDB(dst, b, h) do { _Pragma("unroll") for (int n = 0; n < 2; ++n) _Pragma("unroll") for (int k = 0; k < 2; ++k) dst[n][k] = *(const PG8_LAS bf16x8*)(lds + PG8_SB(b, h) + boff + n * 2048 + k * 1024); } while (0)
; #define PG8_MMA(ai, bj, At, Bt) do { __builtin_amdgcn_s_setprio(1); _Pragma("unroll") for (int m = 0; m < 4; ++m) _Pragma("unroll") for (int n = 0; n < 2; ++n) _Pragma("unroll") for (int k = 0; k < 2; ++k) \
;         acc[ai][bj][m][n] = __builtin_amdgcn_mfma_f32_16x16x32_bf16(Bt[n][k], At[m][k], acc[ai][bj][m][n], 0, 0, 0); __builtin_amdgcn_s_setprio(0); } while (0)
; #define PG8_WAIT_V(n) asm volatile("s_waitcnt vmcnt(" #n ")" ::: "memory")
; #define PG8_WAIT_L(n) asm volatile("s_waitcnt lgkmcnt(" #n ")" ::: "memory")
; #define PG8_BAR __builtin_amdgcn_s_barrier()
; #define PG8_SCHED __builtin_amdgcn_sched_barrier(0)
; template <class Epi, class Sched, bool ALIGN_EPI = false, bool SP2 = false>
; __device__ __forceinline__ void gemm_phase(PG8_LAS unsigned char* lds, const Gemm g, const Sched& S, const Epi& E) {
;     ...
;             const bool last = (t == nt - 2);
;             const char* a1 = cA + (size_t)(t + 1) * kstep;
;             const char* a2 = last ? nA : cA + (size_t)(t + 2) * kstep; const char* b2 = last ? nB : cB + (size_t)(t + 2) * kstep;
;             const char* a3 = a2 + kstep; const char* b3 = b2 + kstep;
;             if (last && has_next) S.a_ready(nxt);
;             if constexpr (SP2) {
;             PG8_LDB(B0, 0, 0); PG8_LDB(B1, 0, 1); PG8_SCHED; PG8_LDA(At, 0, 0); PG8_STAGE(PG8_SA(1, 1), a1 + hstepA, voffA);
;             PG8_WAIT_V(8); PG8_WAIT_L(0); PG8_BAR; PG8_MMA(0, 0, At, B0); PG8_MMA(0, 1, At, B1); PG8_BAR; PG8_SCHED;
;             PG8_LDA(At, 0, 1); PG8_STAGE(PG8_SB(0, 0), b2, voffB); PG8_STAGE(PG8_SB(0, 1), b2 + hstepB, voffB); PG8_STAGE(PG8_SA(0, 0), a2, voffA);
.LBB0_324:
	s_add_u32 s22, s42, 0xfff80080
	s_addc_u32 s23, s43, -1
	s_add_i32 s65, 0, 0x10000
	s_cmp_eq_u32 s64, 28
	s_cselect_b32 s57, s21, s23
	s_cselect_b32 s56, s35, s22
	v_add_u32_e32 v80, s65, v186
	s_cselect_b32 s23, s1, s51
	s_cselect_b32 s22, s37, s49
	s_add_i32 s74, 0, 0x14000
	ds_read_b128 v[130:133], v80
	ds_read_b128 v[134:137], v80 offset:1024
	ds_read_b128 v[138:141], v80 offset:2048
	ds_read_b128 v[142:145], v80 offset:3072
	v_add_u32_e32 v80, s74, v186
	ds_read_b128 v[146:149], v80
	ds_read_b128 v[150:153], v80 offset:1024
	ds_read_b128 v[174:177], v80 offset:2048
	ds_read_b128 v[182:185], v80 offset:3072
	v_lshl_add_u64 v[192:193], s[42:43], 0, v[168:169]
	s_add_i32 m0, s63, 0xc000
	ds_read_b128 v[216:219], v191
	ds_read_b128 v[220:223], v191 offset:1024
	ds_read_b128 v[224:227], v191 offset:2048
	ds_read_b128 v[228:231], v191 offset:3072
	ds_read_b128 v[232:235], v191 offset:4096
	ds_read_b128 v[236:239], v191 offset:5120
	ds_read_b128 v[240:243], v191 offset:6144
	ds_read_b128 v[244:247], v191 offset:7168
	global_load_lds_dwordx4 v[192:193], off
	v_lshl_add_u64 v[192:193], s[42:43], 0, v[170:171]
	s_add_i32 m0, s63, 0xe000
	s_nop 0
	global_load_lds_dwordx4 v[192:193], off
	s_waitcnt vmcnt(8)
	s_waitcnt lgkmcnt(0)
	s_barrier
	s_setprio 1
	s_waitcnt lgkmcnt(0)
	v_mfma_f32_16x16x32_bf16 v[126:129], v[130:133], v[216:219], v[126:129]
	v_mfma_f32_16x16x32_bf16 v[126:129], v[134:137], v[220:223], v[126:129]
	v_mfma_f32_16x16x32_bf16 v[122:125], v[142:145], v[220:223], v[122:125]
	v_mfma_f32_16x16x32_bf16 v[122:125], v[138:141], v[216:219], v[122:125]
	v_mfma_f32_16x16x32_bf16 v[106:109], v[138:141], v[224:227], v[106:109]
	v_mfma_f32_16x16x32_bf16 v[106:109], v[142:145], v[228:231], v[106:109]
	v_mfma_f32_16x16x32_bf16 v[110:113], v[134:137], v[228:231], v[110:113]
	v_mfma_f32_16x16x32_bf16 v[110:113], v[130:133], v[224:227], v[110:113]
	v_mfma_f32_16x16x32_bf16 v[94:97], v[130:133], v[232:235], v[94:97]
	v_mfma_f32_16x16x32_bf16 v[94:97], v[134:137], v[236:239], v[94:97]
	v_mfma_f32_16x16x32_bf16 v[90:93], v[142:145], v[236:239], v[90:93]
	v_mfma_f32_16x16x32_bf16 v[90:93], v[138:141], v[232:235], v[90:93]
	s_setprio 0
	s_setprio 1
	v_mfma_f32_16x16x32_bf16 v[72:75], v[138:141], v[240:243], v[72:75]
	v_mfma_f32_16x16x32_bf16 v[72:75], v[142:145], v[244:247], v[72:75]
	v_mfma_f32_16x16x32_bf16 v[76:79], v[134:137], v[244:247], v[76:79]
	v_mfma_f32_16x16x32_bf16 v[76:79], v[130:133], v[240:243], v[76:79]
	v_mfma_f32_16x16x32_bf16 v[118:121], v[146:149], v[216:219], v[118:121]
	v_mfma_f32_16x16x32_bf16 v[118:121], v[150:153], v[220:223], v[118:121]
	v_mfma_f32_16x16x32_bf16 v[114:117], v[182:185], v[220:223], v[114:117]
	v_mfma_f32_16x16x32_bf16 v[114:117], v[174:177], v[216:219], v[114:117]
	v_mfma_f32_16x16x32_bf16 v[98:101], v[174:177], v[224:227], v[98:101]
	v_mfma_f32_16x16x32_bf16 v[98:101], v[182:185], v[228:231], v[98:101]
	v_mfma_f32_16x16x32_bf16 v[102:105], v[150:153], v[228:231], v[102:105]
	v_mfma_f32_16x16x32_bf16 v[102:105], v[146:149], v[224:227], v[102:105]
	v_mfma_f32_16x16x32_bf16 v[86:89], v[146:149], v[232:235], v[86:89]
	v_mfma_f32_16x16x32_bf16 v[86:89], v[150:153], v[236:239], v[86:89]
	v_mfma_f32_16x16x32_bf16 v[82:85], v[182:185], v[236:239], v[82:85]
	v_mfma_f32_16x16x32_bf16 v[82:85], v[174:177], v[232:235], v[82:85]
	v_mfma_f32_16x16x32_bf16 v[64:67], v[174:177], v[240:243], v[64:67]
	v_mfma_f32_16x16x32_bf16 v[64:67], v[182:185], v[244:247], v[64:67]
	v_mfma_f32_16x16x32_bf16 v[68:71], v[150:153], v[244:247], v[68:71]
	v_mfma_f32_16x16x32_bf16 v[68:71], v[146:149], v[240:243], v[68:71]
	s_setprio 0
	s_barrier
	s_add_i32 s65, s65, s55
	v_lshl_add_u64 v[192:193], s[22:23], 0, v[156:157]
	s_mov_b32 m0, s65
	ds_read_b128 v[216:219], v191 offset:16384
	ds_read_b128 v[220:223], v191 offset:17408
	ds_read_b128 v[224:227], v191 offset:18432
	ds_read_b128 v[228:231], v191 offset:19456
	ds_read_b128 v[232:235], v191 offset:20480
	ds_read_b128 v[236:239], v191 offset:21504
	ds_read_b128 v[240:243], v191 offset:22528
	ds_read_b128 v[244:247], v191 offset:23552
	global_load_lds_dwordx4 v[192:193], off
	s_add_i32 m0, s65, 0x2000
	s_add_u32 s72, s22, 0x80000
	v_lshl_add_u64 v[248:249], s[22:23], 0, v[160:161]
	s_addc_u32 s73, s23, 0
	s_add_i32 s65, s74, s55
	global_load_lds_dwordx4 v[248:249], off
	v_lshl_add_u64 v[202:203], s[72:73], 0, v[156:157]
	s_mov_b32 m0, s65
	v_lshl_add_u64 v[204:205], s[56:57], 0, v[158:159]
	global_load_lds_dwordx4 v[202:203], off
	v_lshl_add_u64 v[202:203], s[72:73], 0, v[160:161]
	s_add_i32 m0, s65, 0x2000
	s_nop 0
	global_load_lds_dwordx4 v[202:203], off
	v_lshl_add_u64 v[202:203], s[56:57], 0, v[154:155]
	s_mov_b32 m0, s63
	s_nop 0
	global_load_lds_dwordx4 v[202:203], off
	s_mov_b32 m0, s66
	s_nop 0
	global_load_lds_dwordx4 v[204:205], off
	s_waitcnt vmcnt(8)
	s_waitcnt lgkmcnt(0)
	s_barrier
; #define PG8_STAGE(bufoff, gbase, voff) do { _Pragma("unroll") for (int _i = 0; _i < 2; ++_i) \
;         __builtin_amdgcn_global_load_lds((const unsigned*)((const char*)(gbase) + (voff)[_i]), (PG8_LAS unsigned*)(lds + (bufoff) + ldsw + _i * 8192), 16, 0, 0); } while (0)
; #define PG8_LDA(dst, b, h) do { _Pragma("unroll") for (int m = 0; m < 4; ++m) _Pragma("unroll") for (int k = 0; k < 2; ++k) dst[m][k] = *(const PG8_LAS bf16x8*)(lds + PG8_SA(b, h) + aoff + m * 2048 + k * 1024); } while (0)
; #define PG8_LDB(dst, b, h) do { _Pragma("unroll") for (int n = 0; n < 2; ++n) _Pragma("unroll") for (int k = 0; k < 2; ++k) dst[n][k] = *(const PG8_LAS bf16x8*)(lds + PG8_SB(b, h) + boff + n * 2048 + k * 1024); } while (0)
; #define PG8_MMA(ai, bj, At, Bt) do { __builtin_amdgcn_s_setprio(1); _Pragma("unroll") for (int m = 0; m < 4; ++m) _Pragma("unroll") for (int n = 0; n < 2; ++n) _Pragma("unroll") for (int k = 0; k < 2; ++k) \
;         acc[ai][bj][m][n] = __builtin_amdgcn_mfma_f32_16x16x32_bf16(Bt[n][k], At[m][k], acc[ai][bj][m][n], 0, 0, 0); __builtin_amdgcn_s_setprio(0); } while (0)
; #define PG8_WAIT_V(n) asm volatile("s_waitcnt vmcnt(" #n ")" ::: "memory")
; #define PG8_WAIT_L(n) asm volatile("s_waitcnt lgkmcnt(" #n ")" ::: "memory")
; #define PG8_BAR __builtin_amdgcn_s_barrier()
; #define PG8_SCHED __builtin_amdgcn_sched_barrier(0)
; template <class Epi, class Sched, bool ALIGN_EPI = false, bool SP2 = false>
; __device__ __forceinline__ void gemm_phase(PG8_LAS unsigned char* lds, const Gemm g, const Sched& S, const Epi& E) {
;     ...
;             PG8_WAIT_V(8); PG8_WAIT_L(0); PG8_BAR; PG8_MMA(1, 0, At, B0); PG8_MMA(1, 1, At, B1); PG8_BAR; PG8_SCHED;
;             PG8_LDB(B0, 1, 0); PG8_LDB(B1, 1, 1); PG8_SCHED; PG8_LDA(At, 1, 0); PG8_STAGE(PG8_SA(0, 1), a2 + hstepA, voffA);
;             PG8_WAIT_V(8); PG8_WAIT_L(0); PG8_BAR; PG8_MMA(0, 0, At, B0); PG8_MMA(0, 1, At, B1); PG8_BAR; PG8_SCHED;
	s_setprio 1
	s_waitcnt lgkmcnt(0)
	v_mfma_f32_16x16x32_bf16 v[60:63], v[130:133], v[216:219], v[60:63]
	v_mfma_f32_16x16x32_bf16 v[60:63], v[134:137], v[220:223], v[60:63]
	v_mfma_f32_16x16x32_bf16 v[56:59], v[142:145], v[220:223], v[56:59]
	v_mfma_f32_16x16x32_bf16 v[56:59], v[138:141], v[216:219], v[56:59]
	v_mfma_f32_16x16x32_bf16 v[40:43], v[138:141], v[224:227], v[40:43]
	v_mfma_f32_16x16x32_bf16 v[40:43], v[142:145], v[228:231], v[40:43]
	v_mfma_f32_16x16x32_bf16 v[44:47], v[134:137], v[228:231], v[44:47]
	v_mfma_f32_16x16x32_bf16 v[44:47], v[130:133], v[224:227], v[44:47]
	v_mfma_f32_16x16x32_bf16 v[28:31], v[130:133], v[232:235], v[28:31]
	v_mfma_f32_16x16x32_bf16 v[28:31], v[134:137], v[236:239], v[28:31]
	v_mfma_f32_16x16x32_bf16 v[24:27], v[142:145], v[236:239], v[24:27]
	v_mfma_f32_16x16x32_bf16 v[24:27], v[138:141], v[232:235], v[24:27]
	s_setprio 0
	s_setprio 1
	v_mfma_f32_16x16x32_bf16 v[8:11], v[138:141], v[240:243], v[8:11]
	v_mfma_f32_16x16x32_bf16 v[8:11], v[142:145], v[244:247], v[8:11]
	v_mfma_f32_16x16x32_bf16 v[12:15], v[134:137], v[244:247], v[12:15]
	v_mfma_f32_16x16x32_bf16 v[12:15], v[130:133], v[240:243], v[12:15]
	v_mfma_f32_16x16x32_bf16 v[52:55], v[146:149], v[216:219], v[52:55]
	v_mfma_f32_16x16x32_bf16 v[52:55], v[150:153], v[220:223], v[52:55]
	v_mfma_f32_16x16x32_bf16 v[48:51], v[182:185], v[220:223], v[48:51]
	v_mfma_f32_16x16x32_bf16 v[48:51], v[174:177], v[216:219], v[48:51]
	v_mfma_f32_16x16x32_bf16 v[32:35], v[174:177], v[224:227], v[32:35]
	v_mfma_f32_16x16x32_bf16 v[32:35], v[182:185], v[228:231], v[32:35]
	v_mfma_f32_16x16x32_bf16 v[36:39], v[150:153], v[228:231], v[36:39]
	v_mfma_f32_16x16x32_bf16 v[36:39], v[146:149], v[224:227], v[36:39]
	v_mfma_f32_16x16x32_bf16 v[20:23], v[146:149], v[232:235], v[20:23]
	v_mfma_f32_16x16x32_bf16 v[20:23], v[150:153], v[236:239], v[20:23]
	v_mfma_f32_16x16x32_bf16 v[16:19], v[182:185], v[236:239], v[16:19]
	v_mfma_f32_16x16x32_bf16 v[16:19], v[174:177], v[232:235], v[16:19]
	v_mfma_f32_16x16x32_bf16 v[0:3], v[174:177], v[240:243], v[0:3]
	v_mfma_f32_16x16x32_bf16 v[0:3], v[182:185], v[244:247], v[0:3]
	v_mfma_f32_16x16x32_bf16 v[4:7], v[150:153], v[244:247], v[4:7]
	v_mfma_f32_16x16x32_bf16 v[4:7], v[146:149], v[240:243], v[4:7]
	s_setprio 0
	s_barrier
	s_add_i32 s65, 0, 0x18000
	v_add_u32_e32 v80, s65, v186
	s_add_i32 s72, 0, 0x1c000
	ds_read_b128 v[130:133], v80
	ds_read_b128 v[134:137], v80 offset:1024
	ds_read_b128 v[138:141], v80 offset:2048
	ds_read_b128 v[142:145], v80 offset:3072
	v_add_u32_e32 v80, s72, v186
	ds_read_b128 v[146:149], v80
	ds_read_b128 v[150:153], v80 offset:1024
	ds_read_b128 v[174:177], v80 offset:2048
	ds_read_b128 v[182:185], v80 offset:3072
	s_add_u32 s56, s56, 0x80000
	s_addc_u32 s57, s57, 0
	s_mov_b32 m0, s67
	v_lshl_add_u64 v[206:207], s[56:57], 0, v[154:155]
	ds_read_b128 v[216:219], v191 offset:32768
	ds_read_b128 v[220:223], v191 offset:33792
	ds_read_b128 v[224:227], v191 offset:34816
	ds_read_b128 v[228:231], v191 offset:35840
	ds_read_b128 v[232:235], v191 offset:36864
	ds_read_b128 v[236:239], v191 offset:37888
	ds_read_b128 v[240:243], v191 offset:38912
	ds_read_b128 v[244:247], v191 offset:39936
	global_load_lds_dwordx4 v[206:207], off
	v_lshl_add_u64 v[206:207], s[56:57], 0, v[158:159]
	s_mov_b32 m0, s68
	s_nop 0
	global_load_lds_dwordx4 v[206:207], off
	s_waitcnt vmcnt(8)
	s_waitcnt lgkmcnt(0)
	s_barrier
	s_setprio 1
	s_waitcnt lgkmcnt(0)
	v_mfma_f32_16x16x32_bf16 v[126:129], v[130:133], v[216:219], v[126:129]
	v_mfma_f32_16x16x32_bf16 v[126:129], v[134:137], v[220:223], v[126:129]
	v_mfma_f32_16x16x32_bf16 v[122:125], v[142:145], v[220:223], v[122:125]
	v_mfma_f32_16x16x32_bf16 v[122:125], v[138:141], v[216:219], v[122:125]
	v_mfma_f32_16x16x32_bf16 v[106:109], v[138:141], v[224:227], v[106:109]
	v_mfma_f32_16x16x32_bf16 v[106:109], v[142:145], v[228:231], v[106:109]
	v_mfma_f32_16x16x32_bf16 v[110:113], v[134:137], v[228:231], v[110:113]
	v_mfma_f32_16x16x32_bf16 v[110:113], v[130:133], v[224:227], v[110:113]
	v_mfma_f32_16x16x32_bf16 v[94:97], v[130:133], v[232:235], v[94:97]
	v_mfma_f32_16x16x32_bf16 v[94:97], v[134:137], v[236:239], v[94:97]
	v_mfma_f32_16x16x32_bf16 v[90:93], v[142:145], v[236:239], v[90:93]
	v_mfma_f32_16x16x32_bf16 v[90:93], v[138:141], v[232:235], v[90:93]
	s_setprio 0
	s_setprio 1
	v_mfma_f32_16x16x32_bf16 v[72:75], v[138:141], v[240:243], v[72:75]
	v_mfma_f32_16x16x32_bf16 v[72:75], v[142:145], v[244:247], v[72:75]
	v_mfma_f32_16x16x32_bf16 v[76:79], v[134:137], v[244:247], v[76:79]
	v_mfma_f32_16x16x32_bf16 v[76:79], v[130:133], v[240:243], v[76:79]
	v_mfma_f32_16x16x32_bf16 v[118:121], v[146:149], v[216:219], v[118:121]
	v_mfma_f32_16x16x32_bf16 v[118:121], v[150:153], v[220:223], v[118:121]
	v_mfma_f32_16x16x32_bf16 v[114:117], v[182:185], v[220:223], v[114:117]
	v_mfma_f32_16x16x32_bf16 v[114:117], v[174:177], v[216:219], v[114:117]
	v_mfma_f32_16x16x32_bf16 v[98:101], v[174:177], v[224:227], v[98:101]
	v_mfma_f32_16x16x32_bf16 v[98:101], v[182:185], v[228:231], v[98:101]
	v_mfma_f32_16x16x32_bf16 v[102:105], v[150:153], v[228:231], v[102:105]
	v_mfma_f32_16x16x32_bf16 v[102:105], v[146:149], v[224:227], v[102:105]
	v_mfma_f32_16x16x32_bf16 v[86:89], v[146:149], v[232:235], v[86:89]
	v_mfma_f32_16x16x32_bf16 v[86:89], v[150:153], v[236:239], v[86:89]
	v_mfma_f32_16x16x32_bf16 v[82:85], v[182:185], v[236:239], v[82:85]
	v_mfma_f32_16x16x32_bf16 v[82:85], v[174:177], v[232:235], v[82:85]
	v_mfma_f32_16x16x32_bf16 v[64:67], v[174:177], v[240:243], v[64:67]
	v_mfma_f32_16x16x32_bf16 v[64:67], v[182:185], v[244:247], v[64:67]
	v_mfma_f32_16x16x32_bf16 v[68:71], v[150:153], v[244:247], v[68:71]
	v_mfma_f32_16x16x32_bf16 v[68:71], v[146:149], v[240:243], v[68:71]
	s_setprio 0
	s_barrier
; #define PG8_STAGE(bufoff, gbase, voff) do { _Pragma("unroll") for (int _i = 0; _i < 2; ++_i) \
;         __builtin_amdgcn_global_load_lds((const unsigned*)((const char*)(gbase) + (voff)[_i]), (PG8_LAS unsigned*)(lds + (bufoff) + ldsw + _i * 8192), 16, 0, 0); } while (0)
; #define PG8_LDA(dst, b, h) do { _Pragma("unroll") for (int m = 0; m < 4; ++m) _Pragma("unroll") for (int k = 0; k < 2; ++k) dst[m][k] = *(const PG8_LAS bf16x8*)(lds + PG8_SA(b, h) + aoff + m * 2048 + k * 1024); } while (0)
; #define PG8_MMA(ai, bj, At, Bt) do { __builtin_amdgcn_s_setprio(1); _Pragma("unroll") for (int m = 0; m < 4; ++m) _Pragma("unroll") for (int n = 0; n < 2; ++n) _Pragma("unroll") for (int k = 0; k < 2; ++k) \
;         acc[ai][bj][m][n] = __builtin_amdgcn_mfma_f32_16x16x32_bf16(Bt[n][k], At[m][k], acc[ai][bj][m][n], 0, 0, 0); __builtin_amdgcn_s_setprio(0); } while (0)
; #define PG8_WAIT_V(n) asm volatile("s_waitcnt vmcnt(" #n ")" ::: "memory")
; #define PG8_WAIT_L(n) asm volatile("s_waitcnt lgkmcnt(" #n ")" ::: "memory")
; #define PG8_BAR __builtin_amdgcn_s_barrier()
; #define PG8_SCHED __builtin_amdgcn_sched_barrier(0)
; template <class Epi, class Sched, bool ALIGN_EPI = false, bool SP2 = false>
; __device__ __forceinline__ void gemm_phase(PG8_LAS unsigned char* lds, const Gemm g, const Sched& S, const Epi& E) {
;     ...
;             PG8_LDA(At, 1, 1); PG8_STAGE(PG8_SB(1, 0), b3, voffB); PG8_STAGE(PG8_SB(1, 1), b3 + hstepB, voffB); PG8_STAGE(PG8_SA(1, 0), a3, voffA);
;             PG8_WAIT_V(8); PG8_WAIT_L(0); PG8_BAR; PG8_MMA(1, 0, At, B0); PG8_MMA(1, 1, At, B1); PG8_BAR; PG8_SCHED;
;     ...
;         if constexpr (ALIGN_EPI) { if (wr == 0) PG8_BAR; }
	s_add_i32 s56, s65, s55
	v_lshl_add_u64 v[192:193], v[192:193], 0, s[60:61]
	s_mov_b32 m0, s56
	ds_read_b128 v[216:219], v191 offset:49152
	ds_read_b128 v[220:223], v191 offset:50176
	ds_read_b128 v[224:227], v191 offset:51200
	ds_read_b128 v[228:231], v191 offset:52224
	ds_read_b128 v[232:235], v191 offset:53248
	ds_read_b128 v[236:239], v191 offset:54272
	ds_read_b128 v[240:243], v191 offset:55296
	ds_read_b128 v[244:247], v191 offset:56320
	global_load_lds_dwordx4 v[192:193], off
	s_add_i32 m0, s56, 0x2000
	s_add_u32 s22, s22, 0x80080
	v_lshl_add_u64 v[192:193], v[248:249], 0, s[60:61]
	s_addc_u32 s23, s23, 0
	s_add_i32 s56, s72, s55
	global_load_lds_dwordx4 v[192:193], off
	v_lshl_add_u64 v[192:193], s[22:23], 0, v[156:157]
	s_mov_b32 m0, s56
	s_nop 0
	global_load_lds_dwordx4 v[192:193], off
	v_lshl_add_u64 v[192:193], s[22:23], 0, v[160:161]
	s_add_i32 m0, s56, 0x2000
	s_nop 0
	global_load_lds_dwordx4 v[192:193], off
	v_lshl_add_u64 v[192:193], v[202:203], 0, s[60:61]
	s_mov_b32 m0, s71
	s_nop 0
	global_load_lds_dwordx4 v[192:193], off
	v_lshl_add_u64 v[192:193], v[204:205], 0, s[60:61]
	s_mov_b32 m0, s48
	s_nop 0
	global_load_lds_dwordx4 v[192:193], off
	s_waitcnt vmcnt(8)
	s_waitcnt lgkmcnt(0)
	s_barrier
	s_setprio 1
	s_waitcnt lgkmcnt(0)
	v_mfma_f32_16x16x32_bf16 v[60:63], v[130:133], v[216:219], v[60:63]
	v_mfma_f32_16x16x32_bf16 v[60:63], v[134:137], v[220:223], v[60:63]
	v_mfma_f32_16x16x32_bf16 v[56:59], v[142:145], v[220:223], v[56:59]
	v_mfma_f32_16x16x32_bf16 v[56:59], v[138:141], v[216:219], v[56:59]
	v_mfma_f32_16x16x32_bf16 v[40:43], v[138:141], v[224:227], v[40:43]
	v_mfma_f32_16x16x32_bf16 v[40:43], v[142:145], v[228:231], v[40:43]
	v_mfma_f32_16x16x32_bf16 v[44:47], v[134:137], v[228:231], v[44:47]
	v_mfma_f32_16x16x32_bf16 v[44:47], v[130:133], v[224:227], v[44:47]
	v_mfma_f32_16x16x32_bf16 v[28:31], v[130:133], v[232:235], v[28:31]
	v_mfma_f32_16x16x32_bf16 v[28:31], v[134:137], v[236:239], v[28:31]
	v_mfma_f32_16x16x32_bf16 v[24:27], v[142:145], v[236:239], v[24:27]
	v_mfma_f32_16x16x32_bf16 v[24:27], v[138:141], v[232:235], v[24:27]
	s_setprio 0
	s_setprio 1
	v_mfma_f32_16x16x32_bf16 v[8:11], v[138:141], v[240:243], v[8:11]
	v_mfma_f32_16x16x32_bf16 v[8:11], v[142:145], v[244:247], v[8:11]
	v_mfma_f32_16x16x32_bf16 v[12:15], v[134:137], v[244:247], v[12:15]
	v_mfma_f32_16x16x32_bf16 v[12:15], v[130:133], v[240:243], v[12:15]
	v_mfma_f32_16x16x32_bf16 v[52:55], v[146:149], v[216:219], v[52:55]
	v_mfma_f32_16x16x32_bf16 v[52:55], v[150:153], v[220:223], v[52:55]
	v_mfma_f32_16x16x32_bf16 v[48:51], v[182:185], v[220:223], v[48:51]
	v_mfma_f32_16x16x32_bf16 v[48:51], v[174:177], v[216:219], v[48:51]
	v_mfma_f32_16x16x32_bf16 v[32:35], v[174:177], v[224:227], v[32:35]
	v_mfma_f32_16x16x32_bf16 v[32:35], v[182:185], v[228:231], v[32:35]
	v_mfma_f32_16x16x32_bf16 v[36:39], v[150:153], v[228:231], v[36:39]
	v_mfma_f32_16x16x32_bf16 v[36:39], v[146:149], v[224:227], v[36:39]
	v_mfma_f32_16x16x32_bf16 v[20:23], v[146:149], v[232:235], v[20:23]
	v_mfma_f32_16x16x32_bf16 v[20:23], v[150:153], v[236:239], v[20:23]
	v_mfma_f32_16x16x32_bf16 v[16:19], v[182:185], v[236:239], v[16:19]
	v_mfma_f32_16x16x32_bf16 v[16:19], v[174:177], v[232:235], v[16:19]
	v_mfma_f32_16x16x32_bf16 v[0:3], v[174:177], v[240:243], v[0:3]
	v_mfma_f32_16x16x32_bf16 v[0:3], v[182:185], v[244:247], v[0:3]
	v_mfma_f32_16x16x32_bf16 v[4:7], v[150:153], v[244:247], v[4:7]
	v_mfma_f32_16x16x32_bf16 v[4:7], v[146:149], v[240:243], v[4:7]
	s_setprio 0
	s_barrier
	s_add_i32 s64, s64, 2
	s_add_u32 s42, s42, 0x100
	s_addc_u32 s43, s43, 0
	s_add_u32 s49, s49, 0x100
	s_addc_u32 s51, s51, 0
	s_cmp_gt_u32 s64, 29
	s_cbranch_scc0 .LBB0_324
	s_and_b64 vcc, exec, s[46:47]
	s_cbranch_vccz .LBB0_327
	s_barrier

; #define PG8_STAGE(bufoff, gbase, voff) do { _Pragma("unroll") for (int _i = 0; _i < 2; ++_i) \
;         __builtin_amdgcn_global_load_lds((const unsigned*)((const char*)(gbase) + (voff)[_i]), (PG8_LAS unsigned*)(lds + (bufoff) + ldsw + _i * 8192), 16, 0, 0); } while (0)
; #define PG8_LDA(dst, b, h) do { _Pragma("unroll") for (int m = 0; m < 4; ++m) _Pragma("unroll") for (int k = 0; k < 2; ++k) dst[m][k] = *(const PG8_LAS bf16x8*)(lds + PG8_SA(b, h) + aoff + m * 2048 + k * 1024); } while (0)
; #define PG8_LDB(dst, b, h) do { _Pragma("unroll") for (int n = 0; n < 2; ++n) _Pragma("unroll") for (int k = 0; k < 2; ++k) dst[n][k] = *(const PG8_LAS bf16x8*)(lds + PG8_SB(b, h) + boff + n * 2048 + k * 1024); } while (0)
; #define PG8_MMA(ai, bj, At, Bt) do { __builtin_amdgcn_s_setprio(1); _Pragma("unroll") for (int m = 0; m < 4; ++m) _Pragma("unroll") for (int n = 0; n < 2; ++n) _Pragma("unroll") for (int k = 0; k < 2; ++k) \
;         acc[ai][bj][m][n] = __builtin_amdgcn_mfma_f32_16x16x32_bf16(Bt[n][k], At[m][k], acc[ai][bj][m][n], 0, 0, 0); __builtin_amdgcn_s_setprio(0); } while (0)
; #define PG8_WAIT_V(n) asm volatile("s_waitcnt vmcnt(" #n ")" ::: "memory")
; #define PG8_WAIT_L(n) asm volatile("s_waitcnt lgkmcnt(" #n ")" ::: "memory")
; #define PG8_BAR __builtin_amdgcn_s_barrier()
; #define PG8_SCHED __builtin_amdgcn_sched_barrier(0)
; template <class Epi, class Sched, bool ALIGN_EPI = false, bool SP2 = false>
; __device__ __forceinline__ void gemm_phase(PG8_LAS unsigned char* lds, const Gemm g, const Sched& S, const Epi& E) {
;     ...
;             const bool last = (t == nt - 2);
;             const char* a1 = cA + (size_t)(t + 1) * kstep;
;             const char* a2 = last ? nA : cA + (size_t)(t + 2) * kstep; const char* b2 = last ? nB : cB + (size_t)(t + 2) * kstep;
;             const char* a3 = a2 + kstep; const char* b3 = b2 + kstep;
;             if (last && has_next) S.a_ready(nxt);
;             if constexpr (SP2) {
;             PG8_LDB(B0, 0, 0); PG8_LDB(B1, 0, 1); PG8_SCHED; PG8_LDA(At, 0, 0); PG8_STAGE(PG8_SA(1, 1), a1 + hstepA, voffA);
;             PG8_WAIT_V(8); PG8_WAIT_L(0); PG8_BAR; PG8_MMA(0, 0, At, B0); PG8_MMA(0, 1, At, B1); PG8_BAR; PG8_SCHED;
;             PG8_LDA(At, 0, 1); PG8_STAGE(PG8_SB(0, 0), b2, voffB); PG8_STAGE(PG8_SB(0, 1), b2 + hstepB, voffB); PG8_STAGE(PG8_SA(0, 0), a2, voffA);
.LBB0_618:
	s_add_u32 s48, s46, 0x100
	s_addc_u32 s49, s47, 0
	s_add_i32 s66, 0, 0x10000
	s_cmp_eq_u32 s65, 4
	s_cselect_b32 s51, s43, s49
	s_cselect_b32 s50, s42, s48
	v_add_u32_e32 v145, s66, v143
	s_cselect_b32 s23, s41, s64
	s_cselect_b32 s22, s62, s63
	s_add_i32 s67, 0, 0x14000
	ds_read_b128 v[146:149], v145
	ds_read_b128 v[150:153], v145 offset:1024
	ds_read_b128 v[154:157], v145 offset:2048
	ds_read_b128 v[158:161], v145 offset:3072
	v_add_u32_e32 v145, s67, v143
	ds_read_b128 v[162:165], v145
	ds_read_b128 v[166:169], v145 offset:1024
	ds_read_b128 v[170:173], v145 offset:2048
	ds_read_b128 v[174:177], v145 offset:3072
	v_lshl_add_u64 v[192:193], s[46:47], 0, v[138:139]
	s_add_i32 m0, s33, 0xc000
	ds_read_b128 v[182:185], v144
	ds_read_b128 v[188:191], v144 offset:1024
	ds_read_b128 v[216:219], v144 offset:2048
	ds_read_b128 v[220:223], v144 offset:3072
	ds_read_b128 v[224:227], v144 offset:4096
	ds_read_b128 v[228:231], v144 offset:5120
	ds_read_b128 v[232:235], v144 offset:6144
	ds_read_b128 v[236:239], v144 offset:7168
	global_load_lds_dwordx4 v[192:193], off
	v_lshl_add_u64 v[192:193], s[46:47], 0, v[140:141]
	s_add_i32 m0, s33, 0xe000
	s_nop 0
	global_load_lds_dwordx4 v[192:193], off
	s_waitcnt vmcnt(8)
	s_waitcnt lgkmcnt(0)
	s_barrier
	s_setprio 1
	s_waitcnt lgkmcnt(0)
	v_mfma_f32_16x16x32_bf16 v[126:129], v[146:149], v[182:185], v[126:129]
	v_mfma_f32_16x16x32_bf16 v[126:129], v[150:153], v[188:191], v[126:129]
	v_mfma_f32_16x16x32_bf16 v[122:125], v[158:161], v[188:191], v[122:125]
	v_mfma_f32_16x16x32_bf16 v[122:125], v[154:157], v[182:185], v[122:125]
	v_mfma_f32_16x16x32_bf16 v[114:117], v[154:157], v[216:219], v[114:117]
	v_mfma_f32_16x16x32_bf16 v[114:117], v[158:161], v[220:223], v[114:117]
	v_mfma_f32_16x16x32_bf16 v[118:121], v[150:153], v[220:223], v[118:121]
	v_mfma_f32_16x16x32_bf16 v[118:121], v[146:149], v[216:219], v[118:121]
	v_mfma_f32_16x16x32_bf16 v[102:105], v[146:149], v[224:227], v[102:105]
	v_mfma_f32_16x16x32_bf16 v[102:105], v[150:153], v[228:231], v[102:105]
	v_mfma_f32_16x16x32_bf16 v[98:101], v[158:161], v[228:231], v[98:101]
	v_mfma_f32_16x16x32_bf16 v[98:101], v[154:157], v[224:227], v[98:101]
	s_setprio 0
	s_setprio 1
	v_mfma_f32_16x16x32_bf16 v[82:85], v[154:157], v[232:235], v[82:85]
	v_mfma_f32_16x16x32_bf16 v[82:85], v[158:161], v[236:239], v[82:85]
	v_mfma_f32_16x16x32_bf16 v[86:89], v[150:153], v[236:239], v[86:89]
	v_mfma_f32_16x16x32_bf16 v[86:89], v[146:149], v[232:235], v[86:89]
	v_mfma_f32_16x16x32_bf16 v[110:113], v[162:165], v[182:185], v[110:113]
	v_mfma_f32_16x16x32_bf16 v[110:113], v[166:169], v[188:191], v[110:113]
	v_mfma_f32_16x16x32_bf16 v[106:109], v[174:177], v[188:191], v[106:109]
	v_mfma_f32_16x16x32_bf16 v[106:109], v[170:173], v[182:185], v[106:109]
	v_mfma_f32_16x16x32_bf16 v[90:93], v[170:173], v[216:219], v[90:93]
	v_mfma_f32_16x16x32_bf16 v[90:93], v[174:177], v[220:223], v[90:93]
	v_mfma_f32_16x16x32_bf16 v[94:97], v[166:169], v[220:223], v[94:97]
	v_mfma_f32_16x16x32_bf16 v[94:97], v[162:165], v[216:219], v[94:97]
	v_mfma_f32_16x16x32_bf16 v[76:79], v[162:165], v[224:227], v[76:79]
	v_mfma_f32_16x16x32_bf16 v[76:79], v[166:169], v[228:231], v[76:79]
	v_mfma_f32_16x16x32_bf16 v[72:75], v[174:177], v[228:231], v[72:75]
	v_mfma_f32_16x16x32_bf16 v[72:75], v[170:173], v[224:227], v[72:75]
	v_mfma_f32_16x16x32_bf16 v[64:67], v[170:173], v[232:235], v[64:67]
	v_mfma_f32_16x16x32_bf16 v[64:67], v[174:177], v[236:239], v[64:67]
	v_mfma_f32_16x16x32_bf16 v[68:71], v[166:169], v[236:239], v[68:71]
	v_mfma_f32_16x16x32_bf16 v[68:71], v[162:165], v[232:235], v[68:71]
	s_setprio 0
	s_barrier
	s_add_i32 s46, s66, s31
	v_lshl_add_u64 v[192:193], s[22:23], 0, v[80:81]
	s_mov_b32 m0, s46
	ds_read_b128 v[182:185], v144 offset:16384
	ds_read_b128 v[188:191], v144 offset:17408
	ds_read_b128 v[216:219], v144 offset:18432
	ds_read_b128 v[220:223], v144 offset:19456
	ds_read_b128 v[224:227], v144 offset:20480
	ds_read_b128 v[228:231], v144 offset:21504
	ds_read_b128 v[232:235], v144 offset:22528
	ds_read_b128 v[236:239], v144 offset:23552
	global_load_lds_dwordx4 v[192:193], off
	s_add_i32 m0, s46, 0x2000
	s_add_u32 s46, s22, 0x20000
	v_lshl_add_u64 v[202:203], s[22:23], 0, v[134:135]
	s_addc_u32 s47, s23, 0
	s_add_i32 s66, s67, s31
	global_load_lds_dwordx4 v[202:203], off
	v_lshl_add_u64 v[204:205], s[46:47], 0, v[80:81]
	s_mov_b32 m0, s66
	v_lshl_add_u64 v[206:207], s[50:51], 0, v[132:133]
	global_load_lds_dwordx4 v[204:205], off
	v_lshl_add_u64 v[204:205], s[46:47], 0, v[134:135]
	s_add_i32 m0, s66, 0x2000
	s_nop 0
	global_load_lds_dwordx4 v[204:205], off
	v_lshl_add_u64 v[204:205], s[50:51], 0, v[130:131]
	s_mov_b32 m0, s33
	s_nop 0
	global_load_lds_dwordx4 v[204:205], off
	s_mov_b32 m0, s35
	s_nop 0
	global_load_lds_dwordx4 v[206:207], off
	s_waitcnt vmcnt(8)
	s_waitcnt lgkmcnt(0)
	s_barrier
; #define PG8_STAGE(bufoff, gbase, voff) do { _Pragma("unroll") for (int _i = 0; _i < 2; ++_i) \
;         __builtin_amdgcn_global_load_lds((const unsigned*)((const char*)(gbase) + (voff)[_i]), (PG8_LAS unsigned*)(lds + (bufoff) + ldsw + _i * 8192), 16, 0, 0); } while (0)
; #define PG8_LDA(dst, b, h) do { _Pragma("unroll") for (int m = 0; m < 4; ++m) _Pragma("unroll") for (int k = 0; k < 2; ++k) dst[m][k] = *(const PG8_LAS bf16x8*)(lds + PG8_SA(b, h) + aoff + m * 2048 + k * 1024); } while (0)
; #define PG8_LDB(dst, b, h) do { _Pragma("unroll") for (int n = 0; n < 2; ++n) _Pragma("unroll") for (int k = 0; k < 2; ++k) dst[n][k] = *(const PG8_LAS bf16x8*)(lds + PG8_SB(b, h) + boff + n * 2048 + k * 1024); } while (0)
; #define PG8_MMA(ai, bj, At, Bt) do { __builtin_amdgcn_s_setprio(1); _Pragma("unroll") for (int m = 0; m < 4; ++m) _Pragma("unroll") for (int n = 0; n < 2; ++n) _Pragma("unroll") for (int k = 0; k < 2; ++k) \
;         acc[ai][bj][m][n] = __builtin_amdgcn_mfma_f32_16x16x32_bf16(Bt[n][k], At[m][k], acc[ai][bj][m][n], 0, 0, 0); __builtin_amdgcn_s_setprio(0); } while (0)
; #define PG8_WAIT_V(n) asm volatile("s_waitcnt vmcnt(" #n ")" ::: "memory")
; #define PG8_WAIT_L(n) asm volatile("s_waitcnt lgkmcnt(" #n ")" ::: "memory")
; #define PG8_BAR __builtin_amdgcn_s_barrier()
; #define PG8_SCHED __builtin_amdgcn_sched_barrier(0)
; template <class Epi, class Sched, bool ALIGN_EPI = false, bool SP2 = false>
; __device__ __forceinline__ void gemm_phase(PG8_LAS unsigned char* lds, const Gemm g, const Sched& S, const Epi& E) {
;     ...
;             PG8_WAIT_V(8); PG8_WAIT_L(0); PG8_BAR; PG8_MMA(1, 0, At, B0); PG8_MMA(1, 1, At, B1); PG8_BAR; PG8_SCHED;
;             PG8_LDB(B0, 1, 0); PG8_LDB(B1, 1, 1); PG8_SCHED; PG8_LDA(At, 1, 0); PG8_STAGE(PG8_SA(0, 1), a2 + hstepA, voffA);
;             PG8_WAIT_V(8); PG8_WAIT_L(0); PG8_BAR; PG8_MMA(0, 0, At, B0); PG8_MMA(0, 1, At, B1); PG8_BAR; PG8_SCHED;
	s_setprio 1
	s_waitcnt lgkmcnt(0)
	v_mfma_f32_16x16x32_bf16 v[60:63], v[146:149], v[182:185], v[60:63]
	v_mfma_f32_16x16x32_bf16 v[60:63], v[150:153], v[188:191], v[60:63]
	v_mfma_f32_16x16x32_bf16 v[56:59], v[158:161], v[188:191], v[56:59]
	v_mfma_f32_16x16x32_bf16 v[56:59], v[154:157], v[182:185], v[56:59]
	v_mfma_f32_16x16x32_bf16 v[48:51], v[154:157], v[216:219], v[48:51]
	v_mfma_f32_16x16x32_bf16 v[48:51], v[158:161], v[220:223], v[48:51]
	v_mfma_f32_16x16x32_bf16 v[52:55], v[150:153], v[220:223], v[52:55]
	v_mfma_f32_16x16x32_bf16 v[52:55], v[146:149], v[216:219], v[52:55]
	v_mfma_f32_16x16x32_bf16 v[36:39], v[146:149], v[224:227], v[36:39]
	v_mfma_f32_16x16x32_bf16 v[36:39], v[150:153], v[228:231], v[36:39]
	v_mfma_f32_16x16x32_bf16 v[32:35], v[158:161], v[228:231], v[32:35]
	v_mfma_f32_16x16x32_bf16 v[32:35], v[154:157], v[224:227], v[32:35]
	s_setprio 0
	s_setprio 1
	v_mfma_f32_16x16x32_bf16 v[16:19], v[154:157], v[232:235], v[16:19]
	v_mfma_f32_16x16x32_bf16 v[16:19], v[158:161], v[236:239], v[16:19]
	v_mfma_f32_16x16x32_bf16 v[20:23], v[150:153], v[236:239], v[20:23]
	v_mfma_f32_16x16x32_bf16 v[20:23], v[146:149], v[232:235], v[20:23]
	v_mfma_f32_16x16x32_bf16 v[44:47], v[162:165], v[182:185], v[44:47]
	v_mfma_f32_16x16x32_bf16 v[44:47], v[166:169], v[188:191], v[44:47]
	v_mfma_f32_16x16x32_bf16 v[40:43], v[174:177], v[188:191], v[40:43]
	v_mfma_f32_16x16x32_bf16 v[40:43], v[170:173], v[182:185], v[40:43]
	v_mfma_f32_16x16x32_bf16 v[24:27], v[170:173], v[216:219], v[24:27]
	v_mfma_f32_16x16x32_bf16 v[24:27], v[174:177], v[220:223], v[24:27]
	v_mfma_f32_16x16x32_bf16 v[28:31], v[166:169], v[220:223], v[28:31]
	v_mfma_f32_16x16x32_bf16 v[28:31], v[162:165], v[216:219], v[28:31]
	v_mfma_f32_16x16x32_bf16 v[12:15], v[162:165], v[224:227], v[12:15]
	v_mfma_f32_16x16x32_bf16 v[12:15], v[166:169], v[228:231], v[12:15]
	v_mfma_f32_16x16x32_bf16 v[8:11], v[174:177], v[228:231], v[8:11]
	v_mfma_f32_16x16x32_bf16 v[8:11], v[170:173], v[224:227], v[8:11]
	v_mfma_f32_16x16x32_bf16 v[0:3], v[170:173], v[232:235], v[0:3]
	v_mfma_f32_16x16x32_bf16 v[0:3], v[174:177], v[236:239], v[0:3]
	v_mfma_f32_16x16x32_bf16 v[4:7], v[166:169], v[236:239], v[4:7]
	v_mfma_f32_16x16x32_bf16 v[4:7], v[162:165], v[232:235], v[4:7]
	s_setprio 0
	s_barrier
	s_add_i32 s66, 0, 0x18000
	v_add_u32_e32 v145, s66, v143
	s_add_i32 s67, 0, 0x1c000
	ds_read_b128 v[146:149], v145
	ds_read_b128 v[150:153], v145 offset:1024
	ds_read_b128 v[154:157], v145 offset:2048
	ds_read_b128 v[158:161], v145 offset:3072
	v_add_u32_e32 v145, s67, v143
	ds_read_b128 v[162:165], v145
	ds_read_b128 v[166:169], v145 offset:1024
	ds_read_b128 v[170:173], v145 offset:2048
	ds_read_b128 v[174:177], v145 offset:3072
	s_add_u32 s46, s50, 0x30000
	s_addc_u32 s47, s51, 0
	s_mov_b32 m0, s36
	v_lshl_add_u64 v[240:241], s[46:47], 0, v[130:131]
	ds_read_b128 v[182:185], v144 offset:32768
	ds_read_b128 v[188:191], v144 offset:33792
	ds_read_b128 v[216:219], v144 offset:34816
	ds_read_b128 v[220:223], v144 offset:35840
	ds_read_b128 v[224:227], v144 offset:36864
	ds_read_b128 v[228:231], v144 offset:37888
	ds_read_b128 v[232:235], v144 offset:38912
	ds_read_b128 v[236:239], v144 offset:39936
	global_load_lds_dwordx4 v[240:241], off
	v_lshl_add_u64 v[240:241], s[46:47], 0, v[132:133]
	s_mov_b32 m0, s37
	s_nop 0
	global_load_lds_dwordx4 v[240:241], off
	s_waitcnt vmcnt(8)
	s_waitcnt lgkmcnt(0)
	s_barrier
	s_setprio 1
	s_waitcnt lgkmcnt(0)
	v_mfma_f32_16x16x32_bf16 v[126:129], v[146:149], v[182:185], v[126:129]
	v_mfma_f32_16x16x32_bf16 v[126:129], v[150:153], v[188:191], v[126:129]
	v_mfma_f32_16x16x32_bf16 v[122:125], v[158:161], v[188:191], v[122:125]
	v_mfma_f32_16x16x32_bf16 v[122:125], v[154:157], v[182:185], v[122:125]
	v_mfma_f32_16x16x32_bf16 v[114:117], v[154:157], v[216:219], v[114:117]
	v_mfma_f32_16x16x32_bf16 v[114:117], v[158:161], v[220:223], v[114:117]
	v_mfma_f32_16x16x32_bf16 v[118:121], v[150:153], v[220:223], v[118:121]
	v_mfma_f32_16x16x32_bf16 v[118:121], v[146:149], v[216:219], v[118:121]
	v_mfma_f32_16x16x32_bf16 v[102:105], v[146:149], v[224:227], v[102:105]
	v_mfma_f32_16x16x32_bf16 v[102:105], v[150:153], v[228:231], v[102:105]
	v_mfma_f32_16x16x32_bf16 v[98:101], v[158:161], v[228:231], v[98:101]
	v_mfma_f32_16x16x32_bf16 v[98:101], v[154:157], v[224:227], v[98:101]
	s_setprio 0
	s_setprio 1
	v_mfma_f32_16x16x32_bf16 v[82:85], v[154:157], v[232:235], v[82:85]
	v_mfma_f32_16x16x32_bf16 v[82:85], v[158:161], v[236:239], v[82:85]
	v_mfma_f32_16x16x32_bf16 v[86:89], v[150:153], v[236:239], v[86:89]
	v_mfma_f32_16x16x32_bf16 v[86:89], v[146:149], v[232:235], v[86:89]
	v_mfma_f32_16x16x32_bf16 v[110:113], v[162:165], v[182:185], v[110:113]
	v_mfma_f32_16x16x32_bf16 v[110:113], v[166:169], v[188:191], v[110:113]
	v_mfma_f32_16x16x32_bf16 v[106:109], v[174:177], v[188:191], v[106:109]
	v_mfma_f32_16x16x32_bf16 v[106:109], v[170:173], v[182:185], v[106:109]
	v_mfma_f32_16x16x32_bf16 v[90:93], v[170:173], v[216:219], v[90:93]
	v_mfma_f32_16x16x32_bf16 v[90:93], v[174:177], v[220:223], v[90:93]
	v_mfma_f32_16x16x32_bf16 v[94:97], v[166:169], v[220:223], v[94:97]
	v_mfma_f32_16x16x32_bf16 v[94:97], v[162:165], v[216:219], v[94:97]
	v_mfma_f32_16x16x32_bf16 v[76:79], v[162:165], v[224:227], v[76:79]
	v_mfma_f32_16x16x32_bf16 v[76:79], v[166:169], v[228:231], v[76:79]
	v_mfma_f32_16x16x32_bf16 v[72:75], v[174:177], v[228:231], v[72:75]
	v_mfma_f32_16x16x32_bf16 v[72:75], v[170:173], v[224:227], v[72:75]
	v_mfma_f32_16x16x32_bf16 v[64:67], v[170:173], v[232:235], v[64:67]
	v_mfma_f32_16x16x32_bf16 v[64:67], v[174:177], v[236:239], v[64:67]
	v_mfma_f32_16x16x32_bf16 v[68:71], v[166:169], v[236:239], v[68:71]
	v_mfma_f32_16x16x32_bf16 v[68:71], v[162:165], v[232:235], v[68:71]
	s_setprio 0
	s_barrier
; #define PG8_STAGE(bufoff, gbase, voff) do { _Pragma("unroll") for (int _i = 0; _i < 2; ++_i) \
;         __builtin_amdgcn_global_load_lds((const unsigned*)((const char*)(gbase) + (voff)[_i]), (PG8_LAS unsigned*)(lds + (bufoff) + ldsw + _i * 8192), 16, 0, 0); } while (0)
; #define PG8_LDA(dst, b, h) do { _Pragma("unroll") for (int m = 0; m < 4; ++m) _Pragma("unroll") for (int k = 0; k < 2; ++k) dst[m][k] = *(const PG8_LAS bf16x8*)(lds + PG8_SA(b, h) + aoff + m * 2048 + k * 1024); } while (0)
; #define PG8_MMA(ai, bj, At, Bt) do { __builtin_amdgcn_s_setprio(1); _Pragma("unroll") for (int m = 0; m < 4; ++m) _Pragma("unroll") for (int n = 0; n < 2; ++n) _Pragma("unroll") for (int k = 0; k < 2; ++k) \
;         acc[ai][bj][m][n] = __builtin_amdgcn_mfma_f32_16x16x32_bf16(Bt[n][k], At[m][k], acc[ai][bj][m][n], 0, 0, 0); __builtin_amdgcn_s_setprio(0); } while (0)
; #define PG8_WAIT_V(n) asm volatile("s_waitcnt vmcnt(" #n ")" ::: "memory")
; #define PG8_WAIT_L(n) asm volatile("s_waitcnt lgkmcnt(" #n ")" ::: "memory")
; #define PG8_BAR __builtin_amdgcn_s_barrier()
; #define PG8_SCHED __builtin_amdgcn_sched_barrier(0)
; template <class Epi, class Sched, bool ALIGN_EPI = false, bool SP2 = false>
; __device__ __forceinline__ void gemm_phase(PG8_LAS unsigned char* lds, const Gemm g, const Sched& S, const Epi& E) {
;     ...
;         for (int t = 0; t < nt; t += 2) {
;     ...
;             PG8_LDA(At, 1, 1); PG8_STAGE(PG8_SB(1, 0), b3, voffB); PG8_STAGE(PG8_SB(1, 1), b3 + hstepB, voffB); PG8_STAGE(PG8_SA(1, 0), a3, voffA);
;             PG8_WAIT_V(8); PG8_WAIT_L(0); PG8_BAR; PG8_MMA(1, 0, At, B0); PG8_MMA(1, 1, At, B1); PG8_BAR; PG8_SCHED;
	s_add_i32 s46, s66, s31
	v_lshl_add_u64 v[192:193], v[192:193], 0, s[60:61]
	s_mov_b32 m0, s46
	ds_read_b128 v[182:185], v144 offset:49152
	ds_read_b128 v[188:191], v144 offset:50176
	ds_read_b128 v[216:219], v144 offset:51200
	ds_read_b128 v[220:223], v144 offset:52224
	ds_read_b128 v[224:227], v144 offset:53248
	ds_read_b128 v[228:231], v144 offset:54272
	ds_read_b128 v[232:235], v144 offset:55296
	ds_read_b128 v[236:239], v144 offset:56320
	global_load_lds_dwordx4 v[192:193], off
	s_add_i32 m0, s46, 0x2000
	s_add_u32 s22, s22, 0x20080
	v_lshl_add_u64 v[192:193], v[202:203], 0, s[60:61]
	s_addc_u32 s23, s23, 0
	s_add_i32 s46, s67, s31
	global_load_lds_dwordx4 v[192:193], off
	v_lshl_add_u64 v[192:193], s[22:23], 0, v[80:81]
	s_mov_b32 m0, s46
	s_nop 0
	global_load_lds_dwordx4 v[192:193], off
	v_lshl_add_u64 v[192:193], s[22:23], 0, v[134:135]
	s_add_i32 m0, s46, 0x2000
	s_nop 0
	global_load_lds_dwordx4 v[192:193], off
	v_lshl_add_u64 v[192:193], v[204:205], 0, s[60:61]
	s_mov_b32 m0, s53
	s_nop 0
	global_load_lds_dwordx4 v[192:193], off
	v_lshl_add_u64 v[192:193], v[206:207], 0, s[60:61]
	s_mov_b32 m0, s55
	s_nop 0
	global_load_lds_dwordx4 v[192:193], off
	s_waitcnt vmcnt(8)
	s_waitcnt lgkmcnt(0)
	s_barrier
	s_setprio 1
	s_waitcnt lgkmcnt(0)
	v_mfma_f32_16x16x32_bf16 v[60:63], v[146:149], v[182:185], v[60:63]
	v_mfma_f32_16x16x32_bf16 v[60:63], v[150:153], v[188:191], v[60:63]
	v_mfma_f32_16x16x32_bf16 v[56:59], v[158:161], v[188:191], v[56:59]
	v_mfma_f32_16x16x32_bf16 v[56:59], v[154:157], v[182:185], v[56:59]
	v_mfma_f32_16x16x32_bf16 v[48:51], v[154:157], v[216:219], v[48:51]
	v_mfma_f32_16x16x32_bf16 v[48:51], v[158:161], v[220:223], v[48:51]
	v_mfma_f32_16x16x32_bf16 v[52:55], v[150:153], v[220:223], v[52:55]
	v_mfma_f32_16x16x32_bf16 v[52:55], v[146:149], v[216:219], v[52:55]
	v_mfma_f32_16x16x32_bf16 v[36:39], v[146:149], v[224:227], v[36:39]
	v_mfma_f32_16x16x32_bf16 v[36:39], v[150:153], v[228:231], v[36:39]
	v_mfma_f32_16x16x32_bf16 v[32:35], v[158:161], v[228:231], v[32:35]
	v_mfma_f32_16x16x32_bf16 v[32:35], v[154:157], v[224:227], v[32:35]
	s_setprio 0
	s_setprio 1
	v_mfma_f32_16x16x32_bf16 v[16:19], v[154:157], v[232:235], v[16:19]
	v_mfma_f32_16x16x32_bf16 v[16:19], v[158:161], v[236:239], v[16:19]
	v_mfma_f32_16x16x32_bf16 v[20:23], v[150:153], v[236:239], v[20:23]
	v_mfma_f32_16x16x32_bf16 v[20:23], v[146:149], v[232:235], v[20:23]
	v_mfma_f32_16x16x32_bf16 v[44:47], v[162:165], v[182:185], v[44:47]
	v_mfma_f32_16x16x32_bf16 v[44:47], v[166:169], v[188:191], v[44:47]
	v_mfma_f32_16x16x32_bf16 v[40:43], v[174:177], v[188:191], v[40:43]
	v_mfma_f32_16x16x32_bf16 v[40:43], v[170:173], v[182:185], v[40:43]
	v_mfma_f32_16x16x32_bf16 v[24:27], v[170:173], v[216:219], v[24:27]
	v_mfma_f32_16x16x32_bf16 v[24:27], v[174:177], v[220:223], v[24:27]
	v_mfma_f32_16x16x32_bf16 v[28:31], v[166:169], v[220:223], v[28:31]
	v_mfma_f32_16x16x32_bf16 v[28:31], v[162:165], v[216:219], v[28:31]
	v_mfma_f32_16x16x32_bf16 v[12:15], v[162:165], v[224:227], v[12:15]
	v_mfma_f32_16x16x32_bf16 v[12:15], v[166:169], v[228:231], v[12:15]
	v_mfma_f32_16x16x32_bf16 v[8:11], v[174:177], v[228:231], v[8:11]
	v_mfma_f32_16x16x32_bf16 v[8:11], v[170:173], v[224:227], v[8:11]
	v_mfma_f32_16x16x32_bf16 v[0:3], v[170:173], v[232:235], v[0:3]
	v_mfma_f32_16x16x32_bf16 v[0:3], v[174:177], v[236:239], v[0:3]
	v_mfma_f32_16x16x32_bf16 v[4:7], v[166:169], v[236:239], v[4:7]
	v_mfma_f32_16x16x32_bf16 v[4:7], v[162:165], v[232:235], v[4:7]
	s_setprio 0
	s_barrier
	s_add_i32 s65, s65, 2
	s_add_u32 s63, s63, 0x100
	s_addc_u32 s64, s64, 0
	s_cmp_gt_u32 s65, 5
	s_mov_b64 s[46:47], s[48:49]
	s_cbranch_scc0 .LBB0_618
	s_and_b64 vcc, exec, s[20:21]
	s_cbranch_vccz .LBB0_621
	s_barrier

; #define PG8_STAGE(bufoff, gbase, voff) do { _Pragma("unroll") for (int _i = 0; _i < 2; ++_i) \
;         __builtin_amdgcn_global_load_lds((const unsigned*)((const char*)(gbase) + (voff)[_i]), (PG8_LAS unsigned*)(lds + (bufoff) + ldsw + _i * 8192), 16, 0, 0); } while (0)
; #define PG8_LDA(dst, b, h) do { _Pragma("unroll") for (int m = 0; m < 4; ++m) _Pragma("unroll") for (int k = 0; k < 2; ++k) dst[m][k] = *(const PG8_LAS bf16x8*)(lds + PG8_SA(b, h) + aoff + m * 2048 + k * 1024); } while (0)
; #define PG8_LDB(dst, b, h) do { _Pragma("unroll") for (int n = 0; n < 2; ++n) _Pragma("unroll") for (int k = 0; k < 2; ++k) dst[n][k] = *(const PG8_LAS bf16x8*)(lds + PG8_SB(b, h) + boff + n * 2048 + k * 1024); } while (0)
; #define PG8_MMA(ai, bj, At, Bt) do { __builtin_amdgcn_s_setprio(1); _Pragma("unroll") for (int m = 0; m < 4; ++m) _Pragma("unroll") for (int n = 0; n < 2; ++n) _Pragma("unroll") for (int k = 0; k < 2; ++k) \
;         acc[ai][bj][m][n] = __builtin_amdgcn_mfma_f32_16x16x32_bf16(Bt[n][k], At[m][k], acc[ai][bj][m][n], 0, 0, 0); __builtin_amdgcn_s_setprio(0); } while (0)
; #define PG8_WAIT_V(n) asm volatile("s_waitcnt vmcnt(" #n ")" ::: "memory")
; #define PG8_WAIT_L(n) asm volatile("s_waitcnt lgkmcnt(" #n ")" ::: "memory")
; #define PG8_BAR __builtin_amdgcn_s_barrier()
; #define PG8_SCHED __builtin_amdgcn_sched_barrier(0)
; template <class Epi, class Sched, bool ALIGN_EPI = false, bool SP2 = false>
; __device__ __forceinline__ void gemm_phase(PG8_LAS unsigned char* lds, const Gemm g, const Sched& S, const Epi& E) {
;     ...
;             const bool last = (t == nt - 2);
;             const char* a1 = cA + (size_t)(t + 1) * kstep;
;             const char* a2 = last ? nA : cA + (size_t)(t + 2) * kstep; const char* b2 = last ? nB : cB + (size_t)(t + 2) * kstep;
;             const char* a3 = a2 + kstep; const char* b3 = b2 + kstep;
;             if (last && has_next) S.a_ready(nxt);
;             if constexpr (SP2) {
;             PG8_LDB(B0, 0, 0); PG8_LDB(B1, 0, 1); PG8_SCHED; PG8_LDA(At, 0, 0); PG8_STAGE(PG8_SA(1, 1), a1 + hstepA, voffA);
;             PG8_WAIT_V(8); PG8_WAIT_L(0); PG8_BAR; PG8_MMA(0, 0, At, B0); PG8_MMA(0, 1, At, B1); PG8_BAR; PG8_SCHED;
;             PG8_LDA(At, 0, 1); PG8_STAGE(PG8_SB(0, 0), b2, voffB); PG8_STAGE(PG8_SB(0, 1), b2 + hstepB, voffB); PG8_STAGE(PG8_SA(0, 0), a2, voffA);
.LBB0_868:
	s_add_u32 s20, s0, 0x100
	s_addc_u32 s21, s1, 0
	s_add_i32 s67, 0, 0x10000
	s_cmp_eq_u32 s37, 8
	s_cselect_b32 s51, s47, s21
	s_cselect_b32 s50, s46, s20
	v_add_u32_e32 v80, s67, v151
	s_cselect_b32 s23, s49, s36
	s_cselect_b32 s22, s48, s35
	s_add_i32 s68, 0, 0x14000
	ds_read_b128 v[142:145], v80
	ds_read_b128 v[146:149], v80 offset:1024
	ds_read_b128 v[156:159], v80 offset:2048
	ds_read_b128 v[160:163], v80 offset:3072
	v_add_u32_e32 v80, s68, v151
	ds_read_b128 v[164:167], v80
	ds_read_b128 v[168:171], v80 offset:1024
	ds_read_b128 v[172:175], v80 offset:2048
	ds_read_b128 v[182:185], v80 offset:3072
	v_lshl_add_u64 v[176:177], s[0:1], 0, v[138:139]
	s_add_i32 m0, s53, 0xc000
	ds_read_b128 v[188:191], v154
	ds_read_b128 v[216:219], v154 offset:1024
	ds_read_b128 v[220:223], v154 offset:2048
	ds_read_b128 v[224:227], v154 offset:3072
	ds_read_b128 v[228:231], v154 offset:4096
	ds_read_b128 v[232:235], v154 offset:5120
	ds_read_b128 v[236:239], v154 offset:6144
	ds_read_b128 v[240:243], v154 offset:7168
	global_load_lds_dwordx4 v[176:177], off
	v_lshl_add_u64 v[176:177], s[0:1], 0, v[140:141]
	s_add_i32 m0, s53, 0xe000
	s_nop 0
	global_load_lds_dwordx4 v[176:177], off
	s_waitcnt vmcnt(8)
	s_waitcnt lgkmcnt(0)
	s_barrier
	s_setprio 1
	s_waitcnt lgkmcnt(0)
	v_mfma_f32_16x16x32_bf16 v[126:129], v[142:145], v[188:191], v[126:129]
	v_mfma_f32_16x16x32_bf16 v[126:129], v[146:149], v[216:219], v[126:129]
	v_mfma_f32_16x16x32_bf16 v[122:125], v[160:163], v[216:219], v[122:125]
	v_mfma_f32_16x16x32_bf16 v[122:125], v[156:159], v[188:191], v[122:125]
	v_mfma_f32_16x16x32_bf16 v[106:109], v[156:159], v[220:223], v[106:109]
	v_mfma_f32_16x16x32_bf16 v[106:109], v[160:163], v[224:227], v[106:109]
	v_mfma_f32_16x16x32_bf16 v[110:113], v[146:149], v[224:227], v[110:113]
	v_mfma_f32_16x16x32_bf16 v[110:113], v[142:145], v[220:223], v[110:113]
	v_mfma_f32_16x16x32_bf16 v[94:97], v[142:145], v[228:231], v[94:97]
	v_mfma_f32_16x16x32_bf16 v[94:97], v[146:149], v[232:235], v[94:97]
	v_mfma_f32_16x16x32_bf16 v[90:93], v[160:163], v[232:235], v[90:93]
	v_mfma_f32_16x16x32_bf16 v[90:93], v[156:159], v[228:231], v[90:93]
	s_setprio 0
	s_setprio 1
	v_mfma_f32_16x16x32_bf16 v[72:75], v[156:159], v[236:239], v[72:75]
	v_mfma_f32_16x16x32_bf16 v[72:75], v[160:163], v[240:243], v[72:75]
	v_mfma_f32_16x16x32_bf16 v[76:79], v[146:149], v[240:243], v[76:79]
	v_mfma_f32_16x16x32_bf16 v[76:79], v[142:145], v[236:239], v[76:79]
	v_mfma_f32_16x16x32_bf16 v[118:121], v[164:167], v[188:191], v[118:121]
	v_mfma_f32_16x16x32_bf16 v[118:121], v[168:171], v[216:219], v[118:121]
	v_mfma_f32_16x16x32_bf16 v[114:117], v[182:185], v[216:219], v[114:117]
	v_mfma_f32_16x16x32_bf16 v[114:117], v[172:175], v[188:191], v[114:117]
	v_mfma_f32_16x16x32_bf16 v[98:101], v[172:175], v[220:223], v[98:101]
	v_mfma_f32_16x16x32_bf16 v[98:101], v[182:185], v[224:227], v[98:101]
	v_mfma_f32_16x16x32_bf16 v[102:105], v[168:171], v[224:227], v[102:105]
	v_mfma_f32_16x16x32_bf16 v[102:105], v[164:167], v[220:223], v[102:105]
	v_mfma_f32_16x16x32_bf16 v[86:89], v[164:167], v[228:231], v[86:89]
	v_mfma_f32_16x16x32_bf16 v[86:89], v[168:171], v[232:235], v[86:89]
	v_mfma_f32_16x16x32_bf16 v[82:85], v[182:185], v[232:235], v[82:85]
	v_mfma_f32_16x16x32_bf16 v[82:85], v[172:175], v[228:231], v[82:85]
	v_mfma_f32_16x16x32_bf16 v[64:67], v[172:175], v[236:239], v[64:67]
	v_mfma_f32_16x16x32_bf16 v[64:67], v[182:185], v[240:243], v[64:67]
	v_mfma_f32_16x16x32_bf16 v[68:71], v[168:171], v[240:243], v[68:71]
	v_mfma_f32_16x16x32_bf16 v[68:71], v[164:167], v[236:239], v[68:71]
	s_setprio 0
	s_barrier
	s_add_i32 s0, s67, s52
	v_lshl_add_u64 v[176:177], s[22:23], 0, v[132:133]
	s_mov_b32 m0, s0
	ds_read_b128 v[188:191], v154 offset:16384
	ds_read_b128 v[216:219], v154 offset:17408
	ds_read_b128 v[220:223], v154 offset:18432
	ds_read_b128 v[224:227], v154 offset:19456
	ds_read_b128 v[228:231], v154 offset:20480
	ds_read_b128 v[232:235], v154 offset:21504
	ds_read_b128 v[236:239], v154 offset:22528
	ds_read_b128 v[240:243], v154 offset:23552
	global_load_lds_dwordx4 v[176:177], off
	s_add_i32 m0, s0, 0x2000
	s_add_u32 s0, s22, 0x30000
	v_lshl_add_u64 v[192:193], s[22:23], 0, v[136:137]
	s_addc_u32 s1, s23, 0
	s_add_i32 s67, s68, s52
	global_load_lds_dwordx4 v[192:193], off
	v_lshl_add_u64 v[202:203], s[0:1], 0, v[132:133]
	s_mov_b32 m0, s67
	v_lshl_add_u64 v[204:205], s[50:51], 0, v[134:135]
	global_load_lds_dwordx4 v[202:203], off
	v_lshl_add_u64 v[202:203], s[0:1], 0, v[136:137]
	s_add_i32 m0, s67, 0x2000
	s_nop 0
	global_load_lds_dwordx4 v[202:203], off
	v_lshl_add_u64 v[202:203], s[50:51], 0, v[130:131]
	s_mov_b32 m0, s53
	s_nop 0
	global_load_lds_dwordx4 v[202:203], off
	s_mov_b32 m0, s55
	s_nop 0
	global_load_lds_dwordx4 v[204:205], off
	s_waitcnt vmcnt(8)
	s_waitcnt lgkmcnt(0)
	s_barrier
; #define PG8_STAGE(bufoff, gbase, voff) do { _Pragma("unroll") for (int _i = 0; _i < 2; ++_i) \
;         __builtin_amdgcn_global_load_lds((const unsigned*)((const char*)(gbase) + (voff)[_i]), (PG8_LAS unsigned*)(lds + (bufoff) + ldsw + _i * 8192), 16, 0, 0); } while (0)
; #define PG8_LDA(dst, b, h) do { _Pragma("unroll") for (int m = 0; m < 4; ++m) _Pragma("unroll") for (int k = 0; k < 2; ++k) dst[m][k] = *(const PG8_LAS bf16x8*)(lds + PG8_SA(b, h) + aoff + m * 2048 + k * 1024); } while (0)
; #define PG8_LDB(dst, b, h) do { _Pragma("unroll") for (int n = 0; n < 2; ++n) _Pragma("unroll") for (int k = 0; k < 2; ++k) dst[n][k] = *(const PG8_LAS bf16x8*)(lds + PG8_SB(b, h) + boff + n * 2048 + k * 1024); } while (0)
; #define PG8_MMA(ai, bj, At, Bt) do { __builtin_amdgcn_s_setprio(1); _Pragma("unroll") for (int m = 0; m < 4; ++m) _Pragma("unroll") for (int n = 0; n < 2; ++n) _Pragma("unroll") for (int k = 0; k < 2; ++k) \
;         acc[ai][bj][m][n] = __builtin_amdgcn_mfma_f32_16x16x32_bf16(Bt[n][k], At[m][k], acc[ai][bj][m][n], 0, 0, 0); __builtin_amdgcn_s_setprio(0); } while (0)
; #define PG8_WAIT_V(n) asm volatile("s_waitcnt vmcnt(" #n ")" ::: "memory")
; #define PG8_WAIT_L(n) asm volatile("s_waitcnt lgkmcnt(" #n ")" ::: "memory")
; #define PG8_BAR __builtin_amdgcn_s_barrier()
; #define PG8_SCHED __builtin_amdgcn_sched_barrier(0)
; template <class Epi, class Sched, bool ALIGN_EPI = false, bool SP2 = false>
; __device__ __forceinline__ void gemm_phase(PG8_LAS unsigned char* lds, const Gemm g, const Sched& S, const Epi& E) {
;     ...
;             PG8_WAIT_V(8); PG8_WAIT_L(0); PG8_BAR; PG8_MMA(1, 0, At, B0); PG8_MMA(1, 1, At, B1); PG8_BAR; PG8_SCHED;
;             PG8_LDB(B0, 1, 0); PG8_LDB(B1, 1, 1); PG8_SCHED; PG8_LDA(At, 1, 0); PG8_STAGE(PG8_SA(0, 1), a2 + hstepA, voffA);
;             PG8_WAIT_V(8); PG8_WAIT_L(0); PG8_BAR; PG8_MMA(0, 0, At, B0); PG8_MMA(0, 1, At, B1); PG8_BAR; PG8_SCHED;
	s_setprio 1
	s_waitcnt lgkmcnt(0)
	v_mfma_f32_16x16x32_bf16 v[60:63], v[142:145], v[188:191], v[60:63]
	v_mfma_f32_16x16x32_bf16 v[60:63], v[146:149], v[216:219], v[60:63]
	v_mfma_f32_16x16x32_bf16 v[56:59], v[160:163], v[216:219], v[56:59]
	v_mfma_f32_16x16x32_bf16 v[56:59], v[156:159], v[188:191], v[56:59]
	v_mfma_f32_16x16x32_bf16 v[40:43], v[156:159], v[220:223], v[40:43]
	v_mfma_f32_16x16x32_bf16 v[40:43], v[160:163], v[224:227], v[40:43]
	v_mfma_f32_16x16x32_bf16 v[44:47], v[146:149], v[224:227], v[44:47]
	v_mfma_f32_16x16x32_bf16 v[44:47], v[142:145], v[220:223], v[44:47]
	v_mfma_f32_16x16x32_bf16 v[28:31], v[142:145], v[228:231], v[28:31]
	v_mfma_f32_16x16x32_bf16 v[28:31], v[146:149], v[232:235], v[28:31]
	v_mfma_f32_16x16x32_bf16 v[24:27], v[160:163], v[232:235], v[24:27]
	v_mfma_f32_16x16x32_bf16 v[24:27], v[156:159], v[228:231], v[24:27]
	s_setprio 0
	s_setprio 1
	v_mfma_f32_16x16x32_bf16 v[8:11], v[156:159], v[236:239], v[8:11]
	v_mfma_f32_16x16x32_bf16 v[8:11], v[160:163], v[240:243], v[8:11]
	v_mfma_f32_16x16x32_bf16 v[12:15], v[146:149], v[240:243], v[12:15]
	v_mfma_f32_16x16x32_bf16 v[12:15], v[142:145], v[236:239], v[12:15]
	v_mfma_f32_16x16x32_bf16 v[52:55], v[164:167], v[188:191], v[52:55]
	v_mfma_f32_16x16x32_bf16 v[52:55], v[168:171], v[216:219], v[52:55]
	v_mfma_f32_16x16x32_bf16 v[48:51], v[182:185], v[216:219], v[48:51]
	v_mfma_f32_16x16x32_bf16 v[48:51], v[172:175], v[188:191], v[48:51]
	v_mfma_f32_16x16x32_bf16 v[32:35], v[172:175], v[220:223], v[32:35]
	v_mfma_f32_16x16x32_bf16 v[32:35], v[182:185], v[224:227], v[32:35]
	v_mfma_f32_16x16x32_bf16 v[36:39], v[168:171], v[224:227], v[36:39]
	v_mfma_f32_16x16x32_bf16 v[36:39], v[164:167], v[220:223], v[36:39]
	v_mfma_f32_16x16x32_bf16 v[20:23], v[164:167], v[228:231], v[20:23]
	v_mfma_f32_16x16x32_bf16 v[20:23], v[168:171], v[232:235], v[20:23]
	v_mfma_f32_16x16x32_bf16 v[16:19], v[182:185], v[232:235], v[16:19]
	v_mfma_f32_16x16x32_bf16 v[16:19], v[172:175], v[228:231], v[16:19]
	v_mfma_f32_16x16x32_bf16 v[0:3], v[172:175], v[236:239], v[0:3]
	v_mfma_f32_16x16x32_bf16 v[0:3], v[182:185], v[240:243], v[0:3]
	v_mfma_f32_16x16x32_bf16 v[4:7], v[168:171], v[240:243], v[4:7]
	v_mfma_f32_16x16x32_bf16 v[4:7], v[164:167], v[236:239], v[4:7]
	s_setprio 0
	s_barrier
	s_add_i32 s67, 0, 0x18000
	v_add_u32_e32 v80, s67, v151
	s_add_i32 s68, 0, 0x1c000
	ds_read_b128 v[142:145], v80
	ds_read_b128 v[146:149], v80 offset:1024
	ds_read_b128 v[156:159], v80 offset:2048
	ds_read_b128 v[160:163], v80 offset:3072
	v_add_u32_e32 v80, s68, v151
	ds_read_b128 v[164:167], v80
	ds_read_b128 v[168:171], v80 offset:1024
	ds_read_b128 v[172:175], v80 offset:2048
	ds_read_b128 v[182:185], v80 offset:3072
	s_add_u32 s0, s50, 0x30000
	s_addc_u32 s1, s51, 0
	s_mov_b32 m0, s56
	v_lshl_add_u64 v[206:207], s[0:1], 0, v[130:131]
	ds_read_b128 v[188:191], v154 offset:32768
	ds_read_b128 v[216:219], v154 offset:33792
	ds_read_b128 v[220:223], v154 offset:34816
	ds_read_b128 v[224:227], v154 offset:35840
	ds_read_b128 v[228:231], v154 offset:36864
	ds_read_b128 v[232:235], v154 offset:37888
	ds_read_b128 v[236:239], v154 offset:38912
	ds_read_b128 v[240:243], v154 offset:39936
	global_load_lds_dwordx4 v[206:207], off
	v_lshl_add_u64 v[206:207], s[0:1], 0, v[134:135]
	s_mov_b32 m0, s57
	s_nop 0
	global_load_lds_dwordx4 v[206:207], off
	s_waitcnt vmcnt(8)
	s_waitcnt lgkmcnt(0)
	s_barrier
	s_setprio 1
	s_waitcnt lgkmcnt(0)
	v_mfma_f32_16x16x32_bf16 v[126:129], v[142:145], v[188:191], v[126:129]
	v_mfma_f32_16x16x32_bf16 v[126:129], v[146:149], v[216:219], v[126:129]
	v_mfma_f32_16x16x32_bf16 v[122:125], v[160:163], v[216:219], v[122:125]
	v_mfma_f32_16x16x32_bf16 v[122:125], v[156:159], v[188:191], v[122:125]
	v_mfma_f32_16x16x32_bf16 v[106:109], v[156:159], v[220:223], v[106:109]
	v_mfma_f32_16x16x32_bf16 v[106:109], v[160:163], v[224:227], v[106:109]
	v_mfma_f32_16x16x32_bf16 v[110:113], v[146:149], v[224:227], v[110:113]
	v_mfma_f32_16x16x32_bf16 v[110:113], v[142:145], v[220:223], v[110:113]
	v_mfma_f32_16x16x32_bf16 v[94:97], v[142:145], v[228:231], v[94:97]
	v_mfma_f32_16x16x32_bf16 v[94:97], v[146:149], v[232:235], v[94:97]
	v_mfma_f32_16x16x32_bf16 v[90:93], v[160:163], v[232:235], v[90:93]
	v_mfma_f32_16x16x32_bf16 v[90:93], v[156:159], v[228:231], v[90:93]
	s_setprio 0
	s_setprio 1
	v_mfma_f32_16x16x32_bf16 v[72:75], v[156:159], v[236:239], v[72:75]
	v_mfma_f32_16x16x32_bf16 v[72:75], v[160:163], v[240:243], v[72:75]
	v_mfma_f32_16x16x32_bf16 v[76:79], v[146:149], v[240:243], v[76:79]
	v_mfma_f32_16x16x32_bf16 v[76:79], v[142:145], v[236:239], v[76:79]
	v_mfma_f32_16x16x32_bf16 v[118:121], v[164:167], v[188:191], v[118:121]
	v_mfma_f32_16x16x32_bf16 v[118:121], v[168:171], v[216:219], v[118:121]
	v_mfma_f32_16x16x32_bf16 v[114:117], v[182:185], v[216:219], v[114:117]
	v_mfma_f32_16x16x32_bf16 v[114:117], v[172:175], v[188:191], v[114:117]
	v_mfma_f32_16x16x32_bf16 v[98:101], v[172:175], v[220:223], v[98:101]
	v_mfma_f32_16x16x32_bf16 v[98:101], v[182:185], v[224:227], v[98:101]
	v_mfma_f32_16x16x32_bf16 v[102:105], v[168:171], v[224:227], v[102:105]
	v_mfma_f32_16x16x32_bf16 v[102:105], v[164:167], v[220:223], v[102:105]
	v_mfma_f32_16x16x32_bf16 v[86:89], v[164:167], v[228:231], v[86:89]
	v_mfma_f32_16x16x32_bf16 v[86:89], v[168:171], v[232:235], v[86:89]
	v_mfma_f32_16x16x32_bf16 v[82:85], v[182:185], v[232:235], v[82:85]
	v_mfma_f32_16x16x32_bf16 v[82:85], v[172:175], v[228:231], v[82:85]
	v_mfma_f32_16x16x32_bf16 v[64:67], v[172:175], v[236:239], v[64:67]
	v_mfma_f32_16x16x32_bf16 v[64:67], v[182:185], v[240:243], v[64:67]
	v_mfma_f32_16x16x32_bf16 v[68:71], v[168:171], v[240:243], v[68:71]
	v_mfma_f32_16x16x32_bf16 v[68:71], v[164:167], v[236:239], v[68:71]
	s_setprio 0
	s_barrier
; #define PG8_STAGE(bufoff, gbase, voff) do { _Pragma("unroll") for (int _i = 0; _i < 2; ++_i) \
;         __builtin_amdgcn_global_load_lds((const unsigned*)((const char*)(gbase) + (voff)[_i]), (PG8_LAS unsigned*)(lds + (bufoff) + ldsw + _i * 8192), 16, 0, 0); } while (0)
; #define PG8_LDA(dst, b, h) do { _Pragma("unroll") for (int m = 0; m < 4; ++m) _Pragma("unroll") for (int k = 0; k < 2; ++k) dst[m][k] = *(const PG8_LAS bf16x8*)(lds + PG8_SA(b, h) + aoff + m * 2048 + k * 1024); } while (0)
; #define PG8_MMA(ai, bj, At, Bt) do { __builtin_amdgcn_s_setprio(1); _Pragma("unroll") for (int m = 0; m < 4; ++m) _Pragma("unroll") for (int n = 0; n < 2; ++n) _Pragma("unroll") for (int k = 0; k < 2; ++k) \
;         acc[ai][bj][m][n] = __builtin_amdgcn_mfma_f32_16x16x32_bf16(Bt[n][k], At[m][k], acc[ai][bj][m][n], 0, 0, 0); __builtin_amdgcn_s_setprio(0); } while (0)
; #define PG8_WAIT_V(n) asm volatile("s_waitcnt vmcnt(" #n ")" ::: "memory")
; #define PG8_WAIT_L(n) asm volatile("s_waitcnt lgkmcnt(" #n ")" ::: "memory")
; #define PG8_BAR __builtin_amdgcn_s_barrier()
; #define PG8_SCHED __builtin_amdgcn_sched_barrier(0)
; template <class Epi, class Sched, bool ALIGN_EPI = false, bool SP2 = false>
; __device__ __forceinline__ void gemm_phase(PG8_LAS unsigned char* lds, const Gemm g, const Sched& S, const Epi& E) {
;     ...
;         for (int t = 0; t < nt; t += 2) {
;     ...
;             PG8_LDA(At, 1, 1); PG8_STAGE(PG8_SB(1, 0), b3, voffB); PG8_STAGE(PG8_SB(1, 1), b3 + hstepB, voffB); PG8_STAGE(PG8_SA(1, 0), a3, voffA);
;             PG8_WAIT_V(8); PG8_WAIT_L(0); PG8_BAR; PG8_MMA(1, 0, At, B0); PG8_MMA(1, 1, At, B1); PG8_BAR; PG8_SCHED;
	s_add_i32 s0, s67, s52
	v_lshl_add_u64 v[176:177], v[176:177], 0, s[60:61]
	s_mov_b32 m0, s0
	ds_read_b128 v[188:191], v154 offset:49152
	ds_read_b128 v[216:219], v154 offset:50176
	ds_read_b128 v[220:223], v154 offset:51200
	ds_read_b128 v[224:227], v154 offset:52224
	ds_read_b128 v[228:231], v154 offset:53248
	ds_read_b128 v[232:235], v154 offset:54272
	ds_read_b128 v[236:239], v154 offset:55296
	ds_read_b128 v[240:243], v154 offset:56320
	global_load_lds_dwordx4 v[176:177], off
	s_add_i32 m0, s0, 0x2000
	s_add_u32 s0, s22, 0x30080
	v_lshl_add_u64 v[176:177], v[192:193], 0, s[60:61]
	s_addc_u32 s1, s23, 0
	s_add_i32 s22, s68, s52
	global_load_lds_dwordx4 v[176:177], off
	v_lshl_add_u64 v[176:177], s[0:1], 0, v[132:133]
	s_mov_b32 m0, s22
	s_nop 0
	global_load_lds_dwordx4 v[176:177], off
	v_lshl_add_u64 v[176:177], s[0:1], 0, v[136:137]
	s_add_i32 m0, s22, 0x2000
	s_nop 0
	global_load_lds_dwordx4 v[176:177], off
	v_lshl_add_u64 v[176:177], v[202:203], 0, s[60:61]
	s_mov_b32 m0, s62
	s_nop 0
	global_load_lds_dwordx4 v[176:177], off
	v_lshl_add_u64 v[176:177], v[204:205], 0, s[60:61]
	s_mov_b32 m0, s63
	s_nop 0
	global_load_lds_dwordx4 v[176:177], off
	s_waitcnt vmcnt(8)
	s_waitcnt lgkmcnt(0)
	s_barrier
	s_setprio 1
	s_waitcnt lgkmcnt(0)
	v_mfma_f32_16x16x32_bf16 v[60:63], v[142:145], v[188:191], v[60:63]
	v_mfma_f32_16x16x32_bf16 v[60:63], v[146:149], v[216:219], v[60:63]
	v_mfma_f32_16x16x32_bf16 v[56:59], v[160:163], v[216:219], v[56:59]
	v_mfma_f32_16x16x32_bf16 v[56:59], v[156:159], v[188:191], v[56:59]
	v_mfma_f32_16x16x32_bf16 v[40:43], v[156:159], v[220:223], v[40:43]
	v_mfma_f32_16x16x32_bf16 v[40:43], v[160:163], v[224:227], v[40:43]
	v_mfma_f32_16x16x32_bf16 v[44:47], v[146:149], v[224:227], v[44:47]
	v_mfma_f32_16x16x32_bf16 v[44:47], v[142:145], v[220:223], v[44:47]
	v_mfma_f32_16x16x32_bf16 v[28:31], v[142:145], v[228:231], v[28:31]
	v_mfma_f32_16x16x32_bf16 v[28:31], v[146:149], v[232:235], v[28:31]
	v_mfma_f32_16x16x32_bf16 v[24:27], v[160:163], v[232:235], v[24:27]
	v_mfma_f32_16x16x32_bf16 v[24:27], v[156:159], v[228:231], v[24:27]
	s_setprio 0
	s_setprio 1
	v_mfma_f32_16x16x32_bf16 v[8:11], v[156:159], v[236:239], v[8:11]
	v_mfma_f32_16x16x32_bf16 v[8:11], v[160:163], v[240:243], v[8:11]
	v_mfma_f32_16x16x32_bf16 v[12:15], v[146:149], v[240:243], v[12:15]
	v_mfma_f32_16x16x32_bf16 v[12:15], v[142:145], v[236:239], v[12:15]
	v_mfma_f32_16x16x32_bf16 v[52:55], v[164:167], v[188:191], v[52:55]
	v_mfma_f32_16x16x32_bf16 v[52:55], v[168:171], v[216:219], v[52:55]
	v_mfma_f32_16x16x32_bf16 v[48:51], v[182:185], v[216:219], v[48:51]
	v_mfma_f32_16x16x32_bf16 v[48:51], v[172:175], v[188:191], v[48:51]
	v_mfma_f32_16x16x32_bf16 v[32:35], v[172:175], v[220:223], v[32:35]
	v_mfma_f32_16x16x32_bf16 v[32:35], v[182:185], v[224:227], v[32:35]
	v_mfma_f32_16x16x32_bf16 v[36:39], v[168:171], v[224:227], v[36:39]
	v_mfma_f32_16x16x32_bf16 v[36:39], v[164:167], v[220:223], v[36:39]
	v_mfma_f32_16x16x32_bf16 v[20:23], v[164:167], v[228:231], v[20:23]
	v_mfma_f32_16x16x32_bf16 v[20:23], v[168:171], v[232:235], v[20:23]
	v_mfma_f32_16x16x32_bf16 v[16:19], v[182:185], v[232:235], v[16:19]
	v_mfma_f32_16x16x32_bf16 v[16:19], v[172:175], v[228:231], v[16:19]
	v_mfma_f32_16x16x32_bf16 v[0:3], v[172:175], v[236:239], v[0:3]
	v_mfma_f32_16x16x32_bf16 v[0:3], v[182:185], v[240:243], v[0:3]
	v_mfma_f32_16x16x32_bf16 v[4:7], v[168:171], v[240:243], v[4:7]
	v_mfma_f32_16x16x32_bf16 v[4:7], v[164:167], v[236:239], v[4:7]
	s_setprio 0
	s_barrier
	s_add_i32 s37, s37, 2
	s_add_u32 s35, s35, 0x100
	s_addc_u32 s36, s36, 0
	s_cmp_gt_u32 s37, 9
	s_mov_b64 s[0:1], s[20:21]
	s_cbranch_scc0 .LBB0_868
	s_and_b64 vcc, exec, s[44:45]
	s_cbranch_vccz .LBB0_871
	s_barrier

; #define PG8_STAGE(bufoff, gbase, voff) do { _Pragma("unroll") for (int _i = 0; _i < 2; ++_i) \
;         __builtin_amdgcn_global_load_lds((const unsigned*)((const char*)(gbase) + (voff)[_i]), (PG8_LAS unsigned*)(lds + (bufoff) + ldsw + _i * 8192), 16, 0, 0); } while (0)
; #define PG8_LDA(dst, b, h) do { _Pragma("unroll") for (int m = 0; m < 4; ++m) _Pragma("unroll") for (int k = 0; k < 2; ++k) dst[m][k] = *(const PG8_LAS bf16x8*)(lds + PG8_SA(b, h) + aoff + m * 2048 + k * 1024); } while (0)
; #define PG8_LDB(dst, b, h) do { _Pragma("unroll") for (int n = 0; n < 2; ++n) _Pragma("unroll") for (int k = 0; k < 2; ++k) dst[n][k] = *(const PG8_LAS bf16x8*)(lds + PG8_SB(b, h) + boff + n * 2048 + k * 1024); } while (0)
; #define PG8_MMA(ai, bj, At, Bt) do { __builtin_amdgcn_s_setprio(1); _Pragma("unroll") for (int m = 0; m < 4; ++m) _Pragma("unroll") for (int n = 0; n < 2; ++n) _Pragma("unroll") for (int k = 0; k < 2; ++k) \
;         acc[ai][bj][m][n] = __builtin_amdgcn_mfma_f32_16x16x32_bf16(Bt[n][k], At[m][k], acc[ai][bj][m][n], 0, 0, 0); __builtin_amdgcn_s_setprio(0); } while (0)
; #define PG8_WAIT_V(n) asm volatile("s_waitcnt vmcnt(" #n ")" ::: "memory")
; #define PG8_WAIT_L(n) asm volatile("s_waitcnt lgkmcnt(" #n ")" ::: "memory")
; #define PG8_BAR __builtin_amdgcn_s_barrier()
; #define PG8_SCHED __builtin_amdgcn_sched_barrier(0)
; template <class Epi, class Sched, bool ALIGN_EPI = false, bool SP2 = false>
; __device__ __forceinline__ void gemm_phase(PG8_LAS unsigned char* lds, const Gemm g, const Sched& S, const Epi& E) {
;     ...
;             const bool last = (t == nt - 2);
;             const char* a1 = cA + (size_t)(t + 1) * kstep;
;             const char* a2 = last ? nA : cA + (size_t)(t + 2) * kstep; const char* b2 = last ? nB : cB + (size_t)(t + 2) * kstep;
;             const char* a3 = a2 + kstep; const char* b3 = b2 + kstep;
;             if (last && has_next) S.a_ready(nxt);
;             if constexpr (SP2) {
;             PG8_LDB(B0, 0, 0); PG8_LDB(B1, 0, 1); PG8_SCHED; PG8_LDA(At, 0, 0); PG8_STAGE(PG8_SA(1, 1), a1 + hstepA, voffA);
;             PG8_WAIT_V(8); PG8_WAIT_L(0); PG8_BAR; PG8_MMA(0, 0, At, B0); PG8_MMA(0, 1, At, B1); PG8_BAR; PG8_SCHED;
;             PG8_LDA(At, 0, 1); PG8_STAGE(PG8_SB(0, 0), b2, voffB); PG8_STAGE(PG8_SB(0, 1), b2 + hstepB, voffB); PG8_STAGE(PG8_SA(0, 0), a2, voffA);
.LBB0_952:
	s_add_u32 s20, s0, 0xfffc0080
	s_addc_u32 s21, s1, -1
	s_add_i32 s51, 0, 0x10000
	s_cmp_eq_u32 s49, 12
	s_cselect_b32 s23, s28, s21
	s_cselect_b32 s22, s33, s20
	v_add_u32_e32 v148, s51, v152
	s_cselect_b32 s21, s35, s47
	s_cselect_b32 s20, s36, s37
	s_add_i32 s53, 0, 0x14000
	ds_read_b128 v[140:143], v148
	ds_read_b128 v[144:147], v148 offset:1024
	ds_read_b128 v[154:157], v148 offset:2048
	ds_read_b128 v[158:161], v148 offset:3072
	v_add_u32_e32 v148, s53, v152
	ds_read_b128 v[162:165], v148
	ds_read_b128 v[166:169], v148 offset:1024
	ds_read_b128 v[170:173], v148 offset:2048
	ds_read_b128 v[174:177], v148 offset:3072
	v_lshl_add_u64 v[148:149], s[0:1], 0, v[136:137]
	s_add_i32 m0, s56, 0xc000
	ds_read_b128 v[182:185], v153
	ds_read_b128 v[188:191], v153 offset:1024
	ds_read_b128 v[216:219], v153 offset:2048
	ds_read_b128 v[220:223], v153 offset:3072
	ds_read_b128 v[224:227], v153 offset:4096
	ds_read_b128 v[228:231], v153 offset:5120
	ds_read_b128 v[232:235], v153 offset:6144
	ds_read_b128 v[236:239], v153 offset:7168
	global_load_lds_dwordx4 v[148:149], off
	v_lshl_add_u64 v[148:149], s[0:1], 0, v[138:139]
	s_add_i32 m0, s56, 0xe000
	s_nop 0
	global_load_lds_dwordx4 v[148:149], off
	s_waitcnt vmcnt(8)
	s_waitcnt lgkmcnt(0)
	s_barrier
	s_setprio 1
	s_waitcnt lgkmcnt(0)
	v_mfma_f32_16x16x32_bf16 v[126:129], v[140:143], v[182:185], v[126:129]
	v_mfma_f32_16x16x32_bf16 v[126:129], v[144:147], v[188:191], v[126:129]
	v_mfma_f32_16x16x32_bf16 v[122:125], v[158:161], v[188:191], v[122:125]
	v_mfma_f32_16x16x32_bf16 v[122:125], v[154:157], v[182:185], v[122:125]
	v_mfma_f32_16x16x32_bf16 v[106:109], v[154:157], v[216:219], v[106:109]
	v_mfma_f32_16x16x32_bf16 v[106:109], v[158:161], v[220:223], v[106:109]
	v_mfma_f32_16x16x32_bf16 v[110:113], v[144:147], v[220:223], v[110:113]
	v_mfma_f32_16x16x32_bf16 v[110:113], v[140:143], v[216:219], v[110:113]
	v_mfma_f32_16x16x32_bf16 v[94:97], v[140:143], v[224:227], v[94:97]
	v_mfma_f32_16x16x32_bf16 v[94:97], v[144:147], v[228:231], v[94:97]
	v_mfma_f32_16x16x32_bf16 v[90:93], v[158:161], v[228:231], v[90:93]
	v_mfma_f32_16x16x32_bf16 v[90:93], v[154:157], v[224:227], v[90:93]
	s_setprio 0
	s_setprio 1
	v_mfma_f32_16x16x32_bf16 v[72:75], v[154:157], v[232:235], v[72:75]
	v_mfma_f32_16x16x32_bf16 v[72:75], v[158:161], v[236:239], v[72:75]
	v_mfma_f32_16x16x32_bf16 v[76:79], v[144:147], v[236:239], v[76:79]
	v_mfma_f32_16x16x32_bf16 v[76:79], v[140:143], v[232:235], v[76:79]
	v_mfma_f32_16x16x32_bf16 v[118:121], v[162:165], v[182:185], v[118:121]
	v_mfma_f32_16x16x32_bf16 v[118:121], v[166:169], v[188:191], v[118:121]
	v_mfma_f32_16x16x32_bf16 v[114:117], v[174:177], v[188:191], v[114:117]
	v_mfma_f32_16x16x32_bf16 v[114:117], v[170:173], v[182:185], v[114:117]
	v_mfma_f32_16x16x32_bf16 v[98:101], v[170:173], v[216:219], v[98:101]
	v_mfma_f32_16x16x32_bf16 v[98:101], v[174:177], v[220:223], v[98:101]
	v_mfma_f32_16x16x32_bf16 v[102:105], v[166:169], v[220:223], v[102:105]
	v_mfma_f32_16x16x32_bf16 v[102:105], v[162:165], v[216:219], v[102:105]
	v_mfma_f32_16x16x32_bf16 v[86:89], v[162:165], v[224:227], v[86:89]
	v_mfma_f32_16x16x32_bf16 v[86:89], v[166:169], v[228:231], v[86:89]
	v_mfma_f32_16x16x32_bf16 v[82:85], v[174:177], v[228:231], v[82:85]
	v_mfma_f32_16x16x32_bf16 v[82:85], v[170:173], v[224:227], v[82:85]
	v_mfma_f32_16x16x32_bf16 v[64:67], v[170:173], v[232:235], v[64:67]
	v_mfma_f32_16x16x32_bf16 v[64:67], v[174:177], v[236:239], v[64:67]
	v_mfma_f32_16x16x32_bf16 v[68:71], v[166:169], v[236:239], v[68:71]
	v_mfma_f32_16x16x32_bf16 v[68:71], v[162:165], v[232:235], v[68:71]
	s_setprio 0
	s_barrier
	s_add_i32 s51, s51, s55
	v_lshl_add_u64 v[148:149], s[20:21], 0, v[80:81]
	s_mov_b32 m0, s51
	ds_read_b128 v[182:185], v153 offset:16384
	ds_read_b128 v[188:191], v153 offset:17408
	ds_read_b128 v[216:219], v153 offset:18432
	ds_read_b128 v[220:223], v153 offset:19456
	ds_read_b128 v[224:227], v153 offset:20480
	ds_read_b128 v[228:231], v153 offset:21504
	ds_read_b128 v[232:235], v153 offset:22528
	ds_read_b128 v[236:239], v153 offset:23552
	global_load_lds_dwordx4 v[148:149], off
	s_add_i32 m0, s51, 0x2000
	s_add_u32 s72, s20, 0x40000
	v_lshl_add_u64 v[192:193], s[20:21], 0, v[130:131]
	s_addc_u32 s73, s21, 0
	s_add_i32 s51, s53, s55
	global_load_lds_dwordx4 v[192:193], off
	v_lshl_add_u64 v[202:203], s[72:73], 0, v[80:81]
	s_mov_b32 m0, s51
	v_lshl_add_u64 v[204:205], s[22:23], 0, v[132:133]
	global_load_lds_dwordx4 v[202:203], off
	v_lshl_add_u64 v[202:203], s[72:73], 0, v[130:131]
	s_add_i32 m0, s51, 0x2000
	s_nop 0
	global_load_lds_dwordx4 v[202:203], off
	v_lshl_add_u64 v[202:203], s[22:23], 0, v[134:135]
	s_mov_b32 m0, s56
	s_nop 0
	global_load_lds_dwordx4 v[202:203], off
	s_mov_b32 m0, s57
	s_nop 0
	global_load_lds_dwordx4 v[204:205], off
	s_waitcnt vmcnt(8)
	s_waitcnt lgkmcnt(0)
	s_barrier
; #define PG8_STAGE(bufoff, gbase, voff) do { _Pragma("unroll") for (int _i = 0; _i < 2; ++_i) \
;         __builtin_amdgcn_global_load_lds((const unsigned*)((const char*)(gbase) + (voff)[_i]), (PG8_LAS unsigned*)(lds + (bufoff) + ldsw + _i * 8192), 16, 0, 0); } while (0)
; #define PG8_LDA(dst, b, h) do { _Pragma("unroll") for (int m = 0; m < 4; ++m) _Pragma("unroll") for (int k = 0; k < 2; ++k) dst[m][k] = *(const PG8_LAS bf16x8*)(lds + PG8_SA(b, h) + aoff + m * 2048 + k * 1024); } while (0)
; #define PG8_LDB(dst, b, h) do { _Pragma("unroll") for (int n = 0; n < 2; ++n) _Pragma("unroll") for (int k = 0; k < 2; ++k) dst[n][k] = *(const PG8_LAS bf16x8*)(lds + PG8_SB(b, h) + boff + n * 2048 + k * 1024); } while (0)
; #define PG8_MMA(ai, bj, At, Bt) do { __builtin_amdgcn_s_setprio(1); _Pragma("unroll") for (int m = 0; m < 4; ++m) _Pragma("unroll") for (int n = 0; n < 2; ++n) _Pragma("unroll") for (int k = 0; k < 2; ++k) \
;         acc[ai][bj][m][n] = __builtin_amdgcn_mfma_f32_16x16x32_bf16(Bt[n][k], At[m][k], acc[ai][bj][m][n], 0, 0, 0); __builtin_amdgcn_s_setprio(0); } while (0)
; #define PG8_WAIT_V(n) asm volatile("s_waitcnt vmcnt(" #n ")" ::: "memory")
; #define PG8_WAIT_L(n) asm volatile("s_waitcnt lgkmcnt(" #n ")" ::: "memory")
; #define PG8_BAR __builtin_amdgcn_s_barrier()
; #define PG8_SCHED __builtin_amdgcn_sched_barrier(0)
; template <class Epi, class Sched, bool ALIGN_EPI = false, bool SP2 = false>
; __device__ __forceinline__ void gemm_phase(PG8_LAS unsigned char* lds, const Gemm g, const Sched& S, const Epi& E) {
;     ...
;             PG8_WAIT_V(8); PG8_WAIT_L(0); PG8_BAR; PG8_MMA(1, 0, At, B0); PG8_MMA(1, 1, At, B1); PG8_BAR; PG8_SCHED;
;             PG8_LDB(B0, 1, 0); PG8_LDB(B1, 1, 1); PG8_SCHED; PG8_LDA(At, 1, 0); PG8_STAGE(PG8_SA(0, 1), a2 + hstepA, voffA);
;             PG8_WAIT_V(8); PG8_WAIT_L(0); PG8_BAR; PG8_MMA(0, 0, At, B0); PG8_MMA(0, 1, At, B1); PG8_BAR; PG8_SCHED;
	s_setprio 1
	s_waitcnt lgkmcnt(0)
	v_mfma_f32_16x16x32_bf16 v[60:63], v[140:143], v[182:185], v[60:63]
	v_mfma_f32_16x16x32_bf16 v[60:63], v[144:147], v[188:191], v[60:63]
	v_mfma_f32_16x16x32_bf16 v[56:59], v[158:161], v[188:191], v[56:59]
	v_mfma_f32_16x16x32_bf16 v[56:59], v[154:157], v[182:185], v[56:59]
	v_mfma_f32_16x16x32_bf16 v[40:43], v[154:157], v[216:219], v[40:43]
	v_mfma_f32_16x16x32_bf16 v[40:43], v[158:161], v[220:223], v[40:43]
	v_mfma_f32_16x16x32_bf16 v[44:47], v[144:147], v[220:223], v[44:47]
	v_mfma_f32_16x16x32_bf16 v[44:47], v[140:143], v[216:219], v[44:47]
	v_mfma_f32_16x16x32_bf16 v[28:31], v[140:143], v[224:227], v[28:31]
	v_mfma_f32_16x16x32_bf16 v[28:31], v[144:147], v[228:231], v[28:31]
	v_mfma_f32_16x16x32_bf16 v[24:27], v[158:161], v[228:231], v[24:27]
	v_mfma_f32_16x16x32_bf16 v[24:27], v[154:157], v[224:227], v[24:27]
	s_setprio 0
	s_setprio 1
	v_mfma_f32_16x16x32_bf16 v[8:11], v[154:157], v[232:235], v[8:11]
	v_mfma_f32_16x16x32_bf16 v[8:11], v[158:161], v[236:239], v[8:11]
	v_mfma_f32_16x16x32_bf16 v[12:15], v[144:147], v[236:239], v[12:15]
	v_mfma_f32_16x16x32_bf16 v[12:15], v[140:143], v[232:235], v[12:15]
	v_mfma_f32_16x16x32_bf16 v[52:55], v[162:165], v[182:185], v[52:55]
	v_mfma_f32_16x16x32_bf16 v[52:55], v[166:169], v[188:191], v[52:55]
	v_mfma_f32_16x16x32_bf16 v[48:51], v[174:177], v[188:191], v[48:51]
	v_mfma_f32_16x16x32_bf16 v[48:51], v[170:173], v[182:185], v[48:51]
	v_mfma_f32_16x16x32_bf16 v[32:35], v[170:173], v[216:219], v[32:35]
	v_mfma_f32_16x16x32_bf16 v[32:35], v[174:177], v[220:223], v[32:35]
	v_mfma_f32_16x16x32_bf16 v[36:39], v[166:169], v[220:223], v[36:39]
	v_mfma_f32_16x16x32_bf16 v[36:39], v[162:165], v[216:219], v[36:39]
	v_mfma_f32_16x16x32_bf16 v[20:23], v[162:165], v[224:227], v[20:23]
	v_mfma_f32_16x16x32_bf16 v[20:23], v[166:169], v[228:231], v[20:23]
	v_mfma_f32_16x16x32_bf16 v[16:19], v[174:177], v[228:231], v[16:19]
	v_mfma_f32_16x16x32_bf16 v[16:19], v[170:173], v[224:227], v[16:19]
	v_mfma_f32_16x16x32_bf16 v[0:3], v[170:173], v[232:235], v[0:3]
	v_mfma_f32_16x16x32_bf16 v[0:3], v[174:177], v[236:239], v[0:3]
	v_mfma_f32_16x16x32_bf16 v[4:7], v[166:169], v[236:239], v[4:7]
	v_mfma_f32_16x16x32_bf16 v[4:7], v[162:165], v[232:235], v[4:7]
	s_setprio 0
	s_barrier
	s_add_i32 s51, 0, 0x18000
	s_add_i32 s53, 0, 0x1c000
	v_add_u32_e32 v158, s51, v152
	v_add_u32_e32 v174, s53, v152
	ds_read_b128 v[140:143], v158
	ds_read_b128 v[144:147], v158 offset:1024
	ds_read_b128 v[154:157], v158 offset:2048
	ds_read_b128 v[158:161], v158 offset:3072
	ds_read_b128 v[162:165], v174
	ds_read_b128 v[166:169], v174 offset:1024
	ds_read_b128 v[170:173], v174 offset:2048
	ds_read_b128 v[174:177], v174 offset:3072
	s_add_u32 s22, s22, 0x40000
	s_addc_u32 s23, s23, 0
	s_mov_b32 m0, s62
	v_lshl_add_u64 v[206:207], s[22:23], 0, v[134:135]
	ds_read_b128 v[182:185], v153 offset:32768
	ds_read_b128 v[188:191], v153 offset:33792
	ds_read_b128 v[216:219], v153 offset:34816
	ds_read_b128 v[220:223], v153 offset:35840
	ds_read_b128 v[224:227], v153 offset:36864
	ds_read_b128 v[228:231], v153 offset:37888
	ds_read_b128 v[232:235], v153 offset:38912
	ds_read_b128 v[236:239], v153 offset:39936
	global_load_lds_dwordx4 v[206:207], off
	v_lshl_add_u64 v[206:207], s[22:23], 0, v[132:133]
	s_mov_b32 m0, s63
	s_nop 0
	global_load_lds_dwordx4 v[206:207], off
	s_waitcnt vmcnt(8)
	s_waitcnt lgkmcnt(0)
	s_barrier
	s_setprio 1
	s_waitcnt lgkmcnt(0)
	v_mfma_f32_16x16x32_bf16 v[126:129], v[140:143], v[182:185], v[126:129]
	v_mfma_f32_16x16x32_bf16 v[126:129], v[144:147], v[188:191], v[126:129]
	v_mfma_f32_16x16x32_bf16 v[122:125], v[158:161], v[188:191], v[122:125]
	v_mfma_f32_16x16x32_bf16 v[122:125], v[154:157], v[182:185], v[122:125]
	v_mfma_f32_16x16x32_bf16 v[106:109], v[154:157], v[216:219], v[106:109]
	v_mfma_f32_16x16x32_bf16 v[106:109], v[158:161], v[220:223], v[106:109]
	v_mfma_f32_16x16x32_bf16 v[110:113], v[144:147], v[220:223], v[110:113]
	v_mfma_f32_16x16x32_bf16 v[110:113], v[140:143], v[216:219], v[110:113]
	v_mfma_f32_16x16x32_bf16 v[94:97], v[140:143], v[224:227], v[94:97]
	v_mfma_f32_16x16x32_bf16 v[94:97], v[144:147], v[228:231], v[94:97]
	v_mfma_f32_16x16x32_bf16 v[90:93], v[158:161], v[228:231], v[90:93]
	v_mfma_f32_16x16x32_bf16 v[90:93], v[154:157], v[224:227], v[90:93]
	s_setprio 0
	s_setprio 1
	v_mfma_f32_16x16x32_bf16 v[72:75], v[154:157], v[232:235], v[72:75]
	v_mfma_f32_16x16x32_bf16 v[72:75], v[158:161], v[236:239], v[72:75]
	v_mfma_f32_16x16x32_bf16 v[76:79], v[144:147], v[236:239], v[76:79]
	v_mfma_f32_16x16x32_bf16 v[76:79], v[140:143], v[232:235], v[76:79]
	v_mfma_f32_16x16x32_bf16 v[118:121], v[162:165], v[182:185], v[118:121]
	v_mfma_f32_16x16x32_bf16 v[118:121], v[166:169], v[188:191], v[118:121]
	v_mfma_f32_16x16x32_bf16 v[114:117], v[174:177], v[188:191], v[114:117]
	v_mfma_f32_16x16x32_bf16 v[114:117], v[170:173], v[182:185], v[114:117]
	v_mfma_f32_16x16x32_bf16 v[98:101], v[170:173], v[216:219], v[98:101]
	v_mfma_f32_16x16x32_bf16 v[98:101], v[174:177], v[220:223], v[98:101]
	v_mfma_f32_16x16x32_bf16 v[102:105], v[166:169], v[220:223], v[102:105]
	v_mfma_f32_16x16x32_bf16 v[102:105], v[162:165], v[216:219], v[102:105]
	v_mfma_f32_16x16x32_bf16 v[86:89], v[162:165], v[224:227], v[86:89]
	v_mfma_f32_16x16x32_bf16 v[86:89], v[166:169], v[228:231], v[86:89]
	v_mfma_f32_16x16x32_bf16 v[82:85], v[174:177], v[228:231], v[82:85]
	v_mfma_f32_16x16x32_bf16 v[82:85], v[170:173], v[224:227], v[82:85]
	v_mfma_f32_16x16x32_bf16 v[64:67], v[170:173], v[232:235], v[64:67]
	v_mfma_f32_16x16x32_bf16 v[64:67], v[174:177], v[236:239], v[64:67]
	v_mfma_f32_16x16x32_bf16 v[68:71], v[166:169], v[236:239], v[68:71]
	v_mfma_f32_16x16x32_bf16 v[68:71], v[162:165], v[232:235], v[68:71]
	s_setprio 0
	s_barrier
; #define PG8_STAGE(bufoff, gbase, voff) do { _Pragma("unroll") for (int _i = 0; _i < 2; ++_i) \
;         __builtin_amdgcn_global_load_lds((const unsigned*)((const char*)(gbase) + (voff)[_i]), (PG8_LAS unsigned*)(lds + (bufoff) + ldsw + _i * 8192), 16, 0, 0); } while (0)
; #define PG8_LDA(dst, b, h) do { _Pragma("unroll") for (int m = 0; m < 4; ++m) _Pragma("unroll") for (int k = 0; k < 2; ++k) dst[m][k] = *(const PG8_LAS bf16x8*)(lds + PG8_SA(b, h) + aoff + m * 2048 + k * 1024); } while (0)
; #define PG8_MMA(ai, bj, At, Bt) do { __builtin_amdgcn_s_setprio(1); _Pragma("unroll") for (int m = 0; m < 4; ++m) _Pragma("unroll") for (int n = 0; n < 2; ++n) _Pragma("unroll") for (int k = 0; k < 2; ++k) \
;         acc[ai][bj][m][n] = __builtin_amdgcn_mfma_f32_16x16x32_bf16(Bt[n][k], At[m][k], acc[ai][bj][m][n], 0, 0, 0); __builtin_amdgcn_s_setprio(0); } while (0)
; #define PG8_WAIT_V(n) asm volatile("s_waitcnt vmcnt(" #n ")" ::: "memory")
; #define PG8_WAIT_L(n) asm volatile("s_waitcnt lgkmcnt(" #n ")" ::: "memory")
; #define PG8_BAR __builtin_amdgcn_s_barrier()
; #define PG8_SCHED __builtin_amdgcn_sched_barrier(0)
; template <class Epi, class Sched, bool ALIGN_EPI = false, bool SP2 = false>
; __device__ __forceinline__ void gemm_phase(PG8_LAS unsigned char* lds, const Gemm g, const Sched& S, const Epi& E) {
;     ...
;         for (int t = 0; t < nt; t += 2) {
;     ...
;             PG8_LDA(At, 1, 1); PG8_STAGE(PG8_SB(1, 0), b3, voffB); PG8_STAGE(PG8_SB(1, 1), b3 + hstepB, voffB); PG8_STAGE(PG8_SA(1, 0), a3, voffA);
;             PG8_WAIT_V(8); PG8_WAIT_L(0); PG8_BAR; PG8_MMA(1, 0, At, B0); PG8_MMA(1, 1, At, B1); PG8_BAR; PG8_SCHED;
	s_add_i32 s22, s51, s55
	v_lshl_add_u64 v[148:149], v[148:149], 0, s[60:61]
	s_mov_b32 m0, s22
	ds_read_b128 v[182:185], v153 offset:49152
	ds_read_b128 v[188:191], v153 offset:50176
	ds_read_b128 v[216:219], v153 offset:51200
	ds_read_b128 v[220:223], v153 offset:52224
	ds_read_b128 v[224:227], v153 offset:53248
	ds_read_b128 v[228:231], v153 offset:54272
	ds_read_b128 v[232:235], v153 offset:55296
	ds_read_b128 v[236:239], v153 offset:56320
	global_load_lds_dwordx4 v[148:149], off
	s_add_i32 m0, s22, 0x2000
	s_add_u32 s20, s20, 0x40080
	v_lshl_add_u64 v[148:149], v[192:193], 0, s[60:61]
	s_addc_u32 s21, s21, 0
	s_add_i32 s22, s53, s55
	global_load_lds_dwordx4 v[148:149], off
	v_lshl_add_u64 v[148:149], s[20:21], 0, v[80:81]
	s_mov_b32 m0, s22
	s_nop 0
	global_load_lds_dwordx4 v[148:149], off
	v_lshl_add_u64 v[148:149], s[20:21], 0, v[130:131]
	s_add_i32 m0, s22, 0x2000
	s_nop 0
	global_load_lds_dwordx4 v[148:149], off
	v_lshl_add_u64 v[148:149], v[202:203], 0, s[60:61]
	s_mov_b32 m0, s66
	s_nop 0
	global_load_lds_dwordx4 v[148:149], off
	v_lshl_add_u64 v[148:149], v[204:205], 0, s[60:61]
	s_mov_b32 m0, s67
	s_nop 0
	global_load_lds_dwordx4 v[148:149], off
	s_waitcnt vmcnt(8)
	s_waitcnt lgkmcnt(0)
	s_barrier
	s_setprio 1
	s_waitcnt lgkmcnt(0)
	v_mfma_f32_16x16x32_bf16 v[60:63], v[140:143], v[182:185], v[60:63]
	v_mfma_f32_16x16x32_bf16 v[60:63], v[144:147], v[188:191], v[60:63]
	v_mfma_f32_16x16x32_bf16 v[56:59], v[158:161], v[188:191], v[56:59]
	v_mfma_f32_16x16x32_bf16 v[56:59], v[154:157], v[182:185], v[56:59]
	v_mfma_f32_16x16x32_bf16 v[40:43], v[154:157], v[216:219], v[40:43]
	v_mfma_f32_16x16x32_bf16 v[40:43], v[158:161], v[220:223], v[40:43]
	v_mfma_f32_16x16x32_bf16 v[44:47], v[144:147], v[220:223], v[44:47]
	v_mfma_f32_16x16x32_bf16 v[44:47], v[140:143], v[216:219], v[44:47]
	v_mfma_f32_16x16x32_bf16 v[28:31], v[140:143], v[224:227], v[28:31]
	v_mfma_f32_16x16x32_bf16 v[28:31], v[144:147], v[228:231], v[28:31]
	v_mfma_f32_16x16x32_bf16 v[24:27], v[158:161], v[228:231], v[24:27]
	v_mfma_f32_16x16x32_bf16 v[24:27], v[154:157], v[224:227], v[24:27]
	s_setprio 0
	s_setprio 1
	v_mfma_f32_16x16x32_bf16 v[8:11], v[154:157], v[232:235], v[8:11]
	v_mfma_f32_16x16x32_bf16 v[8:11], v[158:161], v[236:239], v[8:11]
	v_mfma_f32_16x16x32_bf16 v[12:15], v[144:147], v[236:239], v[12:15]
	v_mfma_f32_16x16x32_bf16 v[12:15], v[140:143], v[232:235], v[12:15]
	v_mfma_f32_16x16x32_bf16 v[52:55], v[162:165], v[182:185], v[52:55]
	v_mfma_f32_16x16x32_bf16 v[52:55], v[166:169], v[188:191], v[52:55]
	v_mfma_f32_16x16x32_bf16 v[48:51], v[174:177], v[188:191], v[48:51]
	v_mfma_f32_16x16x32_bf16 v[48:51], v[170:173], v[182:185], v[48:51]
	v_mfma_f32_16x16x32_bf16 v[32:35], v[170:173], v[216:219], v[32:35]
	v_mfma_f32_16x16x32_bf16 v[32:35], v[174:177], v[220:223], v[32:35]
	v_mfma_f32_16x16x32_bf16 v[36:39], v[166:169], v[220:223], v[36:39]
	v_mfma_f32_16x16x32_bf16 v[36:39], v[162:165], v[216:219], v[36:39]
	v_mfma_f32_16x16x32_bf16 v[20:23], v[162:165], v[224:227], v[20:23]
	v_mfma_f32_16x16x32_bf16 v[20:23], v[166:169], v[228:231], v[20:23]
	v_mfma_f32_16x16x32_bf16 v[16:19], v[174:177], v[228:231], v[16:19]
	v_mfma_f32_16x16x32_bf16 v[16:19], v[170:173], v[224:227], v[16:19]
	v_mfma_f32_16x16x32_bf16 v[0:3], v[170:173], v[232:235], v[0:3]
	v_mfma_f32_16x16x32_bf16 v[0:3], v[174:177], v[236:239], v[0:3]
	v_mfma_f32_16x16x32_bf16 v[4:7], v[166:169], v[236:239], v[4:7]
	v_mfma_f32_16x16x32_bf16 v[4:7], v[162:165], v[232:235], v[4:7]
	s_setprio 0
	s_barrier
	s_add_i32 s49, s49, 2
	s_add_u32 s0, s0, 0x100
	s_addc_u32 s1, s1, 0
	s_add_u32 s37, s37, 0x100
	s_addc_u32 s47, s47, 0
	s_cmp_gt_u32 s49, 13
	s_cbranch_scc0 .LBB0_952
	s_and_b64 vcc, exec, s[78:79]
	s_cbranch_vccz .LBB0_955
	s_barrier

; #define PG8_STAGE(bufoff, gbase, voff) do { _Pragma("unroll") for (int _i = 0; _i < 2; ++_i) \
;         __builtin_amdgcn_global_load_lds((const unsigned*)((const char*)(gbase) + (voff)[_i]), (PG8_LAS unsigned*)(lds + (bufoff) + ldsw + _i * 8192), 16, 0, 0); } while (0)
; #define PG8_LDA(dst, b, h) do { _Pragma("unroll") for (int m = 0; m < 4; ++m) _Pragma("unroll") for (int k = 0; k < 2; ++k) dst[m][k] = *(const PG8_LAS bf16x8*)(lds + PG8_SA(b, h) + aoff + m * 2048 + k * 1024); } while (0)
; #define PG8_LDB(dst, b, h) do { _Pragma("unroll") for (int n = 0; n < 2; ++n) _Pragma("unroll") for (int k = 0; k < 2; ++k) dst[n][k] = *(const PG8_LAS bf16x8*)(lds + PG8_SB(b, h) + boff + n * 2048 + k * 1024); } while (0)
; #define PG8_MMA(ai, bj, At, Bt) do { __builtin_amdgcn_s_setprio(1); _Pragma("unroll") for (int m = 0; m < 4; ++m) _Pragma("unroll") for (int n = 0; n < 2; ++n) _Pragma("unroll") for (int k = 0; k < 2; ++k) \
;         acc[ai][bj][m][n] = __builtin_amdgcn_mfma_f32_16x16x32_bf16(Bt[n][k], At[m][k], acc[ai][bj][m][n], 0, 0, 0); __builtin_amdgcn_s_setprio(0); } while (0)
; #define PG8_WAIT_V(n) asm volatile("s_waitcnt vmcnt(" #n ")" ::: "memory")
; #define PG8_WAIT_L(n) asm volatile("s_waitcnt lgkmcnt(" #n ")" ::: "memory")
; #define PG8_BAR __builtin_amdgcn_s_barrier()
; #define PG8_SCHED __builtin_amdgcn_sched_barrier(0)
; template <class Epi, class Sched, bool ALIGN_EPI = false, bool SP2 = false>
; __device__ __forceinline__ void gemm_phase(PG8_LAS unsigned char* lds, const Gemm g, const Sched& S, const Epi& E) {
;     ...
;             const bool last = (t == nt - 2);
;             const char* a1 = cA + (size_t)(t + 1) * kstep;
;             const char* a2 = last ? nA : cA + (size_t)(t + 2) * kstep; const char* b2 = last ? nB : cB + (size_t)(t + 2) * kstep;
;             const char* a3 = a2 + kstep; const char* b3 = b2 + kstep;
;             if (last && has_next) S.a_ready(nxt);
;             if constexpr (SP2) {
;             PG8_LDB(B0, 0, 0); PG8_LDB(B1, 0, 1); PG8_SCHED; PG8_LDA(At, 0, 0); PG8_STAGE(PG8_SA(1, 1), a1 + hstepA, voffA);
;             PG8_WAIT_V(8); PG8_WAIT_L(0); PG8_BAR; PG8_MMA(0, 0, At, B0); PG8_MMA(0, 1, At, B1); PG8_BAR; PG8_SCHED;
;             PG8_LDA(At, 0, 1); PG8_STAGE(PG8_SB(0, 0), b2, voffB); PG8_STAGE(PG8_SB(0, 1), b2 + hstepB, voffB); PG8_STAGE(PG8_SA(0, 0), a2, voffA);
.LBB0_1030:
	s_add_u32 s22, s20, s62
	s_addc_u32 s23, s21, s63
	s_add_u32 s22, s22, 0x100
	s_addc_u32 s23, s23, 0
	s_add_u32 s75, s72, s62
	s_addc_u32 s76, s73, s63
	s_add_i32 s77, 0, 0x10000
	s_cmpk_eq_i32 s62, 0xf00
	s_cselect_b32 s57, s47, s23
	s_cselect_b32 s56, s49, s22
	v_add_u32_e32 v80, s77, v150
	s_cselect_b32 s23, s45, s76
	s_cselect_b32 s22, s71, s75
	s_add_i32 s75, 0, 0x14000
	ds_read_b128 v[154:157], v80
	ds_read_b128 v[158:161], v80 offset:1024
	ds_read_b128 v[162:165], v80 offset:2048
	ds_read_b128 v[166:169], v80 offset:3072
	v_add_u32_e32 v80, s75, v150
	ds_read_b128 v[170:173], v80
	ds_read_b128 v[174:177], v80 offset:1024
	ds_read_b128 v[182:185], v80 offset:2048
	ds_read_b128 v[188:191], v80 offset:3072
	v_lshl_add_u64 v[82:83], v[144:145], 0, s[62:63]
	s_add_i32 m0, s33, 0xc000
	ds_read_b128 v[216:219], v152
	ds_read_b128 v[220:223], v152 offset:1024
	ds_read_b128 v[224:227], v152 offset:2048
	ds_read_b128 v[228:231], v152 offset:3072
	ds_read_b128 v[232:235], v152 offset:4096
	ds_read_b128 v[236:239], v152 offset:5120
	ds_read_b128 v[240:243], v152 offset:6144
	ds_read_b128 v[244:247], v152 offset:7168
	global_load_lds_dwordx4 v[82:83], off
	v_lshl_add_u64 v[82:83], v[146:147], 0, s[62:63]
	s_add_i32 m0, s33, 0xe000
	s_nop 0
	global_load_lds_dwordx4 v[82:83], off
	s_waitcnt vmcnt(8)
	s_waitcnt lgkmcnt(0)
	s_barrier
	s_setprio 1
	s_waitcnt lgkmcnt(0)
	v_mfma_f32_16x16x32_bf16 v[128:131], v[154:157], v[216:219], v[128:131]
	v_mfma_f32_16x16x32_bf16 v[128:131], v[158:161], v[220:223], v[128:131]
	v_mfma_f32_16x16x32_bf16 v[124:127], v[162:165], v[216:219], v[124:127]
	v_mfma_f32_16x16x32_bf16 v[124:127], v[166:169], v[220:223], v[124:127]
	v_mfma_f32_16x16x32_bf16 v[112:115], v[154:157], v[224:227], v[112:115]
	v_mfma_f32_16x16x32_bf16 v[112:115], v[158:161], v[228:231], v[112:115]
	v_mfma_f32_16x16x32_bf16 v[108:111], v[162:165], v[224:227], v[108:111]
	v_mfma_f32_16x16x32_bf16 v[108:111], v[166:169], v[228:231], v[108:111]
	v_mfma_f32_16x16x32_bf16 v[96:99], v[154:157], v[232:235], v[96:99]
	v_mfma_f32_16x16x32_bf16 v[96:99], v[158:161], v[236:239], v[96:99]
	v_mfma_f32_16x16x32_bf16 v[92:95], v[162:165], v[232:235], v[92:95]
	v_mfma_f32_16x16x32_bf16 v[92:95], v[166:169], v[236:239], v[92:95]
	s_setprio 0
	s_setprio 1
	v_mfma_f32_16x16x32_bf16 v[76:79], v[154:157], v[240:243], v[76:79]
	v_mfma_f32_16x16x32_bf16 v[76:79], v[158:161], v[244:247], v[76:79]
	v_mfma_f32_16x16x32_bf16 v[72:75], v[162:165], v[240:243], v[72:75]
	v_mfma_f32_16x16x32_bf16 v[72:75], v[166:169], v[244:247], v[72:75]
	v_mfma_f32_16x16x32_bf16 v[120:123], v[170:173], v[216:219], v[120:123]
	v_mfma_f32_16x16x32_bf16 v[120:123], v[174:177], v[220:223], v[120:123]
	v_mfma_f32_16x16x32_bf16 v[116:119], v[182:185], v[216:219], v[116:119]
	v_mfma_f32_16x16x32_bf16 v[116:119], v[188:191], v[220:223], v[116:119]
	v_mfma_f32_16x16x32_bf16 v[104:107], v[170:173], v[224:227], v[104:107]
	v_mfma_f32_16x16x32_bf16 v[104:107], v[174:177], v[228:231], v[104:107]
	v_mfma_f32_16x16x32_bf16 v[100:103], v[182:185], v[224:227], v[100:103]
	v_mfma_f32_16x16x32_bf16 v[100:103], v[188:191], v[228:231], v[100:103]
	v_mfma_f32_16x16x32_bf16 v[88:91], v[170:173], v[232:235], v[88:91]
	v_mfma_f32_16x16x32_bf16 v[88:91], v[174:177], v[236:239], v[88:91]
	v_mfma_f32_16x16x32_bf16 v[82:85], v[182:185], v[232:235], v[84:87]
	v_mfma_f32_16x16x32_bf16 v[82:85], v[188:191], v[236:239], v[82:85]
	v_mfma_f32_16x16x32_bf16 v[68:71], v[170:173], v[240:243], v[68:71]
	v_mfma_f32_16x16x32_bf16 v[68:71], v[174:177], v[244:247], v[68:71]
	v_mfma_f32_16x16x32_bf16 v[64:67], v[182:185], v[240:243], v[64:67]
	v_mfma_f32_16x16x32_bf16 v[64:67], v[188:191], v[244:247], v[64:67]
	s_setprio 0
	s_barrier
	s_add_i32 s76, s77, s31
	v_lshl_add_u64 v[192:193], s[22:23], 0, v[136:137]
	s_mov_b32 m0, s76
	ds_read_b128 v[216:219], v152 offset:16384
	ds_read_b128 v[220:223], v152 offset:17408
	ds_read_b128 v[224:227], v152 offset:18432
	ds_read_b128 v[228:231], v152 offset:19456
	ds_read_b128 v[232:235], v152 offset:20480
	ds_read_b128 v[236:239], v152 offset:21504
	ds_read_b128 v[240:243], v152 offset:22528
	ds_read_b128 v[244:247], v152 offset:23552
	global_load_lds_dwordx4 v[192:193], off
	s_add_i32 m0, s76, 0x2000
	s_add_u32 s76, s22, 0x80000
	v_lshl_add_u64 v[202:203], s[22:23], 0, v[132:133]
	s_addc_u32 s77, s23, 0
	s_add_i32 s75, s75, s31
	global_load_lds_dwordx4 v[202:203], off
	v_lshl_add_u64 v[86:87], s[76:77], 0, v[136:137]
	s_mov_b32 m0, s75
	v_lshl_add_u64 v[204:205], s[56:57], 0, v[138:139]
	global_load_lds_dwordx4 v[86:87], off
	v_lshl_add_u64 v[86:87], s[76:77], 0, v[132:133]
	s_add_i32 m0, s75, 0x2000
	v_lshl_add_u64 v[206:207], s[56:57], 0, v[134:135]
	global_load_lds_dwordx4 v[86:87], off
	s_mov_b32 m0, s33
	s_nop 0
	global_load_lds_dwordx4 v[204:205], off
	s_mov_b32 m0, s35
	s_nop 0
	global_load_lds_dwordx4 v[206:207], off
	s_waitcnt vmcnt(8)
	s_waitcnt lgkmcnt(0)
	s_barrier
; #define PG8_STAGE(bufoff, gbase, voff) do { _Pragma("unroll") for (int _i = 0; _i < 2; ++_i) \
;         __builtin_amdgcn_global_load_lds((const unsigned*)((const char*)(gbase) + (voff)[_i]), (PG8_LAS unsigned*)(lds + (bufoff) + ldsw + _i * 8192), 16, 0, 0); } while (0)
; #define PG8_LDA(dst, b, h) do { _Pragma("unroll") for (int m = 0; m < 4; ++m) _Pragma("unroll") for (int k = 0; k < 2; ++k) dst[m][k] = *(const PG8_LAS bf16x8*)(lds + PG8_SA(b, h) + aoff + m * 2048 + k * 1024); } while (0)
; #define PG8_LDB(dst, b, h) do { _Pragma("unroll") for (int n = 0; n < 2; ++n) _Pragma("unroll") for (int k = 0; k < 2; ++k) dst[n][k] = *(const PG8_LAS bf16x8*)(lds + PG8_SB(b, h) + boff + n * 2048 + k * 1024); } while (0)
; #define PG8_MMA(ai, bj, At, Bt) do { __builtin_amdgcn_s_setprio(1); _Pragma("unroll") for (int m = 0; m < 4; ++m) _Pragma("unroll") for (int n = 0; n < 2; ++n) _Pragma("unroll") for (int k = 0; k < 2; ++k) \
;         acc[ai][bj][m][n] = __builtin_amdgcn_mfma_f32_16x16x32_bf16(Bt[n][k], At[m][k], acc[ai][bj][m][n], 0, 0, 0); __builtin_amdgcn_s_setprio(0); } while (0)
; #define PG8_WAIT_V(n) asm volatile("s_waitcnt vmcnt(" #n ")" ::: "memory")
; #define PG8_WAIT_L(n) asm volatile("s_waitcnt lgkmcnt(" #n ")" ::: "memory")
; #define PG8_BAR __builtin_amdgcn_s_barrier()
; #define PG8_SCHED __builtin_amdgcn_sched_barrier(0)
; template <class Epi, class Sched, bool ALIGN_EPI = false, bool SP2 = false>
; __device__ __forceinline__ void gemm_phase(PG8_LAS unsigned char* lds, const Gemm g, const Sched& S, const Epi& E) {
;     ...
;             PG8_WAIT_V(8); PG8_WAIT_L(0); PG8_BAR; PG8_MMA(1, 0, At, B0); PG8_MMA(1, 1, At, B1); PG8_BAR; PG8_SCHED;
;             PG8_LDB(B0, 1, 0); PG8_LDB(B1, 1, 1); PG8_SCHED; PG8_LDA(At, 1, 0); PG8_STAGE(PG8_SA(0, 1), a2 + hstepA, voffA);
;             PG8_WAIT_V(8); PG8_WAIT_L(0); PG8_BAR; PG8_MMA(0, 0, At, B0); PG8_MMA(0, 1, At, B1); PG8_BAR; PG8_SCHED;
	s_setprio 1
	s_waitcnt lgkmcnt(0)
	v_mfma_f32_16x16x32_bf16 v[60:63], v[154:157], v[216:219], v[60:63]
	v_mfma_f32_16x16x32_bf16 v[60:63], v[158:161], v[220:223], v[60:63]
	v_mfma_f32_16x16x32_bf16 v[56:59], v[162:165], v[216:219], v[56:59]
	v_mfma_f32_16x16x32_bf16 v[56:59], v[166:169], v[220:223], v[56:59]
	v_mfma_f32_16x16x32_bf16 v[44:47], v[154:157], v[224:227], v[44:47]
	v_mfma_f32_16x16x32_bf16 v[44:47], v[158:161], v[228:231], v[44:47]
	v_mfma_f32_16x16x32_bf16 v[40:43], v[162:165], v[224:227], v[40:43]
	v_mfma_f32_16x16x32_bf16 v[40:43], v[166:169], v[228:231], v[40:43]
	v_mfma_f32_16x16x32_bf16 v[28:31], v[154:157], v[232:235], v[28:31]
	v_mfma_f32_16x16x32_bf16 v[28:31], v[158:161], v[236:239], v[28:31]
	v_mfma_f32_16x16x32_bf16 v[24:27], v[162:165], v[232:235], v[24:27]
	v_mfma_f32_16x16x32_bf16 v[24:27], v[166:169], v[236:239], v[24:27]
	s_setprio 0
	s_setprio 1
	v_mfma_f32_16x16x32_bf16 v[12:15], v[154:157], v[240:243], v[12:15]
	v_mfma_f32_16x16x32_bf16 v[12:15], v[158:161], v[244:247], v[12:15]
	v_mfma_f32_16x16x32_bf16 v[8:11], v[162:165], v[240:243], v[8:11]
	v_mfma_f32_16x16x32_bf16 v[8:11], v[166:169], v[244:247], v[8:11]
	v_mfma_f32_16x16x32_bf16 v[52:55], v[170:173], v[216:219], v[52:55]
	v_mfma_f32_16x16x32_bf16 v[52:55], v[174:177], v[220:223], v[52:55]
	v_mfma_f32_16x16x32_bf16 v[48:51], v[182:185], v[216:219], v[48:51]
	v_mfma_f32_16x16x32_bf16 v[48:51], v[188:191], v[220:223], v[48:51]
	v_mfma_f32_16x16x32_bf16 v[36:39], v[170:173], v[224:227], v[36:39]
	v_mfma_f32_16x16x32_bf16 v[36:39], v[174:177], v[228:231], v[36:39]
	v_mfma_f32_16x16x32_bf16 v[32:35], v[182:185], v[224:227], v[32:35]
	v_mfma_f32_16x16x32_bf16 v[32:35], v[188:191], v[228:231], v[32:35]
	v_mfma_f32_16x16x32_bf16 v[20:23], v[170:173], v[232:235], v[20:23]
	v_mfma_f32_16x16x32_bf16 v[20:23], v[174:177], v[236:239], v[20:23]
	v_mfma_f32_16x16x32_bf16 v[16:19], v[182:185], v[232:235], v[16:19]
	v_mfma_f32_16x16x32_bf16 v[16:19], v[188:191], v[236:239], v[16:19]
	v_mfma_f32_16x16x32_bf16 v[4:7], v[170:173], v[240:243], v[4:7]
	v_mfma_f32_16x16x32_bf16 v[4:7], v[174:177], v[244:247], v[4:7]
	v_mfma_f32_16x16x32_bf16 v[0:3], v[182:185], v[240:243], v[0:3]
	v_mfma_f32_16x16x32_bf16 v[0:3], v[188:191], v[244:247], v[0:3]
	s_setprio 0
	s_barrier
	s_add_i32 s75, 0, 0x18000
	v_add_u32_e32 v80, s75, v150
	s_add_i32 s76, 0, 0x1c000
	ds_read_b128 v[154:157], v80
	ds_read_b128 v[158:161], v80 offset:1024
	ds_read_b128 v[162:165], v80 offset:2048
	ds_read_b128 v[166:169], v80 offset:3072
	v_add_u32_e32 v80, s76, v150
	ds_read_b128 v[170:173], v80
	ds_read_b128 v[174:177], v80 offset:1024
	ds_read_b128 v[182:185], v80 offset:2048
	ds_read_b128 v[188:191], v80 offset:3072
	s_add_u32 s56, s56, 0x80000
	s_addc_u32 s57, s57, 0
	s_mov_b32 m0, s36
	v_lshl_add_u64 v[86:87], s[56:57], 0, v[138:139]
	ds_read_b128 v[216:219], v152 offset:32768
	ds_read_b128 v[220:223], v152 offset:33792
	ds_read_b128 v[224:227], v152 offset:34816
	ds_read_b128 v[228:231], v152 offset:35840
	ds_read_b128 v[232:235], v152 offset:36864
	ds_read_b128 v[236:239], v152 offset:37888
	ds_read_b128 v[240:243], v152 offset:38912
	ds_read_b128 v[244:247], v152 offset:39936
	global_load_lds_dwordx4 v[86:87], off
	v_lshl_add_u64 v[86:87], s[56:57], 0, v[134:135]
	s_mov_b32 m0, s37
	s_nop 0
	global_load_lds_dwordx4 v[86:87], off
	s_waitcnt vmcnt(8)
	s_waitcnt lgkmcnt(0)
	s_barrier
	s_setprio 1
	s_waitcnt lgkmcnt(0)
	v_mfma_f32_16x16x32_bf16 v[128:131], v[154:157], v[216:219], v[128:131]
	v_mfma_f32_16x16x32_bf16 v[128:131], v[158:161], v[220:223], v[128:131]
	v_mfma_f32_16x16x32_bf16 v[124:127], v[162:165], v[216:219], v[124:127]
	v_mfma_f32_16x16x32_bf16 v[124:127], v[166:169], v[220:223], v[124:127]
	v_mfma_f32_16x16x32_bf16 v[112:115], v[154:157], v[224:227], v[112:115]
	v_mfma_f32_16x16x32_bf16 v[112:115], v[158:161], v[228:231], v[112:115]
	v_mfma_f32_16x16x32_bf16 v[108:111], v[162:165], v[224:227], v[108:111]
	v_mfma_f32_16x16x32_bf16 v[108:111], v[166:169], v[228:231], v[108:111]
	v_mfma_f32_16x16x32_bf16 v[96:99], v[154:157], v[232:235], v[96:99]
	v_mfma_f32_16x16x32_bf16 v[96:99], v[158:161], v[236:239], v[96:99]
	v_mfma_f32_16x16x32_bf16 v[92:95], v[162:165], v[232:235], v[92:95]
	v_mfma_f32_16x16x32_bf16 v[92:95], v[166:169], v[236:239], v[92:95]
	s_setprio 0
	s_setprio 1
	v_mfma_f32_16x16x32_bf16 v[76:79], v[154:157], v[240:243], v[76:79]
	v_mfma_f32_16x16x32_bf16 v[76:79], v[158:161], v[244:247], v[76:79]
	v_mfma_f32_16x16x32_bf16 v[72:75], v[162:165], v[240:243], v[72:75]
	v_mfma_f32_16x16x32_bf16 v[72:75], v[166:169], v[244:247], v[72:75]
	v_mfma_f32_16x16x32_bf16 v[120:123], v[170:173], v[216:219], v[120:123]
	v_mfma_f32_16x16x32_bf16 v[120:123], v[174:177], v[220:223], v[120:123]
	v_mfma_f32_16x16x32_bf16 v[116:119], v[182:185], v[216:219], v[116:119]
	v_mfma_f32_16x16x32_bf16 v[116:119], v[188:191], v[220:223], v[116:119]
	v_mfma_f32_16x16x32_bf16 v[104:107], v[170:173], v[224:227], v[104:107]
	v_mfma_f32_16x16x32_bf16 v[104:107], v[174:177], v[228:231], v[104:107]
	v_mfma_f32_16x16x32_bf16 v[100:103], v[182:185], v[224:227], v[100:103]
	v_mfma_f32_16x16x32_bf16 v[100:103], v[188:191], v[228:231], v[100:103]
	v_mfma_f32_16x16x32_bf16 v[86:89], v[170:173], v[232:235], v[88:91]
	v_mfma_f32_16x16x32_bf16 v[88:91], v[174:177], v[236:239], v[86:89]
	v_mfma_f32_16x16x32_bf16 v[82:85], v[182:185], v[232:235], v[82:85]
	v_mfma_f32_16x16x32_bf16 v[84:87], v[188:191], v[236:239], v[82:85]
	v_mfma_f32_16x16x32_bf16 v[68:71], v[170:173], v[240:243], v[68:71]
	v_mfma_f32_16x16x32_bf16 v[68:71], v[174:177], v[244:247], v[68:71]
	v_mfma_f32_16x16x32_bf16 v[64:67], v[182:185], v[240:243], v[64:67]
	v_mfma_f32_16x16x32_bf16 v[64:67], v[188:191], v[244:247], v[64:67]
	s_setprio 0
	s_barrier
; #define PG8_STAGE(bufoff, gbase, voff) do { _Pragma("unroll") for (int _i = 0; _i < 2; ++_i) \
;         __builtin_amdgcn_global_load_lds((const unsigned*)((const char*)(gbase) + (voff)[_i]), (PG8_LAS unsigned*)(lds + (bufoff) + ldsw + _i * 8192), 16, 0, 0); } while (0)
; #define PG8_LDA(dst, b, h) do { _Pragma("unroll") for (int m = 0; m < 4; ++m) _Pragma("unroll") for (int k = 0; k < 2; ++k) dst[m][k] = *(const PG8_LAS bf16x8*)(lds + PG8_SA(b, h) + aoff + m * 2048 + k * 1024); } while (0)
; #define PG8_MMA(ai, bj, At, Bt) do { __builtin_amdgcn_s_setprio(1); _Pragma("unroll") for (int m = 0; m < 4; ++m) _Pragma("unroll") for (int n = 0; n < 2; ++n) _Pragma("unroll") for (int k = 0; k < 2; ++k) \
;         acc[ai][bj][m][n] = __builtin_amdgcn_mfma_f32_16x16x32_bf16(Bt[n][k], At[m][k], acc[ai][bj][m][n], 0, 0, 0); __builtin_amdgcn_s_setprio(0); } while (0)
; #define PG8_WAIT_V(n) asm volatile("s_waitcnt vmcnt(" #n ")" ::: "memory")
; #define PG8_WAIT_L(n) asm volatile("s_waitcnt lgkmcnt(" #n ")" ::: "memory")
; #define PG8_BAR __builtin_amdgcn_s_barrier()
; #define PG8_SCHED __builtin_amdgcn_sched_barrier(0)
; template <class Epi, class Sched, bool ALIGN_EPI = false, bool SP2 = false>
; __device__ __forceinline__ void gemm_phase(PG8_LAS unsigned char* lds, const Gemm g, const Sched& S, const Epi& E) {
;     ...
;         for (int t = 0; t < nt; t += 2) {
;     ...
;             PG8_LDA(At, 1, 1); PG8_STAGE(PG8_SB(1, 0), b3, voffB); PG8_STAGE(PG8_SB(1, 1), b3 + hstepB, voffB); PG8_STAGE(PG8_SA(1, 0), a3, voffA);
;             PG8_WAIT_V(8); PG8_WAIT_L(0); PG8_BAR; PG8_MMA(1, 0, At, B0); PG8_MMA(1, 1, At, B1); PG8_BAR; PG8_SCHED;
	s_add_i32 s56, s75, s31
	v_lshl_add_u64 v[82:83], v[192:193], 0, s[60:61]
	s_mov_b32 m0, s56
	ds_read_b128 v[216:219], v152 offset:49152
	ds_read_b128 v[220:223], v152 offset:50176
	ds_read_b128 v[224:227], v152 offset:51200
	ds_read_b128 v[228:231], v152 offset:52224
	ds_read_b128 v[232:235], v152 offset:53248
	ds_read_b128 v[236:239], v152 offset:54272
	ds_read_b128 v[240:243], v152 offset:55296
	ds_read_b128 v[244:247], v152 offset:56320
	global_load_lds_dwordx4 v[82:83], off
	s_add_i32 m0, s56, 0x2000
	s_add_u32 s22, s22, 0x80080
	v_lshl_add_u64 v[82:83], v[202:203], 0, s[60:61]
	s_addc_u32 s23, s23, 0
	s_add_i32 s56, s76, s31
	global_load_lds_dwordx4 v[82:83], off
	v_lshl_add_u64 v[82:83], s[22:23], 0, v[136:137]
	s_mov_b32 m0, s56
	s_nop 0
	global_load_lds_dwordx4 v[82:83], off
	v_lshl_add_u64 v[82:83], s[22:23], 0, v[132:133]
	s_add_i32 m0, s56, 0x2000
	s_nop 0
	global_load_lds_dwordx4 v[82:83], off
	v_lshl_add_u64 v[82:83], v[204:205], 0, s[60:61]
	s_mov_b32 m0, s64
	s_nop 0
	global_load_lds_dwordx4 v[82:83], off
	v_lshl_add_u64 v[82:83], v[206:207], 0, s[60:61]
	s_mov_b32 m0, s65
	s_nop 0
	global_load_lds_dwordx4 v[82:83], off
	s_waitcnt vmcnt(8)
	s_waitcnt lgkmcnt(0)
	s_barrier
	s_setprio 1
	s_waitcnt lgkmcnt(0)
	v_mfma_f32_16x16x32_bf16 v[60:63], v[154:157], v[216:219], v[60:63]
	v_mfma_f32_16x16x32_bf16 v[60:63], v[158:161], v[220:223], v[60:63]
	v_mfma_f32_16x16x32_bf16 v[56:59], v[162:165], v[216:219], v[56:59]
	v_mfma_f32_16x16x32_bf16 v[56:59], v[166:169], v[220:223], v[56:59]
	v_mfma_f32_16x16x32_bf16 v[44:47], v[154:157], v[224:227], v[44:47]
	v_mfma_f32_16x16x32_bf16 v[44:47], v[158:161], v[228:231], v[44:47]
	v_mfma_f32_16x16x32_bf16 v[40:43], v[162:165], v[224:227], v[40:43]
	v_mfma_f32_16x16x32_bf16 v[40:43], v[166:169], v[228:231], v[40:43]
	v_mfma_f32_16x16x32_bf16 v[28:31], v[154:157], v[232:235], v[28:31]
	v_mfma_f32_16x16x32_bf16 v[28:31], v[158:161], v[236:239], v[28:31]
	v_mfma_f32_16x16x32_bf16 v[24:27], v[162:165], v[232:235], v[24:27]
	v_mfma_f32_16x16x32_bf16 v[24:27], v[166:169], v[236:239], v[24:27]
	s_setprio 0
	s_setprio 1
	v_mfma_f32_16x16x32_bf16 v[12:15], v[154:157], v[240:243], v[12:15]
	v_mfma_f32_16x16x32_bf16 v[12:15], v[158:161], v[244:247], v[12:15]
	v_mfma_f32_16x16x32_bf16 v[8:11], v[162:165], v[240:243], v[8:11]
	v_mfma_f32_16x16x32_bf16 v[8:11], v[166:169], v[244:247], v[8:11]
	v_mfma_f32_16x16x32_bf16 v[52:55], v[170:173], v[216:219], v[52:55]
	v_mfma_f32_16x16x32_bf16 v[52:55], v[174:177], v[220:223], v[52:55]
	v_mfma_f32_16x16x32_bf16 v[48:51], v[182:185], v[216:219], v[48:51]
	v_mfma_f32_16x16x32_bf16 v[48:51], v[188:191], v[220:223], v[48:51]
	v_mfma_f32_16x16x32_bf16 v[36:39], v[170:173], v[224:227], v[36:39]
	v_mfma_f32_16x16x32_bf16 v[36:39], v[174:177], v[228:231], v[36:39]
	v_mfma_f32_16x16x32_bf16 v[32:35], v[182:185], v[224:227], v[32:35]
	v_mfma_f32_16x16x32_bf16 v[32:35], v[188:191], v[228:231], v[32:35]
	v_mfma_f32_16x16x32_bf16 v[20:23], v[170:173], v[232:235], v[20:23]
	v_mfma_f32_16x16x32_bf16 v[20:23], v[174:177], v[236:239], v[20:23]
	v_mfma_f32_16x16x32_bf16 v[16:19], v[182:185], v[232:235], v[16:19]
	v_mfma_f32_16x16x32_bf16 v[16:19], v[188:191], v[236:239], v[16:19]
	v_mfma_f32_16x16x32_bf16 v[4:7], v[170:173], v[240:243], v[4:7]
	v_mfma_f32_16x16x32_bf16 v[4:7], v[174:177], v[244:247], v[4:7]
	v_mfma_f32_16x16x32_bf16 v[0:3], v[182:185], v[240:243], v[0:3]
	v_mfma_f32_16x16x32_bf16 v[0:3], v[188:191], v[244:247], v[0:3]
	s_setprio 0
	s_barrier
	s_add_i32 s74, s74, 2
	s_add_u32 s62, s62, 0x100
	s_addc_u32 s63, s63, 0
	s_cmp_gt_u32 s74, 29
	s_cbranch_scc1 .LBB0_1033

; #define PG8_STAGE(bufoff, gbase, voff) do { _Pragma("unroll") for (int _i = 0; _i < 2; ++_i) \
;         __builtin_amdgcn_global_load_lds((const unsigned*)((const char*)(gbase) + (voff)[_i]), (PG8_LAS unsigned*)(lds + (bufoff) + ldsw + _i * 8192), 16, 0, 0); } while (0)
; #define PG8_LDA(dst, b, h) do { _Pragma("unroll") for (int m = 0; m < 4; ++m) _Pragma("unroll") for (int k = 0; k < 2; ++k) dst[m][k] = *(const PG8_LAS bf16x8*)(lds + PG8_SA(b, h) + aoff + m * 2048 + k * 1024); } while (0)
; #define PG8_LDB(dst, b, h) do { _Pragma("unroll") for (int n = 0; n < 2; ++n) _Pragma("unroll") for (int k = 0; k < 2; ++k) dst[n][k] = *(const PG8_LAS bf16x8*)(lds + PG8_SB(b, h) + boff + n * 2048 + k * 1024); } while (0)
; #define PG8_MMA(ai, bj, At, Bt) do { __builtin_amdgcn_s_setprio(1); _Pragma("unroll") for (int m = 0; m < 4; ++m) _Pragma("unroll") for (int n = 0; n < 2; ++n) _Pragma("unroll") for (int k = 0; k < 2; ++k) \
;         acc[ai][bj][m][n] = __builtin_amdgcn_mfma_f32_16x16x32_bf16(Bt[n][k], At[m][k], acc[ai][bj][m][n], 0, 0, 0); __builtin_amdgcn_s_setprio(0); } while (0)
; #define PG8_WAIT_V(n) asm volatile("s_waitcnt vmcnt(" #n ")" ::: "memory")
; #define PG8_WAIT_L(n) asm volatile("s_waitcnt lgkmcnt(" #n ")" ::: "memory")
; #define PG8_BAR __builtin_amdgcn_s_barrier()
; template <class Epi, class Sched, bool ALIGN_EPI = false, bool SP2 = false>
; __device__ __forceinline__ void gemm_phase(PG8_LAS unsigned char* lds, const Gemm g, const Sched& S, const Epi& E) {
;     ...
;             const char* a1 = cA + (size_t)(t + 1) * kstep;
;             const char* a2 = last ? nA : cA + (size_t)(t + 2) * kstep; const char* b2 = last ? nB : cB + (size_t)(t + 2) * kstep;
;             const char* a3 = a2 + kstep; const char* b3 = b2 + kstep;
;             if (last && has_next) S.a_ready(nxt);
;             if constexpr (SP2) {
;             PG8_LDB(B0, 0, 0); PG8_LDB(B1, 0, 1); PG8_SCHED; PG8_LDA(At, 0, 0); PG8_STAGE(PG8_SA(1, 1), a1 + hstepA, voffA);
;             PG8_WAIT_V(8); PG8_WAIT_L(0); PG8_BAR; PG8_MMA(0, 0, At, B0); PG8_MMA(0, 1, At, B1); PG8_BAR; PG8_SCHED;
;             PG8_LDA(At, 0, 1); PG8_STAGE(PG8_SB(0, 0), b2, voffB); PG8_STAGE(PG8_SB(0, 1), b2 + hstepB, voffB); PG8_STAGE(PG8_SA(0, 0), a2, voffA);
;             PG8_WAIT_V(8); PG8_WAIT_L(0); PG8_BAR; PG8_MMA(1, 0, At, B0); PG8_MMA(1, 1, At, B1); PG8_BAR; PG8_SCHED;
.LBB0_1088:
	s_add_u32 s43, s52, s22
	s_addc_u32 s45, s53, 0
	s_add_u32 s23, s43, 0x100
	s_addc_u32 s66, s45, 0
	s_and_b64 s[56:57], s[64:65], exec
	s_cselect_b32 s57, s47, s66
	s_cselect_b32 s56, s46, s23
	s_add_u32 s22, s20, s22
	s_addc_u32 s23, s21, 0
	s_add_u32 s66, s22, 0x100
	s_addc_u32 s67, s23, 0
	s_add_i32 s84, 0, 0x10000
	s_and_b64 s[22:23], s[64:65], exec
	s_cselect_b32 s67, s49, s67
	s_cselect_b32 s66, s48, s66
	s_add_i32 s65, 0, 0x14000
	s_add_u32 s70, s43, 0x80080
	s_addc_u32 s71, s45, 0
	s_add_i32 s83, s84, s31
	s_add_i32 m0, s33, 0xc000
	s_add_i32 s86, s33, 0xe000
	s_add_i32 s80, s83, 0x2000
	s_add_u32 s68, s66, 0x80000
	v_add_u32_e32 v152, s84, v138
	v_add_u32_e32 v168, s65, v138
	s_addc_u32 s69, s67, 0
	s_add_i32 s82, s65, s31
	ds_read_b128 v[140:143], v152
	ds_read_b128 v[144:147], v152 offset:1024
	ds_read_b128 v[148:151], v152 offset:2048
	ds_read_b128 v[152:155], v152 offset:3072
	ds_read_b128 v[156:159], v168
	ds_read_b128 v[160:163], v168 offset:1024
	ds_read_b128 v[164:167], v168 offset:2048
	ds_read_b128 v[168:171], v168 offset:3072
	s_add_i32 s81, s82, 0x2000
	s_add_i32 s79, 0, 0x18000
	s_add_i32 s78, 0, 0x1c000
	s_add_u32 s22, s56, 0x80000
	s_addc_u32 s23, s57, 0
	s_add_i32 s45, s79, s31
	s_add_i32 s43, s45, 0x2000
	s_add_u32 s64, s66, 0x80080
	s_addc_u32 s65, s67, 0
	s_add_i32 s85, s78, s31
	s_add_i32 s84, s85, 0x2000
	v_lshl_add_u64 v[176:177], s[70:71], 0, v[134:135]
	ds_read_b128 v[172:175], v139
	ds_read_b128 v[182:185], v139 offset:1024
	ds_read_b128 v[188:191], v139 offset:2048
	ds_read_b128 v[216:219], v139 offset:3072
	ds_read_b128 v[220:223], v139 offset:4096
	ds_read_b128 v[224:227], v139 offset:5120
	ds_read_b128 v[228:231], v139 offset:6144
	ds_read_b128 v[232:235], v139 offset:7168
	global_load_lds_dwordx4 v[176:177], off
	v_lshl_add_u64 v[176:177], s[70:71], 0, v[132:133]
	s_mov_b32 m0, s86
	s_nop 0
	global_load_lds_dwordx4 v[176:177], off
	s_waitcnt vmcnt(8)
	s_waitcnt lgkmcnt(0)
	s_barrier
	s_setprio 1
	s_waitcnt lgkmcnt(0)
	v_mfma_f32_16x16x32_bf16 v[126:129], v[140:143], v[172:175], v[126:129]
	v_mfma_f32_16x16x32_bf16 v[126:129], v[144:147], v[182:185], v[126:129]
	v_mfma_f32_16x16x32_bf16 v[122:125], v[152:155], v[182:185], v[122:125]
	v_mfma_f32_16x16x32_bf16 v[122:125], v[148:151], v[172:175], v[122:125]
	v_mfma_f32_16x16x32_bf16 v[114:117], v[148:151], v[188:191], v[114:117]
	v_mfma_f32_16x16x32_bf16 v[114:117], v[152:155], v[216:219], v[114:117]
	v_mfma_f32_16x16x32_bf16 v[118:121], v[144:147], v[216:219], v[118:121]
	v_mfma_f32_16x16x32_bf16 v[118:121], v[140:143], v[188:191], v[118:121]
	v_mfma_f32_16x16x32_bf16 v[106:109], v[140:143], v[220:223], v[106:109]
	v_mfma_f32_16x16x32_bf16 v[106:109], v[144:147], v[224:227], v[106:109]
	v_mfma_f32_16x16x32_bf16 v[98:101], v[152:155], v[224:227], v[98:101]
	v_mfma_f32_16x16x32_bf16 v[98:101], v[148:151], v[220:223], v[98:101]
	s_setprio 0
	s_setprio 1
	v_mfma_f32_16x16x32_bf16 v[82:85], v[148:151], v[228:231], v[82:85]
	v_mfma_f32_16x16x32_bf16 v[82:85], v[152:155], v[232:235], v[82:85]
	v_mfma_f32_16x16x32_bf16 v[90:93], v[144:147], v[232:235], v[90:93]
	v_mfma_f32_16x16x32_bf16 v[90:93], v[140:143], v[228:231], v[90:93]
	v_mfma_f32_16x16x32_bf16 v[110:113], v[156:159], v[172:175], v[110:113]
	v_mfma_f32_16x16x32_bf16 v[110:113], v[160:163], v[182:185], v[110:113]
	v_mfma_f32_16x16x32_bf16 v[102:105], v[168:171], v[182:185], v[102:105]
	v_mfma_f32_16x16x32_bf16 v[102:105], v[164:167], v[172:175], v[102:105]
	v_mfma_f32_16x16x32_bf16 v[86:89], v[164:167], v[188:191], v[86:89]
	v_mfma_f32_16x16x32_bf16 v[86:89], v[168:171], v[216:219], v[86:89]
	v_mfma_f32_16x16x32_bf16 v[94:97], v[160:163], v[216:219], v[94:97]
	v_mfma_f32_16x16x32_bf16 v[94:97], v[156:159], v[188:191], v[94:97]
	v_mfma_f32_16x16x32_bf16 v[76:79], v[156:159], v[220:223], v[76:79]
	v_mfma_f32_16x16x32_bf16 v[76:79], v[160:163], v[224:227], v[76:79]
	v_mfma_f32_16x16x32_bf16 v[72:75], v[168:171], v[224:227], v[72:75]
	v_mfma_f32_16x16x32_bf16 v[72:75], v[164:167], v[220:223], v[72:75]
	v_mfma_f32_16x16x32_bf16 v[64:67], v[164:167], v[228:231], v[64:67]
	v_mfma_f32_16x16x32_bf16 v[64:67], v[168:171], v[232:235], v[64:67]
	v_mfma_f32_16x16x32_bf16 v[68:71], v[160:163], v[232:235], v[68:71]
	v_mfma_f32_16x16x32_bf16 v[68:71], v[156:159], v[228:231], v[68:71]
	s_setprio 0
	s_barrier
	s_mov_b32 m0, s83
	v_lshl_add_u64 v[176:177], s[66:67], 0, v[80:81]
	ds_read_b128 v[172:175], v139 offset:16384
	ds_read_b128 v[182:185], v139 offset:17408
	ds_read_b128 v[188:191], v139 offset:18432
	ds_read_b128 v[216:219], v139 offset:19456
	ds_read_b128 v[220:223], v139 offset:20480
	ds_read_b128 v[224:227], v139 offset:21504
	ds_read_b128 v[228:231], v139 offset:22528
	ds_read_b128 v[232:235], v139 offset:23552
	global_load_lds_dwordx4 v[176:177], off
	v_lshl_add_u64 v[192:193], s[66:67], 0, v[130:131]
	s_mov_b32 m0, s80
	v_lshl_add_u64 v[202:203], s[68:69], 0, v[80:81]
	global_load_lds_dwordx4 v[192:193], off
	s_mov_b32 m0, s82
	v_lshl_add_u64 v[204:205], s[56:57], 0, v[132:133]
	global_load_lds_dwordx4 v[202:203], off
	v_lshl_add_u64 v[202:203], s[68:69], 0, v[130:131]
	s_mov_b32 m0, s81
	s_nop 0
	global_load_lds_dwordx4 v[202:203], off
	v_lshl_add_u64 v[202:203], s[56:57], 0, v[134:135]
	s_mov_b32 m0, s33
	s_nop 0
	global_load_lds_dwordx4 v[202:203], off
	s_mov_b32 m0, s35
	s_nop 0
	global_load_lds_dwordx4 v[204:205], off
	s_waitcnt vmcnt(8)
	s_waitcnt lgkmcnt(0)
	s_barrier
; #define PG8_STAGE(bufoff, gbase, voff) do { _Pragma("unroll") for (int _i = 0; _i < 2; ++_i) \
;         __builtin_amdgcn_global_load_lds((const unsigned*)((const char*)(gbase) + (voff)[_i]), (PG8_LAS unsigned*)(lds + (bufoff) + ldsw + _i * 8192), 16, 0, 0); } while (0)
; #define PG8_LDA(dst, b, h) do { _Pragma("unroll") for (int m = 0; m < 4; ++m) _Pragma("unroll") for (int k = 0; k < 2; ++k) dst[m][k] = *(const PG8_LAS bf16x8*)(lds + PG8_SA(b, h) + aoff + m * 2048 + k * 1024); } while (0)
; #define PG8_LDB(dst, b, h) do { _Pragma("unroll") for (int n = 0; n < 2; ++n) _Pragma("unroll") for (int k = 0; k < 2; ++k) dst[n][k] = *(const PG8_LAS bf16x8*)(lds + PG8_SB(b, h) + boff + n * 2048 + k * 1024); } while (0)
; #define PG8_MMA(ai, bj, At, Bt) do { __builtin_amdgcn_s_setprio(1); _Pragma("unroll") for (int m = 0; m < 4; ++m) _Pragma("unroll") for (int n = 0; n < 2; ++n) _Pragma("unroll") for (int k = 0; k < 2; ++k) \
;         acc[ai][bj][m][n] = __builtin_amdgcn_mfma_f32_16x16x32_bf16(Bt[n][k], At[m][k], acc[ai][bj][m][n], 0, 0, 0); __builtin_amdgcn_s_setprio(0); } while (0)
; #define PG8_WAIT_V(n) asm volatile("s_waitcnt vmcnt(" #n ")" ::: "memory")
; #define PG8_WAIT_L(n) asm volatile("s_waitcnt lgkmcnt(" #n ")" ::: "memory")
; #define PG8_BAR __builtin_amdgcn_s_barrier()
; #define PG8_SCHED __builtin_amdgcn_sched_barrier(0)
; template <class Epi, class Sched, bool ALIGN_EPI = false, bool SP2 = false>
; __device__ __forceinline__ void gemm_phase(PG8_LAS unsigned char* lds, const Gemm g, const Sched& S, const Epi& E) {
;     ...
;             PG8_WAIT_V(8); PG8_WAIT_L(0); PG8_BAR; PG8_MMA(1, 0, At, B0); PG8_MMA(1, 1, At, B1); PG8_BAR; PG8_SCHED;
;             PG8_LDB(B0, 1, 0); PG8_LDB(B1, 1, 1); PG8_SCHED; PG8_LDA(At, 1, 0); PG8_STAGE(PG8_SA(0, 1), a2 + hstepA, voffA);
;             PG8_WAIT_V(8); PG8_WAIT_L(0); PG8_BAR; PG8_MMA(0, 0, At, B0); PG8_MMA(0, 1, At, B1); PG8_BAR; PG8_SCHED;
	s_setprio 1
	s_waitcnt lgkmcnt(0)
	v_mfma_f32_16x16x32_bf16 v[60:63], v[140:143], v[172:175], v[60:63]
	v_mfma_f32_16x16x32_bf16 v[60:63], v[144:147], v[182:185], v[60:63]
	v_mfma_f32_16x16x32_bf16 v[56:59], v[152:155], v[182:185], v[56:59]
	v_mfma_f32_16x16x32_bf16 v[56:59], v[148:151], v[172:175], v[56:59]
	v_mfma_f32_16x16x32_bf16 v[48:51], v[148:151], v[188:191], v[48:51]
	v_mfma_f32_16x16x32_bf16 v[48:51], v[152:155], v[216:219], v[48:51]
	v_mfma_f32_16x16x32_bf16 v[52:55], v[144:147], v[216:219], v[52:55]
	v_mfma_f32_16x16x32_bf16 v[52:55], v[140:143], v[188:191], v[52:55]
	v_mfma_f32_16x16x32_bf16 v[36:39], v[140:143], v[220:223], v[36:39]
	v_mfma_f32_16x16x32_bf16 v[36:39], v[144:147], v[224:227], v[36:39]
	v_mfma_f32_16x16x32_bf16 v[32:35], v[152:155], v[224:227], v[32:35]
	v_mfma_f32_16x16x32_bf16 v[32:35], v[148:151], v[220:223], v[32:35]
	s_setprio 0
	s_setprio 1
	v_mfma_f32_16x16x32_bf16 v[16:19], v[148:151], v[228:231], v[16:19]
	v_mfma_f32_16x16x32_bf16 v[16:19], v[152:155], v[232:235], v[16:19]
	v_mfma_f32_16x16x32_bf16 v[20:23], v[144:147], v[232:235], v[20:23]
	v_mfma_f32_16x16x32_bf16 v[20:23], v[140:143], v[228:231], v[20:23]
	v_mfma_f32_16x16x32_bf16 v[44:47], v[156:159], v[172:175], v[44:47]
	v_mfma_f32_16x16x32_bf16 v[44:47], v[160:163], v[182:185], v[44:47]
	v_mfma_f32_16x16x32_bf16 v[40:43], v[168:171], v[182:185], v[40:43]
	v_mfma_f32_16x16x32_bf16 v[40:43], v[164:167], v[172:175], v[40:43]
	v_mfma_f32_16x16x32_bf16 v[24:27], v[164:167], v[188:191], v[24:27]
	v_mfma_f32_16x16x32_bf16 v[24:27], v[168:171], v[216:219], v[24:27]
	v_mfma_f32_16x16x32_bf16 v[28:31], v[160:163], v[216:219], v[28:31]
	v_mfma_f32_16x16x32_bf16 v[28:31], v[156:159], v[188:191], v[28:31]
	v_mfma_f32_16x16x32_bf16 v[12:15], v[156:159], v[220:223], v[12:15]
	v_mfma_f32_16x16x32_bf16 v[12:15], v[160:163], v[224:227], v[12:15]
	v_mfma_f32_16x16x32_bf16 v[8:11], v[168:171], v[224:227], v[8:11]
	v_mfma_f32_16x16x32_bf16 v[8:11], v[164:167], v[220:223], v[8:11]
	v_mfma_f32_16x16x32_bf16 v[0:3], v[164:167], v[228:231], v[0:3]
	v_mfma_f32_16x16x32_bf16 v[0:3], v[168:171], v[232:235], v[0:3]
	v_mfma_f32_16x16x32_bf16 v[4:7], v[160:163], v[232:235], v[4:7]
	v_mfma_f32_16x16x32_bf16 v[4:7], v[156:159], v[228:231], v[4:7]
	s_setprio 0
	s_barrier
	v_add_u32_e32 v152, s79, v138
	v_add_u32_e32 v168, s78, v138
	ds_read_b128 v[140:143], v152
	ds_read_b128 v[144:147], v152 offset:1024
	ds_read_b128 v[148:151], v152 offset:2048
	ds_read_b128 v[152:155], v152 offset:3072
	ds_read_b128 v[156:159], v168
	ds_read_b128 v[160:163], v168 offset:1024
	ds_read_b128 v[164:167], v168 offset:2048
	ds_read_b128 v[168:171], v168 offset:3072
	s_mov_b32 m0, s36
	v_lshl_add_u64 v[206:207], s[22:23], 0, v[134:135]
	ds_read_b128 v[172:175], v139 offset:32768
	ds_read_b128 v[182:185], v139 offset:33792
	ds_read_b128 v[188:191], v139 offset:34816
	ds_read_b128 v[216:219], v139 offset:35840
	ds_read_b128 v[220:223], v139 offset:36864
	ds_read_b128 v[224:227], v139 offset:37888
	ds_read_b128 v[228:231], v139 offset:38912
	ds_read_b128 v[232:235], v139 offset:39936
	global_load_lds_dwordx4 v[206:207], off
	v_lshl_add_u64 v[206:207], s[22:23], 0, v[132:133]
	s_mov_b32 m0, s37
	s_nop 0
	global_load_lds_dwordx4 v[206:207], off
	s_waitcnt vmcnt(8)
	s_waitcnt lgkmcnt(0)
	s_barrier
	s_setprio 1
	s_waitcnt lgkmcnt(0)
	v_mfma_f32_16x16x32_bf16 v[126:129], v[140:143], v[172:175], v[126:129]
	v_mfma_f32_16x16x32_bf16 v[126:129], v[144:147], v[182:185], v[126:129]
	v_mfma_f32_16x16x32_bf16 v[122:125], v[152:155], v[182:185], v[122:125]
	v_mfma_f32_16x16x32_bf16 v[122:125], v[148:151], v[172:175], v[122:125]
	v_mfma_f32_16x16x32_bf16 v[114:117], v[148:151], v[188:191], v[114:117]
	v_mfma_f32_16x16x32_bf16 v[114:117], v[152:155], v[216:219], v[114:117]
	v_mfma_f32_16x16x32_bf16 v[118:121], v[144:147], v[216:219], v[118:121]
	v_mfma_f32_16x16x32_bf16 v[118:121], v[140:143], v[188:191], v[118:121]
	v_mfma_f32_16x16x32_bf16 v[106:109], v[140:143], v[220:223], v[106:109]
	v_mfma_f32_16x16x32_bf16 v[106:109], v[144:147], v[224:227], v[106:109]
	v_mfma_f32_16x16x32_bf16 v[98:101], v[152:155], v[224:227], v[98:101]
	v_mfma_f32_16x16x32_bf16 v[98:101], v[148:151], v[220:223], v[98:101]
	s_setprio 0
	s_setprio 1
	v_mfma_f32_16x16x32_bf16 v[82:85], v[148:151], v[228:231], v[82:85]
	v_mfma_f32_16x16x32_bf16 v[82:85], v[152:155], v[232:235], v[82:85]
	v_mfma_f32_16x16x32_bf16 v[90:93], v[144:147], v[232:235], v[90:93]
	v_mfma_f32_16x16x32_bf16 v[90:93], v[140:143], v[228:231], v[90:93]
	v_mfma_f32_16x16x32_bf16 v[110:113], v[156:159], v[172:175], v[110:113]
	v_mfma_f32_16x16x32_bf16 v[110:113], v[160:163], v[182:185], v[110:113]
	v_mfma_f32_16x16x32_bf16 v[102:105], v[168:171], v[182:185], v[102:105]
	v_mfma_f32_16x16x32_bf16 v[102:105], v[164:167], v[172:175], v[102:105]
	v_mfma_f32_16x16x32_bf16 v[86:89], v[164:167], v[188:191], v[86:89]
	v_mfma_f32_16x16x32_bf16 v[86:89], v[168:171], v[216:219], v[86:89]
	v_mfma_f32_16x16x32_bf16 v[94:97], v[160:163], v[216:219], v[94:97]
	v_mfma_f32_16x16x32_bf16 v[94:97], v[156:159], v[188:191], v[94:97]
	v_mfma_f32_16x16x32_bf16 v[76:79], v[156:159], v[220:223], v[76:79]
	v_mfma_f32_16x16x32_bf16 v[76:79], v[160:163], v[224:227], v[76:79]
	v_mfma_f32_16x16x32_bf16 v[72:75], v[168:171], v[224:227], v[72:75]
	v_mfma_f32_16x16x32_bf16 v[72:75], v[164:167], v[220:223], v[72:75]
	v_mfma_f32_16x16x32_bf16 v[64:67], v[164:167], v[228:231], v[64:67]
	v_mfma_f32_16x16x32_bf16 v[64:67], v[168:171], v[232:235], v[64:67]
	v_mfma_f32_16x16x32_bf16 v[68:71], v[160:163], v[232:235], v[68:71]
	v_mfma_f32_16x16x32_bf16 v[68:71], v[156:159], v[228:231], v[68:71]
	s_setprio 0
	s_barrier
; #define PG8_STAGE(bufoff, gbase, voff) do { _Pragma("unroll") for (int _i = 0; _i < 2; ++_i) \
;         __builtin_amdgcn_global_load_lds((const unsigned*)((const char*)(gbase) + (voff)[_i]), (PG8_LAS unsigned*)(lds + (bufoff) + ldsw + _i * 8192), 16, 0, 0); } while (0)
; #define PG8_LDA(dst, b, h) do { _Pragma("unroll") for (int m = 0; m < 4; ++m) _Pragma("unroll") for (int k = 0; k < 2; ++k) dst[m][k] = *(const PG8_LAS bf16x8*)(lds + PG8_SA(b, h) + aoff + m * 2048 + k * 1024); } while (0)
; #define PG8_MMA(ai, bj, At, Bt) do { __builtin_amdgcn_s_setprio(1); _Pragma("unroll") for (int m = 0; m < 4; ++m) _Pragma("unroll") for (int n = 0; n < 2; ++n) _Pragma("unroll") for (int k = 0; k < 2; ++k) \
;         acc[ai][bj][m][n] = __builtin_amdgcn_mfma_f32_16x16x32_bf16(Bt[n][k], At[m][k], acc[ai][bj][m][n], 0, 0, 0); __builtin_amdgcn_s_setprio(0); } while (0)
; #define PG8_WAIT_V(n) asm volatile("s_waitcnt vmcnt(" #n ")" ::: "memory")
; #define PG8_WAIT_L(n) asm volatile("s_waitcnt lgkmcnt(" #n ")" ::: "memory")
; #define PG8_BAR __builtin_amdgcn_s_barrier()
; #define PG8_SCHED __builtin_amdgcn_sched_barrier(0)
; template <class Epi, class Sched, bool ALIGN_EPI = false, bool SP2 = false>
; __device__ __forceinline__ void gemm_phase(PG8_LAS unsigned char* lds, const Gemm g, const Sched& S, const Epi& E) {
;     ...
;             PG8_LDA(At, 1, 1); PG8_STAGE(PG8_SB(1, 0), b3, voffB); PG8_STAGE(PG8_SB(1, 1), b3 + hstepB, voffB); PG8_STAGE(PG8_SA(1, 0), a3, voffA);
;             PG8_WAIT_V(8); PG8_WAIT_L(0); PG8_BAR; PG8_MMA(1, 0, At, B0); PG8_MMA(1, 1, At, B1); PG8_BAR; PG8_SCHED;
	s_mov_b32 m0, s45
	v_lshl_add_u64 v[176:177], v[176:177], 0, s[60:61]
	ds_read_b128 v[172:175], v139 offset:49152
	ds_read_b128 v[182:185], v139 offset:50176
	ds_read_b128 v[188:191], v139 offset:51200
	ds_read_b128 v[216:219], v139 offset:52224
	ds_read_b128 v[220:223], v139 offset:53248
	ds_read_b128 v[224:227], v139 offset:54272
	ds_read_b128 v[228:231], v139 offset:55296
	ds_read_b128 v[232:235], v139 offset:56320
	global_load_lds_dwordx4 v[176:177], off
	v_lshl_add_u64 v[176:177], v[192:193], 0, s[60:61]
	s_mov_b32 m0, s43
	s_nop 0
	global_load_lds_dwordx4 v[176:177], off
	v_lshl_add_u64 v[176:177], s[64:65], 0, v[80:81]
	s_mov_b32 m0, s85
	s_nop 0
	global_load_lds_dwordx4 v[176:177], off
	v_lshl_add_u64 v[176:177], s[64:65], 0, v[130:131]
	s_mov_b32 m0, s84
	s_nop 0
	global_load_lds_dwordx4 v[176:177], off
	v_lshl_add_u64 v[176:177], v[202:203], 0, s[60:61]
	s_mov_b32 m0, s55
	s_nop 0
	global_load_lds_dwordx4 v[176:177], off
	v_lshl_add_u64 v[176:177], v[204:205], 0, s[60:61]
	s_mov_b32 m0, s72
	s_nop 0
	global_load_lds_dwordx4 v[176:177], off
	s_waitcnt vmcnt(8)
	s_waitcnt lgkmcnt(0)
	s_barrier
	s_setprio 1
	s_waitcnt lgkmcnt(0)
	v_mfma_f32_16x16x32_bf16 v[60:63], v[140:143], v[172:175], v[60:63]
	v_mfma_f32_16x16x32_bf16 v[60:63], v[144:147], v[182:185], v[60:63]
	v_mfma_f32_16x16x32_bf16 v[56:59], v[152:155], v[182:185], v[56:59]
	v_mfma_f32_16x16x32_bf16 v[56:59], v[148:151], v[172:175], v[56:59]
	v_mfma_f32_16x16x32_bf16 v[48:51], v[148:151], v[188:191], v[48:51]
	v_mfma_f32_16x16x32_bf16 v[48:51], v[152:155], v[216:219], v[48:51]
	v_mfma_f32_16x16x32_bf16 v[52:55], v[144:147], v[216:219], v[52:55]
	v_mfma_f32_16x16x32_bf16 v[52:55], v[140:143], v[188:191], v[52:55]
	v_mfma_f32_16x16x32_bf16 v[36:39], v[140:143], v[220:223], v[36:39]
	v_mfma_f32_16x16x32_bf16 v[36:39], v[144:147], v[224:227], v[36:39]
	v_mfma_f32_16x16x32_bf16 v[32:35], v[152:155], v[224:227], v[32:35]
	v_mfma_f32_16x16x32_bf16 v[32:35], v[148:151], v[220:223], v[32:35]
	s_setprio 0
	s_setprio 1
	v_mfma_f32_16x16x32_bf16 v[16:19], v[148:151], v[228:231], v[16:19]
	v_mfma_f32_16x16x32_bf16 v[16:19], v[152:155], v[232:235], v[16:19]
	v_mfma_f32_16x16x32_bf16 v[20:23], v[144:147], v[232:235], v[20:23]
	v_mfma_f32_16x16x32_bf16 v[20:23], v[140:143], v[228:231], v[20:23]
	v_mfma_f32_16x16x32_bf16 v[44:47], v[156:159], v[172:175], v[44:47]
	v_mfma_f32_16x16x32_bf16 v[44:47], v[160:163], v[182:185], v[44:47]
	v_mfma_f32_16x16x32_bf16 v[40:43], v[168:171], v[182:185], v[40:43]
	v_mfma_f32_16x16x32_bf16 v[40:43], v[164:167], v[172:175], v[40:43]
	v_mfma_f32_16x16x32_bf16 v[24:27], v[164:167], v[188:191], v[24:27]
	v_mfma_f32_16x16x32_bf16 v[24:27], v[168:171], v[216:219], v[24:27]
	v_mfma_f32_16x16x32_bf16 v[28:31], v[160:163], v[216:219], v[28:31]
	v_mfma_f32_16x16x32_bf16 v[28:31], v[156:159], v[188:191], v[28:31]
	v_mfma_f32_16x16x32_bf16 v[12:15], v[156:159], v[220:223], v[12:15]
	v_mfma_f32_16x16x32_bf16 v[12:15], v[160:163], v[224:227], v[12:15]
	v_mfma_f32_16x16x32_bf16 v[8:11], v[168:171], v[224:227], v[8:11]
	v_mfma_f32_16x16x32_bf16 v[8:11], v[164:167], v[220:223], v[8:11]
	v_mfma_f32_16x16x32_bf16 v[0:3], v[164:167], v[228:231], v[0:3]
	v_mfma_f32_16x16x32_bf16 v[0:3], v[168:171], v[232:235], v[0:3]
	v_mfma_f32_16x16x32_bf16 v[4:7], v[160:163], v[232:235], v[4:7]
	v_mfma_f32_16x16x32_bf16 v[4:7], v[156:159], v[228:231], v[4:7]
	s_setprio 0
	s_barrier
	s_movk_i32 s22, 0x100
	s_andn2_b64 vcc, exec, s[62:63]
	s_mov_b64 s[64:65], -1
	s_mov_b64 s[62:63], 0
	s_cbranch_vccz .LBB0_1088
	s_and_b64 vcc, exec, s[40:41]
	s_cbranch_vccz .LBB0_1091
	s_barrier

; #define PG8_STAGE(bufoff, gbase, voff) do { _Pragma("unroll") for (int _i = 0; _i < 2; ++_i) \
;         __builtin_amdgcn_global_load_lds((const unsigned*)((const char*)(gbase) + (voff)[_i]), (PG8_LAS unsigned*)(lds + (bufoff) + ldsw + _i * 8192), 16, 0, 0); } while (0)
; #define PG8_LDA(dst, b, h) do { _Pragma("unroll") for (int m = 0; m < 4; ++m) _Pragma("unroll") for (int k = 0; k < 2; ++k) dst[m][k] = *(const PG8_LAS bf16x8*)(lds + PG8_SA(b, h) + aoff + m * 2048 + k * 1024); } while (0)
; #define PG8_LDB(dst, b, h) do { _Pragma("unroll") for (int n = 0; n < 2; ++n) _Pragma("unroll") for (int k = 0; k < 2; ++k) dst[n][k] = *(const PG8_LAS bf16x8*)(lds + PG8_SB(b, h) + boff + n * 2048 + k * 1024); } while (0)
; #define PG8_MMA(ai, bj, At, Bt) do { __builtin_amdgcn_s_setprio(1); _Pragma("unroll") for (int m = 0; m < 4; ++m) _Pragma("unroll") for (int n = 0; n < 2; ++n) _Pragma("unroll") for (int k = 0; k < 2; ++k) \
;         acc[ai][bj][m][n] = __builtin_amdgcn_mfma_f32_16x16x32_bf16(Bt[n][k], At[m][k], acc[ai][bj][m][n], 0, 0, 0); __builtin_amdgcn_s_setprio(0); } while (0)
; #define PG8_WAIT_V(n) asm volatile("s_waitcnt vmcnt(" #n ")" ::: "memory")
; #define PG8_WAIT_L(n) asm volatile("s_waitcnt lgkmcnt(" #n ")" ::: "memory")
; #define PG8_BAR __builtin_amdgcn_s_barrier()
; template <class Epi, class Sched, bool ALIGN_EPI = false, bool SP2 = false>
; __device__ __forceinline__ void gemm_phase(PG8_LAS unsigned char* lds, const Gemm g, const Sched& S, const Epi& E) {
;     ...
;             const char* a1 = cA + (size_t)(t + 1) * kstep;
;             const char* a2 = last ? nA : cA + (size_t)(t + 2) * kstep; const char* b2 = last ? nB : cB + (size_t)(t + 2) * kstep;
;             const char* a3 = a2 + kstep; const char* b3 = b2 + kstep;
;             if (last && has_next) S.a_ready(nxt);
;             if constexpr (SP2) {
;             PG8_LDB(B0, 0, 0); PG8_LDB(B1, 0, 1); PG8_SCHED; PG8_LDA(At, 0, 0); PG8_STAGE(PG8_SA(1, 1), a1 + hstepA, voffA);
;             PG8_WAIT_V(8); PG8_WAIT_L(0); PG8_BAR; PG8_MMA(0, 0, At, B0); PG8_MMA(0, 1, At, B1); PG8_BAR; PG8_SCHED;
;             PG8_LDA(At, 0, 1); PG8_STAGE(PG8_SB(0, 0), b2, voffB); PG8_STAGE(PG8_SB(0, 1), b2 + hstepB, voffB); PG8_STAGE(PG8_SA(0, 0), a2, voffA);
;             PG8_WAIT_V(8); PG8_WAIT_L(0); PG8_BAR; PG8_MMA(1, 0, At, B0); PG8_MMA(1, 1, At, B1); PG8_BAR; PG8_SCHED;
.LBB0_1183:
	s_add_u32 s68, vcc_lo, 0xfff80080
	s_addc_u32 s69, vcc_hi, -1
	s_add_i32 s82, 0, 0x10000
	s_cmp_eq_u32 s81, 28
	s_cselect_b32 s71, s41, s69
	s_cselect_b32 s70, s67, s68
	v_add_u32_e32 v146, s82, v151
	s_cselect_b32 s69, s65, s80
	s_cselect_b32 s68, s78, s79
	s_add_i32 s84, 0, 0x14000
	ds_read_b128 v[142:145], v146
	ds_read_b128 v[156:159], v146 offset:1024
	ds_read_b128 v[160:163], v146 offset:2048
	ds_read_b128 v[164:167], v146 offset:3072
	v_add_u32_e32 v146, s84, v151
	ds_read_b128 v[168:171], v146
	ds_read_b128 v[172:175], v146 offset:1024
	ds_read_b128 v[182:185], v146 offset:2048
	ds_read_b128 v[188:191], v146 offset:3072
	v_lshl_add_u64 v[176:177], vcc, 0, v[138:139]
	s_add_i32 m0, s45, 0xc000
	ds_read_b128 v[216:219], v154
	ds_read_b128 v[220:223], v154 offset:1024
	ds_read_b128 v[224:227], v154 offset:2048
	ds_read_b128 v[228:231], v154 offset:3072
	ds_read_b128 v[232:235], v154 offset:4096
	ds_read_b128 v[236:239], v154 offset:5120
	ds_read_b128 v[240:243], v154 offset:6144
	ds_read_b128 v[244:247], v154 offset:7168
	global_load_lds_dwordx4 v[176:177], off
	v_lshl_add_u64 v[176:177], vcc, 0, v[140:141]
	s_add_i32 m0, s45, 0xe000
	s_nop 0
	global_load_lds_dwordx4 v[176:177], off
	s_waitcnt vmcnt(8)
	s_waitcnt lgkmcnt(0)
	s_barrier
	s_setprio 1
	s_waitcnt lgkmcnt(0)
	v_mfma_f32_16x16x32_bf16 v[126:129], v[142:145], v[216:219], v[126:129]
	v_mfma_f32_16x16x32_bf16 v[126:129], v[156:159], v[220:223], v[126:129]
	v_mfma_f32_16x16x32_bf16 v[122:125], v[164:167], v[220:223], v[122:125]
	v_mfma_f32_16x16x32_bf16 v[122:125], v[160:163], v[216:219], v[122:125]
	v_mfma_f32_16x16x32_bf16 v[106:109], v[160:163], v[224:227], v[106:109]
	v_mfma_f32_16x16x32_bf16 v[106:109], v[164:167], v[228:231], v[106:109]
	v_mfma_f32_16x16x32_bf16 v[110:113], v[156:159], v[228:231], v[110:113]
	v_mfma_f32_16x16x32_bf16 v[110:113], v[142:145], v[224:227], v[110:113]
	v_mfma_f32_16x16x32_bf16 v[94:97], v[142:145], v[232:235], v[94:97]
	v_mfma_f32_16x16x32_bf16 v[94:97], v[156:159], v[236:239], v[94:97]
	v_mfma_f32_16x16x32_bf16 v[90:93], v[164:167], v[236:239], v[90:93]
	v_mfma_f32_16x16x32_bf16 v[90:93], v[160:163], v[232:235], v[90:93]
	s_setprio 0
	s_setprio 1
	v_mfma_f32_16x16x32_bf16 v[72:75], v[160:163], v[240:243], v[72:75]
	v_mfma_f32_16x16x32_bf16 v[72:75], v[164:167], v[244:247], v[72:75]
	v_mfma_f32_16x16x32_bf16 v[76:79], v[156:159], v[244:247], v[76:79]
	v_mfma_f32_16x16x32_bf16 v[76:79], v[142:145], v[240:243], v[76:79]
	v_mfma_f32_16x16x32_bf16 v[118:121], v[168:171], v[216:219], v[118:121]
	v_mfma_f32_16x16x32_bf16 v[118:121], v[172:175], v[220:223], v[118:121]
	v_mfma_f32_16x16x32_bf16 v[114:117], v[188:191], v[220:223], v[114:117]
	v_mfma_f32_16x16x32_bf16 v[114:117], v[182:185], v[216:219], v[114:117]
	v_mfma_f32_16x16x32_bf16 v[98:101], v[182:185], v[224:227], v[98:101]
	v_mfma_f32_16x16x32_bf16 v[98:101], v[188:191], v[228:231], v[98:101]
	v_mfma_f32_16x16x32_bf16 v[102:105], v[172:175], v[228:231], v[102:105]
	v_mfma_f32_16x16x32_bf16 v[102:105], v[168:171], v[224:227], v[102:105]
	v_mfma_f32_16x16x32_bf16 v[86:89], v[168:171], v[232:235], v[86:89]
	v_mfma_f32_16x16x32_bf16 v[86:89], v[172:175], v[236:239], v[86:89]
	v_mfma_f32_16x16x32_bf16 v[82:85], v[188:191], v[236:239], v[82:85]
	v_mfma_f32_16x16x32_bf16 v[82:85], v[182:185], v[232:235], v[82:85]
	v_mfma_f32_16x16x32_bf16 v[64:67], v[182:185], v[240:243], v[64:67]
	v_mfma_f32_16x16x32_bf16 v[64:67], v[188:191], v[244:247], v[64:67]
	v_mfma_f32_16x16x32_bf16 v[68:71], v[172:175], v[244:247], v[68:71]
	v_mfma_f32_16x16x32_bf16 v[68:71], v[168:171], v[240:243], v[68:71]
	s_setprio 0
	s_barrier
	s_add_i32 s82, s82, s33
	v_lshl_add_u64 v[176:177], s[68:69], 0, v[132:133]
	s_mov_b32 m0, s82
	ds_read_b128 v[216:219], v154 offset:16384
	ds_read_b128 v[220:223], v154 offset:17408
	ds_read_b128 v[224:227], v154 offset:18432
	ds_read_b128 v[228:231], v154 offset:19456
	ds_read_b128 v[232:235], v154 offset:20480
	ds_read_b128 v[236:239], v154 offset:21504
	ds_read_b128 v[240:243], v154 offset:22528
	ds_read_b128 v[244:247], v154 offset:23552
	global_load_lds_dwordx4 v[176:177], off
	s_add_i32 m0, s82, 0x2000
	s_add_u32 s82, s68, 0x80000
	v_lshl_add_u64 v[192:193], s[68:69], 0, v[136:137]
	s_addc_u32 s83, s69, 0
	s_add_i32 s84, s84, s33
	global_load_lds_dwordx4 v[192:193], off
	v_lshl_add_u64 v[202:203], s[82:83], 0, v[132:133]
	s_mov_b32 m0, s84
	v_lshl_add_u64 v[204:205], s[70:71], 0, v[134:135]
	global_load_lds_dwordx4 v[202:203], off
	v_lshl_add_u64 v[202:203], s[82:83], 0, v[136:137]
	s_add_i32 m0, s84, 0x2000
	s_nop 0
	global_load_lds_dwordx4 v[202:203], off
	v_lshl_add_u64 v[202:203], s[70:71], 0, v[130:131]
	s_mov_b32 m0, s45
	s_nop 0
	global_load_lds_dwordx4 v[202:203], off
	s_mov_b32 m0, s49
	s_nop 0
	global_load_lds_dwordx4 v[204:205], off
	s_waitcnt vmcnt(8)
	s_waitcnt lgkmcnt(0)
	s_barrier
; #define PG8_STAGE(bufoff, gbase, voff) do { _Pragma("unroll") for (int _i = 0; _i < 2; ++_i) \
;         __builtin_amdgcn_global_load_lds((const unsigned*)((const char*)(gbase) + (voff)[_i]), (PG8_LAS unsigned*)(lds + (bufoff) + ldsw + _i * 8192), 16, 0, 0); } while (0)
; #define PG8_LDA(dst, b, h) do { _Pragma("unroll") for (int m = 0; m < 4; ++m) _Pragma("unroll") for (int k = 0; k < 2; ++k) dst[m][k] = *(const PG8_LAS bf16x8*)(lds + PG8_SA(b, h) + aoff + m * 2048 + k * 1024); } while (0)
; #define PG8_LDB(dst, b, h) do { _Pragma("unroll") for (int n = 0; n < 2; ++n) _Pragma("unroll") for (int k = 0; k < 2; ++k) dst[n][k] = *(const PG8_LAS bf16x8*)(lds + PG8_SB(b, h) + boff + n * 2048 + k * 1024); } while (0)
; #define PG8_MMA(ai, bj, At, Bt) do { __builtin_amdgcn_s_setprio(1); _Pragma("unroll") for (int m = 0; m < 4; ++m) _Pragma("unroll") for (int n = 0; n < 2; ++n) _Pragma("unroll") for (int k = 0; k < 2; ++k) \
;         acc[ai][bj][m][n] = __builtin_amdgcn_mfma_f32_16x16x32_bf16(Bt[n][k], At[m][k], acc[ai][bj][m][n], 0, 0, 0); __builtin_amdgcn_s_setprio(0); } while (0)
; #define PG8_WAIT_V(n) asm volatile("s_waitcnt vmcnt(" #n ")" ::: "memory")
; #define PG8_WAIT_L(n) asm volatile("s_waitcnt lgkmcnt(" #n ")" ::: "memory")
; #define PG8_BAR __builtin_amdgcn_s_barrier()
; #define PG8_SCHED __builtin_amdgcn_sched_barrier(0)
; template <class Epi, class Sched, bool ALIGN_EPI = false, bool SP2 = false>
; __device__ __forceinline__ void gemm_phase(PG8_LAS unsigned char* lds, const Gemm g, const Sched& S, const Epi& E) {
;     ...
;             PG8_WAIT_V(8); PG8_WAIT_L(0); PG8_BAR; PG8_MMA(1, 0, At, B0); PG8_MMA(1, 1, At, B1); PG8_BAR; PG8_SCHED;
;             PG8_LDB(B0, 1, 0); PG8_LDB(B1, 1, 1); PG8_SCHED; PG8_LDA(At, 1, 0); PG8_STAGE(PG8_SA(0, 1), a2 + hstepA, voffA);
;             PG8_WAIT_V(8); PG8_WAIT_L(0); PG8_BAR; PG8_MMA(0, 0, At, B0); PG8_MMA(0, 1, At, B1); PG8_BAR; PG8_SCHED;
	s_setprio 1
	s_waitcnt lgkmcnt(0)
	v_mfma_f32_16x16x32_bf16 v[60:63], v[142:145], v[216:219], v[60:63]
	v_mfma_f32_16x16x32_bf16 v[60:63], v[156:159], v[220:223], v[60:63]
	v_mfma_f32_16x16x32_bf16 v[56:59], v[164:167], v[220:223], v[56:59]
	v_mfma_f32_16x16x32_bf16 v[56:59], v[160:163], v[216:219], v[56:59]
	v_mfma_f32_16x16x32_bf16 v[40:43], v[160:163], v[224:227], v[40:43]
	v_mfma_f32_16x16x32_bf16 v[40:43], v[164:167], v[228:231], v[40:43]
	v_mfma_f32_16x16x32_bf16 v[48:51], v[156:159], v[228:231], v[48:51]
	v_mfma_f32_16x16x32_bf16 v[48:51], v[142:145], v[224:227], v[48:51]
	v_mfma_f32_16x16x32_bf16 v[32:35], v[142:145], v[232:235], v[32:35]
	v_mfma_f32_16x16x32_bf16 v[32:35], v[156:159], v[236:239], v[32:35]
	v_mfma_f32_16x16x32_bf16 v[24:27], v[164:167], v[236:239], v[24:27]
	v_mfma_f32_16x16x32_bf16 v[24:27], v[160:163], v[232:235], v[24:27]
	s_setprio 0
	s_setprio 1
	v_mfma_f32_16x16x32_bf16 v[8:11], v[160:163], v[240:243], v[8:11]
	v_mfma_f32_16x16x32_bf16 v[8:11], v[164:167], v[244:247], v[8:11]
	v_mfma_f32_16x16x32_bf16 v[12:15], v[156:159], v[244:247], v[12:15]
	v_mfma_f32_16x16x32_bf16 v[12:15], v[142:145], v[240:243], v[12:15]
	v_mfma_f32_16x16x32_bf16 v[52:55], v[168:171], v[216:219], v[52:55]
	v_mfma_f32_16x16x32_bf16 v[52:55], v[172:175], v[220:223], v[52:55]
	v_mfma_f32_16x16x32_bf16 v[44:47], v[188:191], v[220:223], v[44:47]
	v_mfma_f32_16x16x32_bf16 v[44:47], v[182:185], v[216:219], v[44:47]
	v_mfma_f32_16x16x32_bf16 v[28:31], v[182:185], v[224:227], v[28:31]
	v_mfma_f32_16x16x32_bf16 v[28:31], v[188:191], v[228:231], v[28:31]
	v_mfma_f32_16x16x32_bf16 v[36:39], v[172:175], v[228:231], v[36:39]
	v_mfma_f32_16x16x32_bf16 v[36:39], v[168:171], v[224:227], v[36:39]
	v_mfma_f32_16x16x32_bf16 v[20:23], v[168:171], v[232:235], v[20:23]
	v_mfma_f32_16x16x32_bf16 v[20:23], v[172:175], v[236:239], v[20:23]
	v_mfma_f32_16x16x32_bf16 v[16:19], v[188:191], v[236:239], v[16:19]
	v_mfma_f32_16x16x32_bf16 v[16:19], v[182:185], v[232:235], v[16:19]
	v_mfma_f32_16x16x32_bf16 v[0:3], v[182:185], v[240:243], v[0:3]
	v_mfma_f32_16x16x32_bf16 v[0:3], v[188:191], v[244:247], v[0:3]
	v_mfma_f32_16x16x32_bf16 v[4:7], v[172:175], v[244:247], v[4:7]
	v_mfma_f32_16x16x32_bf16 v[4:7], v[168:171], v[240:243], v[4:7]
	s_setprio 0
	s_barrier
	s_add_i32 s82, 0, 0x18000
	v_add_u32_e32 v146, s82, v151
	s_add_i32 s83, 0, 0x1c000
	ds_read_b128 v[142:145], v146
	ds_read_b128 v[156:159], v146 offset:1024
	ds_read_b128 v[160:163], v146 offset:2048
	ds_read_b128 v[164:167], v146 offset:3072
	v_add_u32_e32 v146, s83, v151
	ds_read_b128 v[168:171], v146
	ds_read_b128 v[172:175], v146 offset:1024
	ds_read_b128 v[182:185], v146 offset:2048
	ds_read_b128 v[188:191], v146 offset:3072
	s_add_u32 s70, s70, 0x80000
	s_addc_u32 s71, s71, 0
	s_mov_b32 m0, s72
	v_lshl_add_u64 v[206:207], s[70:71], 0, v[130:131]
	ds_read_b128 v[216:219], v154 offset:32768
	ds_read_b128 v[220:223], v154 offset:33792
	ds_read_b128 v[224:227], v154 offset:34816
	ds_read_b128 v[228:231], v154 offset:35840
	ds_read_b128 v[232:235], v154 offset:36864
	ds_read_b128 v[236:239], v154 offset:37888
	ds_read_b128 v[240:243], v154 offset:38912
	ds_read_b128 v[244:247], v154 offset:39936
	global_load_lds_dwordx4 v[206:207], off
	v_lshl_add_u64 v[206:207], s[70:71], 0, v[134:135]
	s_mov_b32 m0, s73
	s_nop 0
	global_load_lds_dwordx4 v[206:207], off
	s_waitcnt vmcnt(8)
	s_waitcnt lgkmcnt(0)
	s_barrier
	s_setprio 1
	s_waitcnt lgkmcnt(0)
	v_mfma_f32_16x16x32_bf16 v[126:129], v[142:145], v[216:219], v[126:129]
	v_mfma_f32_16x16x32_bf16 v[126:129], v[156:159], v[220:223], v[126:129]
	v_mfma_f32_16x16x32_bf16 v[122:125], v[164:167], v[220:223], v[122:125]
	v_mfma_f32_16x16x32_bf16 v[122:125], v[160:163], v[216:219], v[122:125]
	v_mfma_f32_16x16x32_bf16 v[106:109], v[160:163], v[224:227], v[106:109]
	v_mfma_f32_16x16x32_bf16 v[106:109], v[164:167], v[228:231], v[106:109]
	v_mfma_f32_16x16x32_bf16 v[110:113], v[156:159], v[228:231], v[110:113]
	v_mfma_f32_16x16x32_bf16 v[110:113], v[142:145], v[224:227], v[110:113]
	v_mfma_f32_16x16x32_bf16 v[94:97], v[142:145], v[232:235], v[94:97]
	v_mfma_f32_16x16x32_bf16 v[94:97], v[156:159], v[236:239], v[94:97]
	v_mfma_f32_16x16x32_bf16 v[90:93], v[164:167], v[236:239], v[90:93]
	v_mfma_f32_16x16x32_bf16 v[90:93], v[160:163], v[232:235], v[90:93]
	s_setprio 0
	s_setprio 1
	v_mfma_f32_16x16x32_bf16 v[72:75], v[160:163], v[240:243], v[72:75]
	v_mfma_f32_16x16x32_bf16 v[72:75], v[164:167], v[244:247], v[72:75]
	v_mfma_f32_16x16x32_bf16 v[76:79], v[156:159], v[244:247], v[76:79]
	v_mfma_f32_16x16x32_bf16 v[76:79], v[142:145], v[240:243], v[76:79]
	v_mfma_f32_16x16x32_bf16 v[118:121], v[168:171], v[216:219], v[118:121]
	v_mfma_f32_16x16x32_bf16 v[118:121], v[172:175], v[220:223], v[118:121]
	v_mfma_f32_16x16x32_bf16 v[114:117], v[188:191], v[220:223], v[114:117]
	v_mfma_f32_16x16x32_bf16 v[114:117], v[182:185], v[216:219], v[114:117]
	v_mfma_f32_16x16x32_bf16 v[98:101], v[182:185], v[224:227], v[98:101]
	v_mfma_f32_16x16x32_bf16 v[98:101], v[188:191], v[228:231], v[98:101]
	v_mfma_f32_16x16x32_bf16 v[102:105], v[172:175], v[228:231], v[102:105]
	v_mfma_f32_16x16x32_bf16 v[102:105], v[168:171], v[224:227], v[102:105]
	v_mfma_f32_16x16x32_bf16 v[86:89], v[168:171], v[232:235], v[86:89]
	v_mfma_f32_16x16x32_bf16 v[86:89], v[172:175], v[236:239], v[86:89]
	v_mfma_f32_16x16x32_bf16 v[82:85], v[188:191], v[236:239], v[82:85]
	v_mfma_f32_16x16x32_bf16 v[82:85], v[182:185], v[232:235], v[82:85]
	v_mfma_f32_16x16x32_bf16 v[64:67], v[182:185], v[240:243], v[64:67]
	v_mfma_f32_16x16x32_bf16 v[64:67], v[188:191], v[244:247], v[64:67]
	v_mfma_f32_16x16x32_bf16 v[68:71], v[172:175], v[244:247], v[68:71]
	v_mfma_f32_16x16x32_bf16 v[68:71], v[168:171], v[240:243], v[68:71]
	s_setprio 0
	s_barrier
; #define PG8_STAGE(bufoff, gbase, voff) do { _Pragma("unroll") for (int _i = 0; _i < 2; ++_i) \
;         __builtin_amdgcn_global_load_lds((const unsigned*)((const char*)(gbase) + (voff)[_i]), (PG8_LAS unsigned*)(lds + (bufoff) + ldsw + _i * 8192), 16, 0, 0); } while (0)
; #define PG8_LDA(dst, b, h) do { _Pragma("unroll") for (int m = 0; m < 4; ++m) _Pragma("unroll") for (int k = 0; k < 2; ++k) dst[m][k] = *(const PG8_LAS bf16x8*)(lds + PG8_SA(b, h) + aoff + m * 2048 + k * 1024); } while (0)
; #define PG8_MMA(ai, bj, At, Bt) do { __builtin_amdgcn_s_setprio(1); _Pragma("unroll") for (int m = 0; m < 4; ++m) _Pragma("unroll") for (int n = 0; n < 2; ++n) _Pragma("unroll") for (int k = 0; k < 2; ++k) \
;         acc[ai][bj][m][n] = __builtin_amdgcn_mfma_f32_16x16x32_bf16(Bt[n][k], At[m][k], acc[ai][bj][m][n], 0, 0, 0); __builtin_amdgcn_s_setprio(0); } while (0)
; #define PG8_WAIT_V(n) asm volatile("s_waitcnt vmcnt(" #n ")" ::: "memory")
; #define PG8_WAIT_L(n) asm volatile("s_waitcnt lgkmcnt(" #n ")" ::: "memory")
; #define PG8_BAR __builtin_amdgcn_s_barrier()
; #define PG8_SCHED __builtin_amdgcn_sched_barrier(0)
; template <class Epi, class Sched, bool ALIGN_EPI = false, bool SP2 = false>
; __device__ __forceinline__ void gemm_phase(PG8_LAS unsigned char* lds, const Gemm g, const Sched& S, const Epi& E) {
;     ...
;             PG8_LDA(At, 1, 1); PG8_STAGE(PG8_SB(1, 0), b3, voffB); PG8_STAGE(PG8_SB(1, 1), b3 + hstepB, voffB); PG8_STAGE(PG8_SA(1, 0), a3, voffA);
;             PG8_WAIT_V(8); PG8_WAIT_L(0); PG8_BAR; PG8_MMA(1, 0, At, B0); PG8_MMA(1, 1, At, B1); PG8_BAR; PG8_SCHED;
	s_add_i32 s70, s82, s33
	v_lshl_add_u64 v[176:177], v[176:177], 0, s[60:61]
	s_mov_b32 m0, s70
	ds_read_b128 v[216:219], v154 offset:49152
	ds_read_b128 v[220:223], v154 offset:50176
	ds_read_b128 v[224:227], v154 offset:51200
	ds_read_b128 v[228:231], v154 offset:52224
	ds_read_b128 v[232:235], v154 offset:53248
	ds_read_b128 v[236:239], v154 offset:54272
	ds_read_b128 v[240:243], v154 offset:55296
	ds_read_b128 v[244:247], v154 offset:56320
	global_load_lds_dwordx4 v[176:177], off
	s_add_i32 m0, s70, 0x2000
	s_add_u32 s68, s68, 0x80080
	v_lshl_add_u64 v[176:177], v[192:193], 0, s[60:61]
	s_addc_u32 s69, s69, 0
	s_add_i32 s70, s83, s33
	global_load_lds_dwordx4 v[176:177], off
	v_lshl_add_u64 v[176:177], s[68:69], 0, v[132:133]
	s_mov_b32 m0, s70
	s_nop 0
	global_load_lds_dwordx4 v[176:177], off
	v_lshl_add_u64 v[176:177], s[68:69], 0, v[136:137]
	s_add_i32 m0, s70, 0x2000
	s_nop 0
	global_load_lds_dwordx4 v[176:177], off
	v_lshl_add_u64 v[176:177], v[202:203], 0, s[60:61]
	s_mov_b32 m0, s75
	s_nop 0
	global_load_lds_dwordx4 v[176:177], off
	v_lshl_add_u64 v[176:177], v[204:205], 0, s[60:61]
	s_mov_b32 m0, s76
	s_nop 0
	global_load_lds_dwordx4 v[176:177], off
	s_waitcnt vmcnt(8)
	s_waitcnt lgkmcnt(0)
	s_barrier
	s_setprio 1
	s_waitcnt lgkmcnt(0)
	v_mfma_f32_16x16x32_bf16 v[60:63], v[142:145], v[216:219], v[60:63]
	v_mfma_f32_16x16x32_bf16 v[60:63], v[156:159], v[220:223], v[60:63]
	v_mfma_f32_16x16x32_bf16 v[56:59], v[164:167], v[220:223], v[56:59]
	v_mfma_f32_16x16x32_bf16 v[56:59], v[160:163], v[216:219], v[56:59]
	v_mfma_f32_16x16x32_bf16 v[40:43], v[160:163], v[224:227], v[40:43]
	v_mfma_f32_16x16x32_bf16 v[40:43], v[164:167], v[228:231], v[40:43]
	v_mfma_f32_16x16x32_bf16 v[48:51], v[156:159], v[228:231], v[48:51]
	v_mfma_f32_16x16x32_bf16 v[48:51], v[142:145], v[224:227], v[48:51]
	v_mfma_f32_16x16x32_bf16 v[32:35], v[142:145], v[232:235], v[32:35]
	v_mfma_f32_16x16x32_bf16 v[32:35], v[156:159], v[236:239], v[32:35]
	v_mfma_f32_16x16x32_bf16 v[24:27], v[164:167], v[236:239], v[24:27]
	v_mfma_f32_16x16x32_bf16 v[24:27], v[160:163], v[232:235], v[24:27]
	s_setprio 0
	s_setprio 1
	v_mfma_f32_16x16x32_bf16 v[8:11], v[160:163], v[240:243], v[8:11]
	v_mfma_f32_16x16x32_bf16 v[8:11], v[164:167], v[244:247], v[8:11]
	v_mfma_f32_16x16x32_bf16 v[12:15], v[156:159], v[244:247], v[12:15]
	v_mfma_f32_16x16x32_bf16 v[12:15], v[142:145], v[240:243], v[12:15]
	v_mfma_f32_16x16x32_bf16 v[52:55], v[168:171], v[216:219], v[52:55]
	v_mfma_f32_16x16x32_bf16 v[52:55], v[172:175], v[220:223], v[52:55]
	v_mfma_f32_16x16x32_bf16 v[44:47], v[188:191], v[220:223], v[44:47]
	v_mfma_f32_16x16x32_bf16 v[44:47], v[182:185], v[216:219], v[44:47]
	v_mfma_f32_16x16x32_bf16 v[28:31], v[182:185], v[224:227], v[28:31]
	v_mfma_f32_16x16x32_bf16 v[28:31], v[188:191], v[228:231], v[28:31]
	v_mfma_f32_16x16x32_bf16 v[36:39], v[172:175], v[228:231], v[36:39]
	v_mfma_f32_16x16x32_bf16 v[36:39], v[168:171], v[224:227], v[36:39]
	v_mfma_f32_16x16x32_bf16 v[20:23], v[168:171], v[232:235], v[20:23]
	v_mfma_f32_16x16x32_bf16 v[20:23], v[172:175], v[236:239], v[20:23]
	v_mfma_f32_16x16x32_bf16 v[16:19], v[188:191], v[236:239], v[16:19]
	v_mfma_f32_16x16x32_bf16 v[16:19], v[182:185], v[232:235], v[16:19]
	v_mfma_f32_16x16x32_bf16 v[0:3], v[182:185], v[240:243], v[0:3]
	v_mfma_f32_16x16x32_bf16 v[0:3], v[188:191], v[244:247], v[0:3]
	v_mfma_f32_16x16x32_bf16 v[4:7], v[172:175], v[244:247], v[4:7]
	v_mfma_f32_16x16x32_bf16 v[4:7], v[168:171], v[240:243], v[4:7]
	s_setprio 0
	s_barrier
	s_add_i32 s81, s81, 2
	s_add_u32 vcc_lo, vcc_lo, 0x100
	s_addc_u32 vcc_hi, vcc_hi, 0
	s_add_u32 s79, s79, 0x100
	s_addc_u32 s80, s80, 0
	s_cmp_gt_u32 s81, 29
	s_cbranch_scc0 .LBB0_1183
	s_and_b64 vcc, exec, s[62:63]
	s_cbranch_vccz .LBB0_1186
	s_barrier

; #define PG8_STAGE(bufoff, gbase, voff) do { _Pragma("unroll") for (int _i = 0; _i < 2; ++_i) \
;         __builtin_amdgcn_global_load_lds((const unsigned*)((const char*)(gbase) + (voff)[_i]), (PG8_LAS unsigned*)(lds + (bufoff) + ldsw + _i * 8192), 16, 0, 0); } while (0)
; #define PG8_LDA(dst, b, h) do { _Pragma("unroll") for (int m = 0; m < 4; ++m) _Pragma("unroll") for (int k = 0; k < 2; ++k) dst[m][k] = *(const PG8_LAS bf16x8*)(lds + PG8_SA(b, h) + aoff + m * 2048 + k * 1024); } while (0)
; #define PG8_LDB(dst, b, h) do { _Pragma("unroll") for (int n = 0; n < 2; ++n) _Pragma("unroll") for (int k = 0; k < 2; ++k) dst[n][k] = *(const PG8_LAS bf16x8*)(lds + PG8_SB(b, h) + boff + n * 2048 + k * 1024); } while (0)
; #define PG8_MMA(ai, bj, At, Bt) do { __builtin_amdgcn_s_setprio(1); _Pragma("unroll") for (int m = 0; m < 4; ++m) _Pragma("unroll") for (int n = 0; n < 2; ++n) _Pragma("unroll") for (int k = 0; k < 2; ++k) \
;         acc[ai][bj][m][n] = __builtin_amdgcn_mfma_f32_16x16x32_bf16(Bt[n][k], At[m][k], acc[ai][bj][m][n], 0, 0, 0); __builtin_amdgcn_s_setprio(0); } while (0)
; #define PG8_WAIT_V(n) asm volatile("s_waitcnt vmcnt(" #n ")" ::: "memory")
; #define PG8_WAIT_L(n) asm volatile("s_waitcnt lgkmcnt(" #n ")" ::: "memory")
; #define PG8_BAR __builtin_amdgcn_s_barrier()
; template <class Epi, class Sched, bool ALIGN_EPI = false, bool SP2 = false>
; __device__ __forceinline__ void gemm_phase(PG8_LAS unsigned char* lds, const Gemm g, const Sched& S, const Epi& E) {
;     ...
;             const char* a1 = cA + (size_t)(t + 1) * kstep;
;             const char* a2 = last ? nA : cA + (size_t)(t + 2) * kstep; const char* b2 = last ? nB : cB + (size_t)(t + 2) * kstep;
;             const char* a3 = a2 + kstep; const char* b3 = b2 + kstep;
;             if (last && has_next) S.a_ready(nxt);
;             if constexpr (SP2) {
;             PG8_LDB(B0, 0, 0); PG8_LDB(B1, 0, 1); PG8_SCHED; PG8_LDA(At, 0, 0); PG8_STAGE(PG8_SA(1, 1), a1 + hstepA, voffA);
;             PG8_WAIT_V(8); PG8_WAIT_L(0); PG8_BAR; PG8_MMA(0, 0, At, B0); PG8_MMA(0, 1, At, B1); PG8_BAR; PG8_SCHED;
;             PG8_LDA(At, 0, 1); PG8_STAGE(PG8_SB(0, 0), b2, voffB); PG8_STAGE(PG8_SB(0, 1), b2 + hstepB, voffB); PG8_STAGE(PG8_SA(0, 0), a2, voffA);
;             PG8_WAIT_V(8); PG8_WAIT_L(0); PG8_BAR; PG8_MMA(1, 0, At, B0); PG8_MMA(1, 1, At, B1); PG8_BAR; PG8_SCHED;
.LBB0_1367:
	s_add_u32 s22, s66, 0xffe00080
	s_addc_u32 s23, s67, -1
	s_add_i32 s74, 0, 0x10000
	s_cmp_eq_u32 s73, 12
	s_cselect_b32 s57, s53, s23
	s_cselect_b32 s56, s52, s22
	s_cselect_b32 s23, s63, s43
	s_cselect_b32 s22, s62, s41
	s_add_i32 s76, 0, 0x14000
	v_add_u32_e32 v156, s74, v142
	v_add_u32_e32 v172, s76, v142
	ds_read_b128 v[144:147], v156
	ds_read_b128 v[148:151], v156 offset:1024
	ds_read_b128 v[152:155], v156 offset:2048
	ds_read_b128 v[156:159], v156 offset:3072
	ds_read_b128 v[160:163], v172
	ds_read_b128 v[164:167], v172 offset:1024
	ds_read_b128 v[168:171], v172 offset:2048
	ds_read_b128 v[172:175], v172 offset:3072
	v_lshl_add_u64 v[176:177], s[66:67], 0, v[136:137]
	s_add_i32 m0, s35, 0xc000
	ds_read_b128 v[182:185], v143
	ds_read_b128 v[188:191], v143 offset:1024
	ds_read_b128 v[216:219], v143 offset:2048
	ds_read_b128 v[220:223], v143 offset:3072
	ds_read_b128 v[224:227], v143 offset:4096
	ds_read_b128 v[228:231], v143 offset:5120
	ds_read_b128 v[232:235], v143 offset:6144
	ds_read_b128 v[236:239], v143 offset:7168
	global_load_lds_dwordx4 v[176:177], off
	v_lshl_add_u64 v[176:177], s[66:67], 0, v[138:139]
	s_add_i32 m0, s35, 0xe000
	s_nop 0
	global_load_lds_dwordx4 v[176:177], off
	s_waitcnt vmcnt(8)
	s_waitcnt lgkmcnt(0)
	s_barrier
	s_setprio 1
	s_waitcnt lgkmcnt(0)
	v_mfma_f32_16x16x32_bf16 v[126:129], v[144:147], v[182:185], v[126:129]
	v_mfma_f32_16x16x32_bf16 v[126:129], v[148:151], v[188:191], v[126:129]
	v_mfma_f32_16x16x32_bf16 v[122:125], v[156:159], v[188:191], v[122:125]
	v_mfma_f32_16x16x32_bf16 v[122:125], v[152:155], v[182:185], v[122:125]
	v_mfma_f32_16x16x32_bf16 v[114:117], v[152:155], v[216:219], v[114:117]
	v_mfma_f32_16x16x32_bf16 v[114:117], v[156:159], v[220:223], v[114:117]
	v_mfma_f32_16x16x32_bf16 v[118:121], v[148:151], v[220:223], v[118:121]
	v_mfma_f32_16x16x32_bf16 v[118:121], v[144:147], v[216:219], v[118:121]
	v_mfma_f32_16x16x32_bf16 v[106:109], v[144:147], v[224:227], v[106:109]
	v_mfma_f32_16x16x32_bf16 v[106:109], v[148:151], v[228:231], v[106:109]
	v_mfma_f32_16x16x32_bf16 v[98:101], v[156:159], v[228:231], v[98:101]
	v_mfma_f32_16x16x32_bf16 v[98:101], v[152:155], v[224:227], v[98:101]
	s_setprio 0
	s_setprio 1
	v_mfma_f32_16x16x32_bf16 v[82:85], v[152:155], v[232:235], v[82:85]
	v_mfma_f32_16x16x32_bf16 v[82:85], v[156:159], v[236:239], v[82:85]
	v_mfma_f32_16x16x32_bf16 v[90:93], v[148:151], v[236:239], v[90:93]
	v_mfma_f32_16x16x32_bf16 v[90:93], v[144:147], v[232:235], v[90:93]
	v_mfma_f32_16x16x32_bf16 v[110:113], v[160:163], v[182:185], v[110:113]
	v_mfma_f32_16x16x32_bf16 v[110:113], v[164:167], v[188:191], v[110:113]
	v_mfma_f32_16x16x32_bf16 v[102:105], v[172:175], v[188:191], v[102:105]
	v_mfma_f32_16x16x32_bf16 v[102:105], v[168:171], v[182:185], v[102:105]
	v_mfma_f32_16x16x32_bf16 v[86:89], v[168:171], v[216:219], v[86:89]
	v_mfma_f32_16x16x32_bf16 v[86:89], v[172:175], v[220:223], v[86:89]
	v_mfma_f32_16x16x32_bf16 v[94:97], v[164:167], v[220:223], v[94:97]
	v_mfma_f32_16x16x32_bf16 v[94:97], v[160:163], v[216:219], v[94:97]
	v_mfma_f32_16x16x32_bf16 v[76:79], v[160:163], v[224:227], v[76:79]
	v_mfma_f32_16x16x32_bf16 v[76:79], v[164:167], v[228:231], v[76:79]
	v_mfma_f32_16x16x32_bf16 v[72:75], v[172:175], v[228:231], v[72:75]
	v_mfma_f32_16x16x32_bf16 v[72:75], v[168:171], v[224:227], v[72:75]
	v_mfma_f32_16x16x32_bf16 v[64:67], v[168:171], v[232:235], v[64:67]
	v_mfma_f32_16x16x32_bf16 v[64:67], v[172:175], v[236:239], v[64:67]
	v_mfma_f32_16x16x32_bf16 v[68:71], v[164:167], v[236:239], v[68:71]
	v_mfma_f32_16x16x32_bf16 v[68:71], v[160:163], v[232:235], v[68:71]
	s_setprio 0
	s_barrier
	s_add_i32 s74, s74, s33
	v_lshl_add_u64 v[176:177], s[22:23], 0, v[80:81]
	s_mov_b32 m0, s74
	ds_read_b128 v[182:185], v143 offset:16384
	ds_read_b128 v[188:191], v143 offset:17408
	ds_read_b128 v[216:219], v143 offset:18432
	ds_read_b128 v[220:223], v143 offset:19456
	ds_read_b128 v[224:227], v143 offset:20480
	ds_read_b128 v[228:231], v143 offset:21504
	ds_read_b128 v[232:235], v143 offset:22528
	ds_read_b128 v[236:239], v143 offset:23552
	global_load_lds_dwordx4 v[176:177], off
	s_add_i32 m0, s74, 0x2000
	s_add_u32 s74, s22, 0x200000
	v_lshl_add_u64 v[192:193], s[22:23], 0, v[130:131]
	s_addc_u32 s75, s23, 0
	s_add_i32 s76, s76, s33
	global_load_lds_dwordx4 v[192:193], off
	v_lshl_add_u64 v[202:203], s[74:75], 0, v[80:81]
	s_mov_b32 m0, s76
	v_lshl_add_u64 v[204:205], s[56:57], 0, v[132:133]
	global_load_lds_dwordx4 v[202:203], off
	v_lshl_add_u64 v[202:203], s[74:75], 0, v[130:131]
	s_add_i32 m0, s76, 0x2000
	s_nop 0
	global_load_lds_dwordx4 v[202:203], off
	v_lshl_add_u64 v[202:203], s[56:57], 0, v[134:135]
	s_mov_b32 m0, s35
	s_nop 0
	global_load_lds_dwordx4 v[202:203], off
	s_mov_b32 m0, s36
	s_nop 0
	global_load_lds_dwordx4 v[204:205], off
	s_waitcnt vmcnt(8)
	s_waitcnt lgkmcnt(0)
	s_barrier
; #define PG8_STAGE(bufoff, gbase, voff) do { _Pragma("unroll") for (int _i = 0; _i < 2; ++_i) \
;         __builtin_amdgcn_global_load_lds((const unsigned*)((const char*)(gbase) + (voff)[_i]), (PG8_LAS unsigned*)(lds + (bufoff) + ldsw + _i * 8192), 16, 0, 0); } while (0)
; #define PG8_LDA(dst, b, h) do { _Pragma("unroll") for (int m = 0; m < 4; ++m) _Pragma("unroll") for (int k = 0; k < 2; ++k) dst[m][k] = *(const PG8_LAS bf16x8*)(lds + PG8_SA(b, h) + aoff + m * 2048 + k * 1024); } while (0)
; #define PG8_LDB(dst, b, h) do { _Pragma("unroll") for (int n = 0; n < 2; ++n) _Pragma("unroll") for (int k = 0; k < 2; ++k) dst[n][k] = *(const PG8_LAS bf16x8*)(lds + PG8_SB(b, h) + boff + n * 2048 + k * 1024); } while (0)
; #define PG8_MMA(ai, bj, At, Bt) do { __builtin_amdgcn_s_setprio(1); _Pragma("unroll") for (int m = 0; m < 4; ++m) _Pragma("unroll") for (int n = 0; n < 2; ++n) _Pragma("unroll") for (int k = 0; k < 2; ++k) \
;         acc[ai][bj][m][n] = __builtin_amdgcn_mfma_f32_16x16x32_bf16(Bt[n][k], At[m][k], acc[ai][bj][m][n], 0, 0, 0); __builtin_amdgcn_s_setprio(0); } while (0)
; #define PG8_WAIT_V(n) asm volatile("s_waitcnt vmcnt(" #n ")" ::: "memory")
; #define PG8_WAIT_L(n) asm volatile("s_waitcnt lgkmcnt(" #n ")" ::: "memory")
; #define PG8_BAR __builtin_amdgcn_s_barrier()
; #define PG8_SCHED __builtin_amdgcn_sched_barrier(0)
; template <class Epi, class Sched, bool ALIGN_EPI = false, bool SP2 = false>
; __device__ __forceinline__ void gemm_phase(PG8_LAS unsigned char* lds, const Gemm g, const Sched& S, const Epi& E) {
;     ...
;             PG8_WAIT_V(8); PG8_WAIT_L(0); PG8_BAR; PG8_MMA(1, 0, At, B0); PG8_MMA(1, 1, At, B1); PG8_BAR; PG8_SCHED;
;             PG8_LDB(B0, 1, 0); PG8_LDB(B1, 1, 1); PG8_SCHED; PG8_LDA(At, 1, 0); PG8_STAGE(PG8_SA(0, 1), a2 + hstepA, voffA);
;             PG8_WAIT_V(8); PG8_WAIT_L(0); PG8_BAR; PG8_MMA(0, 0, At, B0); PG8_MMA(0, 1, At, B1); PG8_BAR; PG8_SCHED;
	s_setprio 1
	s_waitcnt lgkmcnt(0)
	v_mfma_f32_16x16x32_bf16 v[60:63], v[144:147], v[182:185], v[60:63]
	v_mfma_f32_16x16x32_bf16 v[60:63], v[148:151], v[188:191], v[60:63]
	v_mfma_f32_16x16x32_bf16 v[56:59], v[156:159], v[188:191], v[56:59]
	v_mfma_f32_16x16x32_bf16 v[56:59], v[152:155], v[182:185], v[56:59]
	v_mfma_f32_16x16x32_bf16 v[48:51], v[152:155], v[216:219], v[48:51]
	v_mfma_f32_16x16x32_bf16 v[48:51], v[156:159], v[220:223], v[48:51]
	v_mfma_f32_16x16x32_bf16 v[52:55], v[148:151], v[220:223], v[52:55]
	v_mfma_f32_16x16x32_bf16 v[52:55], v[144:147], v[216:219], v[52:55]
	v_mfma_f32_16x16x32_bf16 v[36:39], v[144:147], v[224:227], v[36:39]
	v_mfma_f32_16x16x32_bf16 v[36:39], v[148:151], v[228:231], v[36:39]
	v_mfma_f32_16x16x32_bf16 v[32:35], v[156:159], v[228:231], v[32:35]
	v_mfma_f32_16x16x32_bf16 v[32:35], v[152:155], v[224:227], v[32:35]
	s_setprio 0
	s_setprio 1
	v_mfma_f32_16x16x32_bf16 v[16:19], v[152:155], v[232:235], v[16:19]
	v_mfma_f32_16x16x32_bf16 v[16:19], v[156:159], v[236:239], v[16:19]
	v_mfma_f32_16x16x32_bf16 v[20:23], v[148:151], v[236:239], v[20:23]
	v_mfma_f32_16x16x32_bf16 v[20:23], v[144:147], v[232:235], v[20:23]
	v_mfma_f32_16x16x32_bf16 v[44:47], v[160:163], v[182:185], v[44:47]
	v_mfma_f32_16x16x32_bf16 v[44:47], v[164:167], v[188:191], v[44:47]
	v_mfma_f32_16x16x32_bf16 v[40:43], v[172:175], v[188:191], v[40:43]
	v_mfma_f32_16x16x32_bf16 v[40:43], v[168:171], v[182:185], v[40:43]
	v_mfma_f32_16x16x32_bf16 v[24:27], v[168:171], v[216:219], v[24:27]
	v_mfma_f32_16x16x32_bf16 v[24:27], v[172:175], v[220:223], v[24:27]
	v_mfma_f32_16x16x32_bf16 v[28:31], v[164:167], v[220:223], v[28:31]
	v_mfma_f32_16x16x32_bf16 v[28:31], v[160:163], v[216:219], v[28:31]
	v_mfma_f32_16x16x32_bf16 v[12:15], v[160:163], v[224:227], v[12:15]
	v_mfma_f32_16x16x32_bf16 v[12:15], v[164:167], v[228:231], v[12:15]
	v_mfma_f32_16x16x32_bf16 v[8:11], v[172:175], v[228:231], v[8:11]
	v_mfma_f32_16x16x32_bf16 v[8:11], v[168:171], v[224:227], v[8:11]
	v_mfma_f32_16x16x32_bf16 v[0:3], v[168:171], v[232:235], v[0:3]
	v_mfma_f32_16x16x32_bf16 v[0:3], v[172:175], v[236:239], v[0:3]
	v_mfma_f32_16x16x32_bf16 v[4:7], v[164:167], v[236:239], v[4:7]
	v_mfma_f32_16x16x32_bf16 v[4:7], v[160:163], v[232:235], v[4:7]
	s_setprio 0
	s_barrier
	s_add_i32 s74, 0, 0x18000
	s_add_i32 s75, 0, 0x1c000
	v_add_u32_e32 v156, s74, v142
	v_add_u32_e32 v172, s75, v142
	ds_read_b128 v[144:147], v156
	ds_read_b128 v[148:151], v156 offset:1024
	ds_read_b128 v[152:155], v156 offset:2048
	ds_read_b128 v[156:159], v156 offset:3072
	ds_read_b128 v[160:163], v172
	ds_read_b128 v[164:167], v172 offset:1024
	ds_read_b128 v[168:171], v172 offset:2048
	ds_read_b128 v[172:175], v172 offset:3072
	s_add_u32 s56, s56, 0x200000
	s_addc_u32 s57, s57, 0
	s_mov_b32 m0, s37
	v_lshl_add_u64 v[206:207], s[56:57], 0, v[134:135]
	ds_read_b128 v[182:185], v143 offset:32768
	ds_read_b128 v[188:191], v143 offset:33792
	ds_read_b128 v[216:219], v143 offset:34816
	ds_read_b128 v[220:223], v143 offset:35840
	ds_read_b128 v[224:227], v143 offset:36864
	ds_read_b128 v[228:231], v143 offset:37888
	ds_read_b128 v[232:235], v143 offset:38912
	ds_read_b128 v[236:239], v143 offset:39936
	global_load_lds_dwordx4 v[206:207], off
	v_lshl_add_u64 v[206:207], s[56:57], 0, v[132:133]
	s_mov_b32 m0, s44
	s_nop 0
	global_load_lds_dwordx4 v[206:207], off
	s_waitcnt vmcnt(8)
	s_waitcnt lgkmcnt(0)
	s_barrier
	s_setprio 1
	s_waitcnt lgkmcnt(0)
	v_mfma_f32_16x16x32_bf16 v[126:129], v[144:147], v[182:185], v[126:129]
	v_mfma_f32_16x16x32_bf16 v[126:129], v[148:151], v[188:191], v[126:129]
	v_mfma_f32_16x16x32_bf16 v[122:125], v[156:159], v[188:191], v[122:125]
	v_mfma_f32_16x16x32_bf16 v[122:125], v[152:155], v[182:185], v[122:125]
	v_mfma_f32_16x16x32_bf16 v[114:117], v[152:155], v[216:219], v[114:117]
	v_mfma_f32_16x16x32_bf16 v[114:117], v[156:159], v[220:223], v[114:117]
	v_mfma_f32_16x16x32_bf16 v[118:121], v[148:151], v[220:223], v[118:121]
	v_mfma_f32_16x16x32_bf16 v[118:121], v[144:147], v[216:219], v[118:121]
	v_mfma_f32_16x16x32_bf16 v[106:109], v[144:147], v[224:227], v[106:109]
	v_mfma_f32_16x16x32_bf16 v[106:109], v[148:151], v[228:231], v[106:109]
	v_mfma_f32_16x16x32_bf16 v[98:101], v[156:159], v[228:231], v[98:101]
	v_mfma_f32_16x16x32_bf16 v[98:101], v[152:155], v[224:227], v[98:101]
	s_setprio 0
	s_setprio 1
	v_mfma_f32_16x16x32_bf16 v[82:85], v[152:155], v[232:235], v[82:85]
	v_mfma_f32_16x16x32_bf16 v[82:85], v[156:159], v[236:239], v[82:85]
	v_mfma_f32_16x16x32_bf16 v[90:93], v[148:151], v[236:239], v[90:93]
	v_mfma_f32_16x16x32_bf16 v[90:93], v[144:147], v[232:235], v[90:93]
	v_mfma_f32_16x16x32_bf16 v[110:113], v[160:163], v[182:185], v[110:113]
	v_mfma_f32_16x16x32_bf16 v[110:113], v[164:167], v[188:191], v[110:113]
	v_mfma_f32_16x16x32_bf16 v[102:105], v[172:175], v[188:191], v[102:105]
	v_mfma_f32_16x16x32_bf16 v[102:105], v[168:171], v[182:185], v[102:105]
	v_mfma_f32_16x16x32_bf16 v[86:89], v[168:171], v[216:219], v[86:89]
	v_mfma_f32_16x16x32_bf16 v[86:89], v[172:175], v[220:223], v[86:89]
	v_mfma_f32_16x16x32_bf16 v[94:97], v[164:167], v[220:223], v[94:97]
	v_mfma_f32_16x16x32_bf16 v[94:97], v[160:163], v[216:219], v[94:97]
	v_mfma_f32_16x16x32_bf16 v[76:79], v[160:163], v[224:227], v[76:79]
	v_mfma_f32_16x16x32_bf16 v[76:79], v[164:167], v[228:231], v[76:79]
	v_mfma_f32_16x16x32_bf16 v[72:75], v[172:175], v[228:231], v[72:75]
	v_mfma_f32_16x16x32_bf16 v[72:75], v[168:171], v[224:227], v[72:75]
	v_mfma_f32_16x16x32_bf16 v[64:67], v[168:171], v[232:235], v[64:67]
	v_mfma_f32_16x16x32_bf16 v[64:67], v[172:175], v[236:239], v[64:67]
	v_mfma_f32_16x16x32_bf16 v[68:71], v[164:167], v[236:239], v[68:71]
	v_mfma_f32_16x16x32_bf16 v[68:71], v[160:163], v[232:235], v[68:71]
	s_setprio 0
	s_barrier
; #define PG8_STAGE(bufoff, gbase, voff) do { _Pragma("unroll") for (int _i = 0; _i < 2; ++_i) \
;         __builtin_amdgcn_global_load_lds((const unsigned*)((const char*)(gbase) + (voff)[_i]), (PG8_LAS unsigned*)(lds + (bufoff) + ldsw + _i * 8192), 16, 0, 0); } while (0)
; #define PG8_LDA(dst, b, h) do { _Pragma("unroll") for (int m = 0; m < 4; ++m) _Pragma("unroll") for (int k = 0; k < 2; ++k) dst[m][k] = *(const PG8_LAS bf16x8*)(lds + PG8_SA(b, h) + aoff + m * 2048 + k * 1024); } while (0)
; #define PG8_MMA(ai, bj, At, Bt) do { __builtin_amdgcn_s_setprio(1); _Pragma("unroll") for (int m = 0; m < 4; ++m) _Pragma("unroll") for (int n = 0; n < 2; ++n) _Pragma("unroll") for (int k = 0; k < 2; ++k) \
;         acc[ai][bj][m][n] = __builtin_amdgcn_mfma_f32_16x16x32_bf16(Bt[n][k], At[m][k], acc[ai][bj][m][n], 0, 0, 0); __builtin_amdgcn_s_setprio(0); } while (0)
; #define PG8_WAIT_V(n) asm volatile("s_waitcnt vmcnt(" #n ")" ::: "memory")
; #define PG8_WAIT_L(n) asm volatile("s_waitcnt lgkmcnt(" #n ")" ::: "memory")
; #define PG8_BAR __builtin_amdgcn_s_barrier()
; #define PG8_SCHED __builtin_amdgcn_sched_barrier(0)
; template <class Epi, class Sched, bool ALIGN_EPI = false, bool SP2 = false>
; __device__ __forceinline__ void gemm_phase(PG8_LAS unsigned char* lds, const Gemm g, const Sched& S, const Epi& E) {
;     ...
;             PG8_LDA(At, 1, 1); PG8_STAGE(PG8_SB(1, 0), b3, voffB); PG8_STAGE(PG8_SB(1, 1), b3 + hstepB, voffB); PG8_STAGE(PG8_SA(1, 0), a3, voffA);
;             PG8_WAIT_V(8); PG8_WAIT_L(0); PG8_BAR; PG8_MMA(1, 0, At, B0); PG8_MMA(1, 1, At, B1); PG8_BAR; PG8_SCHED;
	s_add_i32 s56, s74, s33
	v_lshl_add_u64 v[176:177], v[176:177], 0, s[60:61]
	s_mov_b32 m0, s56
	ds_read_b128 v[182:185], v143 offset:49152
	ds_read_b128 v[188:191], v143 offset:50176
	ds_read_b128 v[216:219], v143 offset:51200
	ds_read_b128 v[220:223], v143 offset:52224
	ds_read_b128 v[224:227], v143 offset:53248
	ds_read_b128 v[228:231], v143 offset:54272
	ds_read_b128 v[232:235], v143 offset:55296
	ds_read_b128 v[236:239], v143 offset:56320
	global_load_lds_dwordx4 v[176:177], off
	s_add_i32 m0, s56, 0x2000
	s_add_u32 s22, s22, 0x200080
	v_lshl_add_u64 v[176:177], v[192:193], 0, s[60:61]
	s_addc_u32 s23, s23, 0
	s_add_i32 s56, s75, s33
	global_load_lds_dwordx4 v[176:177], off
	v_lshl_add_u64 v[176:177], s[22:23], 0, v[80:81]
	s_mov_b32 m0, s56
	s_nop 0
	global_load_lds_dwordx4 v[176:177], off
	v_lshl_add_u64 v[176:177], s[22:23], 0, v[130:131]
	s_add_i32 m0, s56, 0x2000
	s_nop 0
	global_load_lds_dwordx4 v[176:177], off
	v_lshl_add_u64 v[176:177], v[202:203], 0, s[60:61]
	s_mov_b32 m0, s45
	s_nop 0
	global_load_lds_dwordx4 v[176:177], off
	v_lshl_add_u64 v[176:177], v[204:205], 0, s[60:61]
	s_mov_b32 m0, s49
	s_nop 0
	global_load_lds_dwordx4 v[176:177], off
	s_waitcnt vmcnt(8)
	s_waitcnt lgkmcnt(0)
	s_barrier
	s_setprio 1
	s_waitcnt lgkmcnt(0)
	v_mfma_f32_16x16x32_bf16 v[60:63], v[144:147], v[182:185], v[60:63]
	v_mfma_f32_16x16x32_bf16 v[60:63], v[148:151], v[188:191], v[60:63]
	v_mfma_f32_16x16x32_bf16 v[56:59], v[156:159], v[188:191], v[56:59]
	v_mfma_f32_16x16x32_bf16 v[56:59], v[152:155], v[182:185], v[56:59]
	v_mfma_f32_16x16x32_bf16 v[48:51], v[152:155], v[216:219], v[48:51]
	v_mfma_f32_16x16x32_bf16 v[48:51], v[156:159], v[220:223], v[48:51]
	v_mfma_f32_16x16x32_bf16 v[52:55], v[148:151], v[220:223], v[52:55]
	v_mfma_f32_16x16x32_bf16 v[52:55], v[144:147], v[216:219], v[52:55]
	v_mfma_f32_16x16x32_bf16 v[36:39], v[144:147], v[224:227], v[36:39]
	v_mfma_f32_16x16x32_bf16 v[36:39], v[148:151], v[228:231], v[36:39]
	v_mfma_f32_16x16x32_bf16 v[32:35], v[156:159], v[228:231], v[32:35]
	v_mfma_f32_16x16x32_bf16 v[32:35], v[152:155], v[224:227], v[32:35]
	s_setprio 0
	s_setprio 1
	v_mfma_f32_16x16x32_bf16 v[16:19], v[152:155], v[232:235], v[16:19]
	v_mfma_f32_16x16x32_bf16 v[16:19], v[156:159], v[236:239], v[16:19]
	v_mfma_f32_16x16x32_bf16 v[20:23], v[148:151], v[236:239], v[20:23]
	v_mfma_f32_16x16x32_bf16 v[20:23], v[144:147], v[232:235], v[20:23]
	v_mfma_f32_16x16x32_bf16 v[44:47], v[160:163], v[182:185], v[44:47]
	v_mfma_f32_16x16x32_bf16 v[44:47], v[164:167], v[188:191], v[44:47]
	v_mfma_f32_16x16x32_bf16 v[40:43], v[172:175], v[188:191], v[40:43]
	v_mfma_f32_16x16x32_bf16 v[40:43], v[168:171], v[182:185], v[40:43]
	v_mfma_f32_16x16x32_bf16 v[24:27], v[168:171], v[216:219], v[24:27]
	v_mfma_f32_16x16x32_bf16 v[24:27], v[172:175], v[220:223], v[24:27]
	v_mfma_f32_16x16x32_bf16 v[28:31], v[164:167], v[220:223], v[28:31]
	v_mfma_f32_16x16x32_bf16 v[28:31], v[160:163], v[216:219], v[28:31]
	v_mfma_f32_16x16x32_bf16 v[12:15], v[160:163], v[224:227], v[12:15]
	v_mfma_f32_16x16x32_bf16 v[12:15], v[164:167], v[228:231], v[12:15]
	v_mfma_f32_16x16x32_bf16 v[8:11], v[172:175], v[228:231], v[8:11]
	v_mfma_f32_16x16x32_bf16 v[8:11], v[168:171], v[224:227], v[8:11]
	v_mfma_f32_16x16x32_bf16 v[0:3], v[168:171], v[232:235], v[0:3]
	v_mfma_f32_16x16x32_bf16 v[0:3], v[172:175], v[236:239], v[0:3]
	v_mfma_f32_16x16x32_bf16 v[4:7], v[164:167], v[236:239], v[4:7]
	v_mfma_f32_16x16x32_bf16 v[4:7], v[160:163], v[232:235], v[4:7]
	s_setprio 0
	s_barrier
	s_add_i32 s73, s73, 2
	s_add_u32 s66, s66, 0x100
	s_addc_u32 s67, s67, 0
	s_add_u32 s41, s41, 0x100
	s_addc_u32 s43, s43, 0
	s_cmp_gt_u32 s73, 13
	s_cbranch_scc0 .LBB0_1367
	s_and_b64 vcc, exec, s[20:21]
	s_cbranch_vccz .LBB0_1370
	s_barrier

; #define PG8_STAGE(bufoff, gbase, voff) do { _Pragma("unroll") for (int _i = 0; _i < 2; ++_i) \
;         __builtin_amdgcn_global_load_lds((const unsigned*)((const char*)(gbase) + (voff)[_i]), (PG8_LAS unsigned*)(lds + (bufoff) + ldsw + _i * 8192), 16, 0, 0); } while (0)
; #define PG8_LDA(dst, b, h) do { _Pragma("unroll") for (int m = 0; m < 4; ++m) _Pragma("unroll") for (int k = 0; k < 2; ++k) dst[m][k] = *(const PG8_LAS bf16x8*)(lds + PG8_SA(b, h) + aoff + m * 2048 + k * 1024); } while (0)
; #define PG8_LDB(dst, b, h) do { _Pragma("unroll") for (int n = 0; n < 2; ++n) _Pragma("unroll") for (int k = 0; k < 2; ++k) dst[n][k] = *(const PG8_LAS bf16x8*)(lds + PG8_SB(b, h) + boff + n * 2048 + k * 1024); } while (0)
; #define PG8_MMA(ai, bj, At, Bt) do { __builtin_amdgcn_s_setprio(1); _Pragma("unroll") for (int m = 0; m < 4; ++m) _Pragma("unroll") for (int n = 0; n < 2; ++n) _Pragma("unroll") for (int k = 0; k < 2; ++k) \
;         acc[ai][bj][m][n] = __builtin_amdgcn_mfma_f32_16x16x32_bf16(Bt[n][k], At[m][k], acc[ai][bj][m][n], 0, 0, 0); __builtin_amdgcn_s_setprio(0); } while (0)
; #define PG8_WAIT_V(n) asm volatile("s_waitcnt vmcnt(" #n ")" ::: "memory")
; #define PG8_WAIT_L(n) asm volatile("s_waitcnt lgkmcnt(" #n ")" ::: "memory")
; #define PG8_BAR __builtin_amdgcn_s_barrier()
; template <class Epi, class Sched, bool ALIGN_EPI = false, bool SP2 = false>
; __device__ __forceinline__ void gemm_phase(PG8_LAS unsigned char* lds, const Gemm g, const Sched& S, const Epi& E) {
;     ...
;             const char* a1 = cA + (size_t)(t + 1) * kstep;
;             const char* a2 = last ? nA : cA + (size_t)(t + 2) * kstep; const char* b2 = last ? nB : cB + (size_t)(t + 2) * kstep;
;             const char* a3 = a2 + kstep; const char* b3 = b2 + kstep;
;             if (last && has_next) S.a_ready(nxt);
;             if constexpr (SP2) {
;             PG8_LDB(B0, 0, 0); PG8_LDB(B1, 0, 1); PG8_SCHED; PG8_LDA(At, 0, 0); PG8_STAGE(PG8_SA(1, 1), a1 + hstepA, voffA);
;             PG8_WAIT_V(8); PG8_WAIT_L(0); PG8_BAR; PG8_MMA(0, 0, At, B0); PG8_MMA(0, 1, At, B1); PG8_BAR; PG8_SCHED;
;             PG8_LDA(At, 0, 1); PG8_STAGE(PG8_SB(0, 0), b2, voffB); PG8_STAGE(PG8_SB(0, 1), b2 + hstepB, voffB); PG8_STAGE(PG8_SA(0, 0), a2, voffA);
;             PG8_WAIT_V(8); PG8_WAIT_L(0); PG8_BAR; PG8_MMA(1, 0, At, B0); PG8_MMA(1, 1, At, B1); PG8_BAR; PG8_SCHED;
.LBB0_1446:
	s_add_u32 s22, s20, 0xffe00080
	s_addc_u32 s23, s21, -1
	s_add_i32 s74, 0, 0x10000
	s_cmpk_eq_i32 s73, 0x7c
	s_cselect_b32 s57, s43, s23
	s_cselect_b32 s56, s47, s22
	v_add_u32_e32 v144, s74, v148
	s_cselect_b32 s23, s49, s69
	s_cselect_b32 s22, s63, s68
	s_add_i32 s76, 0, 0x14000
	ds_read_b128 v[140:143], v144
	ds_read_b128 v[150:153], v144 offset:1024
	ds_read_b128 v[154:157], v144 offset:2048
	ds_read_b128 v[158:161], v144 offset:3072
	v_add_u32_e32 v144, s76, v148
	ds_read_b128 v[162:165], v144
	ds_read_b128 v[166:169], v144 offset:1024
	ds_read_b128 v[170:173], v144 offset:2048
	ds_read_b128 v[174:177], v144 offset:3072
	v_lshl_add_u64 v[144:145], s[20:21], 0, v[136:137]
	s_add_i32 m0, s91, 0xc000
	ds_read_b128 v[182:185], v149
	ds_read_b128 v[188:191], v149 offset:1024
	ds_read_b128 v[216:219], v149 offset:2048
	ds_read_b128 v[220:223], v149 offset:3072
	ds_read_b128 v[224:227], v149 offset:4096
	ds_read_b128 v[228:231], v149 offset:5120
	ds_read_b128 v[232:235], v149 offset:6144
	ds_read_b128 v[236:239], v149 offset:7168
	global_load_lds_dwordx4 v[144:145], off
	v_lshl_add_u64 v[144:145], s[20:21], 0, v[138:139]
	s_add_i32 m0, s91, 0xe000
	s_nop 0
	global_load_lds_dwordx4 v[144:145], off
	s_waitcnt vmcnt(8)
	s_waitcnt lgkmcnt(0)
	s_barrier
	s_setprio 1
	s_waitcnt lgkmcnt(0)
	v_mfma_f32_16x16x32_bf16 v[126:129], v[140:143], v[182:185], v[126:129]
	v_mfma_f32_16x16x32_bf16 v[126:129], v[150:153], v[188:191], v[126:129]
	v_mfma_f32_16x16x32_bf16 v[122:125], v[158:161], v[188:191], v[122:125]
	v_mfma_f32_16x16x32_bf16 v[122:125], v[154:157], v[182:185], v[122:125]
	v_mfma_f32_16x16x32_bf16 v[106:109], v[154:157], v[216:219], v[106:109]
	v_mfma_f32_16x16x32_bf16 v[106:109], v[158:161], v[220:223], v[106:109]
	v_mfma_f32_16x16x32_bf16 v[110:113], v[150:153], v[220:223], v[110:113]
	v_mfma_f32_16x16x32_bf16 v[110:113], v[140:143], v[216:219], v[110:113]
	v_mfma_f32_16x16x32_bf16 v[94:97], v[140:143], v[224:227], v[94:97]
	v_mfma_f32_16x16x32_bf16 v[94:97], v[150:153], v[228:231], v[94:97]
	v_mfma_f32_16x16x32_bf16 v[90:93], v[158:161], v[228:231], v[90:93]
	v_mfma_f32_16x16x32_bf16 v[90:93], v[154:157], v[224:227], v[90:93]
	s_setprio 0
	s_setprio 1
	v_mfma_f32_16x16x32_bf16 v[72:75], v[154:157], v[232:235], v[72:75]
	v_mfma_f32_16x16x32_bf16 v[72:75], v[158:161], v[236:239], v[72:75]
	v_mfma_f32_16x16x32_bf16 v[76:79], v[150:153], v[236:239], v[76:79]
	v_mfma_f32_16x16x32_bf16 v[76:79], v[140:143], v[232:235], v[76:79]
	v_mfma_f32_16x16x32_bf16 v[118:121], v[162:165], v[182:185], v[118:121]
	v_mfma_f32_16x16x32_bf16 v[118:121], v[166:169], v[188:191], v[118:121]
	v_mfma_f32_16x16x32_bf16 v[114:117], v[174:177], v[188:191], v[114:117]
	v_mfma_f32_16x16x32_bf16 v[114:117], v[170:173], v[182:185], v[114:117]
	v_mfma_f32_16x16x32_bf16 v[98:101], v[170:173], v[216:219], v[98:101]
	v_mfma_f32_16x16x32_bf16 v[98:101], v[174:177], v[220:223], v[98:101]
	v_mfma_f32_16x16x32_bf16 v[102:105], v[166:169], v[220:223], v[102:105]
	v_mfma_f32_16x16x32_bf16 v[102:105], v[162:165], v[216:219], v[102:105]
	v_mfma_f32_16x16x32_bf16 v[86:89], v[162:165], v[224:227], v[86:89]
	v_mfma_f32_16x16x32_bf16 v[86:89], v[166:169], v[228:231], v[86:89]
	v_mfma_f32_16x16x32_bf16 v[82:85], v[174:177], v[228:231], v[82:85]
	v_mfma_f32_16x16x32_bf16 v[82:85], v[170:173], v[224:227], v[82:85]
	v_mfma_f32_16x16x32_bf16 v[64:67], v[170:173], v[232:235], v[64:67]
	v_mfma_f32_16x16x32_bf16 v[64:67], v[174:177], v[236:239], v[64:67]
	v_mfma_f32_16x16x32_bf16 v[68:71], v[166:169], v[236:239], v[68:71]
	v_mfma_f32_16x16x32_bf16 v[68:71], v[162:165], v[232:235], v[68:71]
	s_setprio 0
	s_barrier
	s_add_i32 s74, s74, s71
	v_lshl_add_u64 v[144:145], s[22:23], 0, v[80:81]
	s_mov_b32 m0, s74
	ds_read_b128 v[182:185], v149 offset:16384
	ds_read_b128 v[188:191], v149 offset:17408
	ds_read_b128 v[216:219], v149 offset:18432
	ds_read_b128 v[220:223], v149 offset:19456
	ds_read_b128 v[224:227], v149 offset:20480
	ds_read_b128 v[228:231], v149 offset:21504
	ds_read_b128 v[232:235], v149 offset:22528
	ds_read_b128 v[236:239], v149 offset:23552
	global_load_lds_dwordx4 v[144:145], off
	s_add_i32 m0, s74, 0x2000
	s_add_u32 s74, s22, 0x200000
	v_lshl_add_u64 v[192:193], s[22:23], 0, v[134:135]
	s_addc_u32 s75, s23, 0
	s_add_i32 s76, s76, s71
	global_load_lds_dwordx4 v[192:193], off
	v_lshl_add_u64 v[202:203], s[74:75], 0, v[80:81]
	s_mov_b32 m0, s76
	v_lshl_add_u64 v[204:205], s[56:57], 0, v[132:133]
	global_load_lds_dwordx4 v[202:203], off
	v_lshl_add_u64 v[202:203], s[74:75], 0, v[134:135]
	s_add_i32 m0, s76, 0x2000
	s_nop 0
	global_load_lds_dwordx4 v[202:203], off
	v_lshl_add_u64 v[202:203], s[56:57], 0, v[130:131]
	s_mov_b32 m0, s91
	s_nop 0
	global_load_lds_dwordx4 v[202:203], off
	s_mov_b32 m0, s36
	s_nop 0
	global_load_lds_dwordx4 v[204:205], off
	s_waitcnt vmcnt(8)
	s_waitcnt lgkmcnt(0)
	s_barrier
; #define PG8_STAGE(bufoff, gbase, voff) do { _Pragma("unroll") for (int _i = 0; _i < 2; ++_i) \
;         __builtin_amdgcn_global_load_lds((const unsigned*)((const char*)(gbase) + (voff)[_i]), (PG8_LAS unsigned*)(lds + (bufoff) + ldsw + _i * 8192), 16, 0, 0); } while (0)
; #define PG8_LDA(dst, b, h) do { _Pragma("unroll") for (int m = 0; m < 4; ++m) _Pragma("unroll") for (int k = 0; k < 2; ++k) dst[m][k] = *(const PG8_LAS bf16x8*)(lds + PG8_SA(b, h) + aoff + m * 2048 + k * 1024); } while (0)
; #define PG8_LDB(dst, b, h) do { _Pragma("unroll") for (int n = 0; n < 2; ++n) _Pragma("unroll") for (int k = 0; k < 2; ++k) dst[n][k] = *(const PG8_LAS bf16x8*)(lds + PG8_SB(b, h) + boff + n * 2048 + k * 1024); } while (0)
; #define PG8_MMA(ai, bj, At, Bt) do { __builtin_amdgcn_s_setprio(1); _Pragma("unroll") for (int m = 0; m < 4; ++m) _Pragma("unroll") for (int n = 0; n < 2; ++n) _Pragma("unroll") for (int k = 0; k < 2; ++k) \
;         acc[ai][bj][m][n] = __builtin_amdgcn_mfma_f32_16x16x32_bf16(Bt[n][k], At[m][k], acc[ai][bj][m][n], 0, 0, 0); __builtin_amdgcn_s_setprio(0); } while (0)
; #define PG8_WAIT_V(n) asm volatile("s_waitcnt vmcnt(" #n ")" ::: "memory")
; #define PG8_WAIT_L(n) asm volatile("s_waitcnt lgkmcnt(" #n ")" ::: "memory")
; #define PG8_BAR __builtin_amdgcn_s_barrier()
; #define PG8_SCHED __builtin_amdgcn_sched_barrier(0)
; template <class Epi, class Sched, bool ALIGN_EPI = false, bool SP2 = false>
; __device__ __forceinline__ void gemm_phase(PG8_LAS unsigned char* lds, const Gemm g, const Sched& S, const Epi& E) {
;     ...
;             PG8_WAIT_V(8); PG8_WAIT_L(0); PG8_BAR; PG8_MMA(1, 0, At, B0); PG8_MMA(1, 1, At, B1); PG8_BAR; PG8_SCHED;
;             PG8_LDB(B0, 1, 0); PG8_LDB(B1, 1, 1); PG8_SCHED; PG8_LDA(At, 1, 0); PG8_STAGE(PG8_SA(0, 1), a2 + hstepA, voffA);
;             PG8_WAIT_V(8); PG8_WAIT_L(0); PG8_BAR; PG8_MMA(0, 0, At, B0); PG8_MMA(0, 1, At, B1); PG8_BAR; PG8_SCHED;
	s_setprio 1
	s_waitcnt lgkmcnt(0)
	v_mfma_f32_16x16x32_bf16 v[60:63], v[140:143], v[182:185], v[60:63]
	v_mfma_f32_16x16x32_bf16 v[60:63], v[150:153], v[188:191], v[60:63]
	v_mfma_f32_16x16x32_bf16 v[56:59], v[158:161], v[188:191], v[56:59]
	v_mfma_f32_16x16x32_bf16 v[56:59], v[154:157], v[182:185], v[56:59]
	v_mfma_f32_16x16x32_bf16 v[40:43], v[154:157], v[216:219], v[40:43]
	v_mfma_f32_16x16x32_bf16 v[40:43], v[158:161], v[220:223], v[40:43]
	v_mfma_f32_16x16x32_bf16 v[44:47], v[150:153], v[220:223], v[44:47]
	v_mfma_f32_16x16x32_bf16 v[44:47], v[140:143], v[216:219], v[44:47]
	v_mfma_f32_16x16x32_bf16 v[28:31], v[140:143], v[224:227], v[28:31]
	v_mfma_f32_16x16x32_bf16 v[28:31], v[150:153], v[228:231], v[28:31]
	v_mfma_f32_16x16x32_bf16 v[24:27], v[158:161], v[228:231], v[24:27]
	v_mfma_f32_16x16x32_bf16 v[24:27], v[154:157], v[224:227], v[24:27]
	s_setprio 0
	s_setprio 1
	v_mfma_f32_16x16x32_bf16 v[8:11], v[154:157], v[232:235], v[8:11]
	v_mfma_f32_16x16x32_bf16 v[8:11], v[158:161], v[236:239], v[8:11]
	v_mfma_f32_16x16x32_bf16 v[12:15], v[150:153], v[236:239], v[12:15]
	v_mfma_f32_16x16x32_bf16 v[12:15], v[140:143], v[232:235], v[12:15]
	v_mfma_f32_16x16x32_bf16 v[52:55], v[162:165], v[182:185], v[52:55]
	v_mfma_f32_16x16x32_bf16 v[52:55], v[166:169], v[188:191], v[52:55]
	v_mfma_f32_16x16x32_bf16 v[48:51], v[174:177], v[188:191], v[48:51]
	v_mfma_f32_16x16x32_bf16 v[48:51], v[170:173], v[182:185], v[48:51]
	v_mfma_f32_16x16x32_bf16 v[32:35], v[170:173], v[216:219], v[32:35]
	v_mfma_f32_16x16x32_bf16 v[32:35], v[174:177], v[220:223], v[32:35]
	v_mfma_f32_16x16x32_bf16 v[36:39], v[166:169], v[220:223], v[36:39]
	v_mfma_f32_16x16x32_bf16 v[36:39], v[162:165], v[216:219], v[36:39]
	v_mfma_f32_16x16x32_bf16 v[20:23], v[162:165], v[224:227], v[20:23]
	v_mfma_f32_16x16x32_bf16 v[20:23], v[166:169], v[228:231], v[20:23]
	v_mfma_f32_16x16x32_bf16 v[16:19], v[174:177], v[228:231], v[16:19]
	v_mfma_f32_16x16x32_bf16 v[16:19], v[170:173], v[224:227], v[16:19]
	v_mfma_f32_16x16x32_bf16 v[0:3], v[170:173], v[232:235], v[0:3]
	v_mfma_f32_16x16x32_bf16 v[0:3], v[174:177], v[236:239], v[0:3]
	v_mfma_f32_16x16x32_bf16 v[4:7], v[166:169], v[236:239], v[4:7]
	v_mfma_f32_16x16x32_bf16 v[4:7], v[162:165], v[232:235], v[4:7]
	s_setprio 0
	s_barrier
	s_add_i32 s74, 0, 0x18000
	s_add_i32 s75, 0, 0x1c000
	v_add_u32_e32 v158, s74, v148
	v_add_u32_e32 v174, s75, v148
	ds_read_b128 v[140:143], v158
	ds_read_b128 v[150:153], v158 offset:1024
	ds_read_b128 v[154:157], v158 offset:2048
	ds_read_b128 v[158:161], v158 offset:3072
	ds_read_b128 v[162:165], v174
	ds_read_b128 v[166:169], v174 offset:1024
	ds_read_b128 v[170:173], v174 offset:2048
	ds_read_b128 v[174:177], v174 offset:3072
	s_add_u32 s56, s56, 0x200000
	s_addc_u32 s57, s57, 0
	s_mov_b32 m0, s44
	v_lshl_add_u64 v[206:207], s[56:57], 0, v[130:131]
	ds_read_b128 v[182:185], v149 offset:32768
	ds_read_b128 v[188:191], v149 offset:33792
	ds_read_b128 v[216:219], v149 offset:34816
	ds_read_b128 v[220:223], v149 offset:35840
	ds_read_b128 v[224:227], v149 offset:36864
	ds_read_b128 v[228:231], v149 offset:37888
	ds_read_b128 v[232:235], v149 offset:38912
	ds_read_b128 v[236:239], v149 offset:39936
	global_load_lds_dwordx4 v[206:207], off
	v_lshl_add_u64 v[206:207], s[56:57], 0, v[132:133]
	s_mov_b32 m0, s45
	s_nop 0
	global_load_lds_dwordx4 v[206:207], off
	s_waitcnt vmcnt(8)
	s_waitcnt lgkmcnt(0)
	s_barrier
	s_setprio 1
	s_waitcnt lgkmcnt(0)
	v_mfma_f32_16x16x32_bf16 v[126:129], v[140:143], v[182:185], v[126:129]
	v_mfma_f32_16x16x32_bf16 v[126:129], v[150:153], v[188:191], v[126:129]
	v_mfma_f32_16x16x32_bf16 v[122:125], v[158:161], v[188:191], v[122:125]
	v_mfma_f32_16x16x32_bf16 v[122:125], v[154:157], v[182:185], v[122:125]
	v_mfma_f32_16x16x32_bf16 v[106:109], v[154:157], v[216:219], v[106:109]
	v_mfma_f32_16x16x32_bf16 v[106:109], v[158:161], v[220:223], v[106:109]
	v_mfma_f32_16x16x32_bf16 v[110:113], v[150:153], v[220:223], v[110:113]
	v_mfma_f32_16x16x32_bf16 v[110:113], v[140:143], v[216:219], v[110:113]
	v_mfma_f32_16x16x32_bf16 v[94:97], v[140:143], v[224:227], v[94:97]
	v_mfma_f32_16x16x32_bf16 v[94:97], v[150:153], v[228:231], v[94:97]
	v_mfma_f32_16x16x32_bf16 v[90:93], v[158:161], v[228:231], v[90:93]
	v_mfma_f32_16x16x32_bf16 v[90:93], v[154:157], v[224:227], v[90:93]
	s_setprio 0
	s_setprio 1
	v_mfma_f32_16x16x32_bf16 v[72:75], v[154:157], v[232:235], v[72:75]
	v_mfma_f32_16x16x32_bf16 v[72:75], v[158:161], v[236:239], v[72:75]
	v_mfma_f32_16x16x32_bf16 v[76:79], v[150:153], v[236:239], v[76:79]
	v_mfma_f32_16x16x32_bf16 v[76:79], v[140:143], v[232:235], v[76:79]
	v_mfma_f32_16x16x32_bf16 v[118:121], v[162:165], v[182:185], v[118:121]
	v_mfma_f32_16x16x32_bf16 v[118:121], v[166:169], v[188:191], v[118:121]
	v_mfma_f32_16x16x32_bf16 v[114:117], v[174:177], v[188:191], v[114:117]
	v_mfma_f32_16x16x32_bf16 v[114:117], v[170:173], v[182:185], v[114:117]
	v_mfma_f32_16x16x32_bf16 v[98:101], v[170:173], v[216:219], v[98:101]
	v_mfma_f32_16x16x32_bf16 v[98:101], v[174:177], v[220:223], v[98:101]
	v_mfma_f32_16x16x32_bf16 v[102:105], v[166:169], v[220:223], v[102:105]
	v_mfma_f32_16x16x32_bf16 v[102:105], v[162:165], v[216:219], v[102:105]
	v_mfma_f32_16x16x32_bf16 v[86:89], v[162:165], v[224:227], v[86:89]
	v_mfma_f32_16x16x32_bf16 v[86:89], v[166:169], v[228:231], v[86:89]
	v_mfma_f32_16x16x32_bf16 v[82:85], v[174:177], v[228:231], v[82:85]
	v_mfma_f32_16x16x32_bf16 v[82:85], v[170:173], v[224:227], v[82:85]
	v_mfma_f32_16x16x32_bf16 v[64:67], v[170:173], v[232:235], v[64:67]
	v_mfma_f32_16x16x32_bf16 v[64:67], v[174:177], v[236:239], v[64:67]
	v_mfma_f32_16x16x32_bf16 v[68:71], v[166:169], v[236:239], v[68:71]
	v_mfma_f32_16x16x32_bf16 v[68:71], v[162:165], v[232:235], v[68:71]
	s_setprio 0
	s_barrier
; #define PG8_STAGE(bufoff, gbase, voff) do { _Pragma("unroll") for (int _i = 0; _i < 2; ++_i) \
;         __builtin_amdgcn_global_load_lds((const unsigned*)((const char*)(gbase) + (voff)[_i]), (PG8_LAS unsigned*)(lds + (bufoff) + ldsw + _i * 8192), 16, 0, 0); } while (0)
; #define PG8_LDA(dst, b, h) do { _Pragma("unroll") for (int m = 0; m < 4; ++m) _Pragma("unroll") for (int k = 0; k < 2; ++k) dst[m][k] = *(const PG8_LAS bf16x8*)(lds + PG8_SA(b, h) + aoff + m * 2048 + k * 1024); } while (0)
; #define PG8_MMA(ai, bj, At, Bt) do { __builtin_amdgcn_s_setprio(1); _Pragma("unroll") for (int m = 0; m < 4; ++m) _Pragma("unroll") for (int n = 0; n < 2; ++n) _Pragma("unroll") for (int k = 0; k < 2; ++k) \
;         acc[ai][bj][m][n] = __builtin_amdgcn_mfma_f32_16x16x32_bf16(Bt[n][k], At[m][k], acc[ai][bj][m][n], 0, 0, 0); __builtin_amdgcn_s_setprio(0); } while (0)
; #define PG8_WAIT_V(n) asm volatile("s_waitcnt vmcnt(" #n ")" ::: "memory")
; #define PG8_WAIT_L(n) asm volatile("s_waitcnt lgkmcnt(" #n ")" ::: "memory")
; #define PG8_BAR __builtin_amdgcn_s_barrier()
; #define PG8_SCHED __builtin_amdgcn_sched_barrier(0)
; template <class Epi, class Sched, bool ALIGN_EPI = false, bool SP2 = false>
; __device__ __forceinline__ void gemm_phase(PG8_LAS unsigned char* lds, const Gemm g, const Sched& S, const Epi& E) {
;     ...
;             PG8_LDA(At, 1, 1); PG8_STAGE(PG8_SB(1, 0), b3, voffB); PG8_STAGE(PG8_SB(1, 1), b3 + hstepB, voffB); PG8_STAGE(PG8_SA(1, 0), a3, voffA);
;             PG8_WAIT_V(8); PG8_WAIT_L(0); PG8_BAR; PG8_MMA(1, 0, At, B0); PG8_MMA(1, 1, At, B1); PG8_BAR; PG8_SCHED;
	s_add_i32 s56, s74, s71
	v_lshl_add_u64 v[144:145], v[144:145], 0, s[60:61]
	s_mov_b32 m0, s56
	ds_read_b128 v[182:185], v149 offset:49152
	ds_read_b128 v[188:191], v149 offset:50176
	ds_read_b128 v[216:219], v149 offset:51200
	ds_read_b128 v[220:223], v149 offset:52224
	ds_read_b128 v[224:227], v149 offset:53248
	ds_read_b128 v[228:231], v149 offset:54272
	ds_read_b128 v[232:235], v149 offset:55296
	ds_read_b128 v[236:239], v149 offset:56320
	global_load_lds_dwordx4 v[144:145], off
	s_add_i32 m0, s56, 0x2000
	s_add_u32 s22, s22, 0x200080
	v_lshl_add_u64 v[144:145], v[192:193], 0, s[60:61]
	s_addc_u32 s23, s23, 0
	s_add_i32 s56, s75, s71
	global_load_lds_dwordx4 v[144:145], off
	v_lshl_add_u64 v[144:145], s[22:23], 0, v[80:81]
	s_mov_b32 m0, s56
	s_nop 0
	global_load_lds_dwordx4 v[144:145], off
	v_lshl_add_u64 v[144:145], s[22:23], 0, v[134:135]
	s_add_i32 m0, s56, 0x2000
	s_nop 0
	global_load_lds_dwordx4 v[144:145], off
	v_lshl_add_u64 v[144:145], v[202:203], 0, s[60:61]
	s_mov_b32 m0, s92
	s_nop 0
	global_load_lds_dwordx4 v[144:145], off
	v_lshl_add_u64 v[144:145], v[204:205], 0, s[60:61]
	s_mov_b32 m0, s37
	s_nop 0
	global_load_lds_dwordx4 v[144:145], off
	s_waitcnt vmcnt(8)
	s_waitcnt lgkmcnt(0)
	s_barrier
	s_setprio 1
	s_waitcnt lgkmcnt(0)
	v_mfma_f32_16x16x32_bf16 v[60:63], v[140:143], v[182:185], v[60:63]
	v_mfma_f32_16x16x32_bf16 v[60:63], v[150:153], v[188:191], v[60:63]
	v_mfma_f32_16x16x32_bf16 v[56:59], v[158:161], v[188:191], v[56:59]
	v_mfma_f32_16x16x32_bf16 v[56:59], v[154:157], v[182:185], v[56:59]
	v_mfma_f32_16x16x32_bf16 v[40:43], v[154:157], v[216:219], v[40:43]
	v_mfma_f32_16x16x32_bf16 v[40:43], v[158:161], v[220:223], v[40:43]
	v_mfma_f32_16x16x32_bf16 v[44:47], v[150:153], v[220:223], v[44:47]
	v_mfma_f32_16x16x32_bf16 v[44:47], v[140:143], v[216:219], v[44:47]
	v_mfma_f32_16x16x32_bf16 v[28:31], v[140:143], v[224:227], v[28:31]
	v_mfma_f32_16x16x32_bf16 v[28:31], v[150:153], v[228:231], v[28:31]
	v_mfma_f32_16x16x32_bf16 v[24:27], v[158:161], v[228:231], v[24:27]
	v_mfma_f32_16x16x32_bf16 v[24:27], v[154:157], v[224:227], v[24:27]
	s_setprio 0
	s_setprio 1
	v_mfma_f32_16x16x32_bf16 v[8:11], v[154:157], v[232:235], v[8:11]
	v_mfma_f32_16x16x32_bf16 v[8:11], v[158:161], v[236:239], v[8:11]
	v_mfma_f32_16x16x32_bf16 v[12:15], v[150:153], v[236:239], v[12:15]
	v_mfma_f32_16x16x32_bf16 v[12:15], v[140:143], v[232:235], v[12:15]
	v_mfma_f32_16x16x32_bf16 v[52:55], v[162:165], v[182:185], v[52:55]
	v_mfma_f32_16x16x32_bf16 v[52:55], v[166:169], v[188:191], v[52:55]
	v_mfma_f32_16x16x32_bf16 v[48:51], v[174:177], v[188:191], v[48:51]
	v_mfma_f32_16x16x32_bf16 v[48:51], v[170:173], v[182:185], v[48:51]
	v_mfma_f32_16x16x32_bf16 v[32:35], v[170:173], v[216:219], v[32:35]
	v_mfma_f32_16x16x32_bf16 v[32:35], v[174:177], v[220:223], v[32:35]
	v_mfma_f32_16x16x32_bf16 v[36:39], v[166:169], v[220:223], v[36:39]
	v_mfma_f32_16x16x32_bf16 v[36:39], v[162:165], v[216:219], v[36:39]
	v_mfma_f32_16x16x32_bf16 v[20:23], v[162:165], v[224:227], v[20:23]
	v_mfma_f32_16x16x32_bf16 v[20:23], v[166:169], v[228:231], v[20:23]
	v_mfma_f32_16x16x32_bf16 v[16:19], v[174:177], v[228:231], v[16:19]
	v_mfma_f32_16x16x32_bf16 v[16:19], v[170:173], v[224:227], v[16:19]
	v_mfma_f32_16x16x32_bf16 v[0:3], v[170:173], v[232:235], v[0:3]
	v_mfma_f32_16x16x32_bf16 v[0:3], v[174:177], v[236:239], v[0:3]
	v_mfma_f32_16x16x32_bf16 v[4:7], v[166:169], v[236:239], v[4:7]
	v_mfma_f32_16x16x32_bf16 v[4:7], v[162:165], v[232:235], v[4:7]
	s_setprio 0
	s_barrier
	s_add_i32 s73, s73, 2
	s_add_u32 s20, s20, 0x100
	s_addc_u32 s21, s21, 0
	s_add_u32 s68, s68, 0x100
	s_addc_u32 s69, s69, 0
	s_cmpk_gt_u32 s73, 0x7d
	s_cbranch_scc0 .LBB0_1446
	s_and_b64 vcc, exec, s[52:53]
	s_cbranch_vccz .LBB0_1449
	s_barrier
